# MFMA issue order in the 4 GEMM K-loops: the two K-halves of each accumulator issued back to back (accumulate chain, SrcC forwarding) instead of 8 apart; bit-identical math; rest as v69
# speedup vs baseline: 1.0105x; 1.0105x over previous
; #define PG8_STAGE(bufoff, gbase, voff) do { _Pragma("unroll") for (int _i = 0; _i < 2; ++_i) \
;         __builtin_amdgcn_global_load_lds((const unsigned*)((const char*)(gbase) + (voff)[_i]), (LAS unsigned*)(lds + (bufoff) + ldsw + _i * 8192), 16, 0, 0); } while (0)
; #define PG8_LDA(dst, b, h) do { _Pragma("unroll") for (int m = 0; m < 4; ++m) _Pragma("unroll") for (int k = 0; k < 2; ++k) dst[m][k] = *(const LAS bf16x8*)(lds + PG8_SA(b, h) + aoff + m * 2048 + k * 1024); } while (0)
; #define PG8_LDB(dst, b, h) do { _Pragma("unroll") for (int n = 0; n < 2; ++n) _Pragma("unroll") for (int k = 0; k < 2; ++k) dst[n][k] = *(const LAS bf16x8*)(lds + PG8_SB(b, h) + boff + n * 2048 + k * 1024); } while (0)
; #define PG8_SCHED __builtin_amdgcn_sched_barrier(0)
; template <class Epi, bool ALIGN_EPI>
; __device__ __forceinline__ void gemm_phase(LAS unsigned char* lds, const Gemm g, const StaticOrder& S, const Epi& E, const int tid) {
;     ...
;             const bool last = (t == nt - 2);
;             const char* a1 = cA + (size_t)(t + 1) * kstepA;
;             const char* a2 = last ? nA : cA + (size_t)(t + 2) * kstepA; const char* b2 = last ? nB : cB + (size_t)(t + 2) * kstepB;
;             const char* a3 = a2 + kstepA; const char* b3 = b2 + kstepB;
;             PG8_LDB(B0, 0, 0); PG8_LDB(B1, 0, 1); PG8_SCHED; PG8_LDA(At, 0, 0); PG8_STAGE(PG8_SA(1, 1), a1 + hstepA, voffA);
.LBB0_211:
	s_add_u32 s50, s48, 0x4000
	s_addc_u32 s51, s49, 0
	s_cmp_eq_u32 s89, 28
	s_cselect_b32 s54, s87, s50
	s_cselect_b32 s55, s43, s51
	s_cselect_b32 s52, vcc_lo, vcc_hi
	s_cselect_b32 s53, s35, s88
	s_add_u32 s50, s54, 0x8000
	s_addc_u32 s51, s55, 0
	s_add_i32 s90, 0, 0x10000
	v_add_u32_e32 v0, s90, v160
	s_add_i32 s92, 0, 0x14000
	ds_read_b128 v[132:135], v0
	ds_read_b128 v[136:139], v0 offset:1024
	ds_read_b128 v[152:155], v0 offset:2048
	ds_read_b128 v[156:159], v0 offset:3072
	v_add_u32_e32 v0, s92, v160
	ds_read_b128 v[162:165], v0
	ds_read_b128 v[166:169], v0 offset:1024
	ds_read_b128 v[170:173], v0 offset:2048
	ds_read_b128 v[174:177], v0 offset:3072
	s_add_i32 m0, s72, 0xc000
	ds_read_b128 v[178:181], v161
	ds_read_b128 v[182:185], v161 offset:1024
	ds_read_b128 v[186:189], v161 offset:2048
	ds_read_b128 v[190:193], v161 offset:3072
	ds_read_b128 v[194:197], v161 offset:4096
	ds_read_b128 v[198:201], v161 offset:5120
	ds_read_b128 v[214:217], v161 offset:6144

; #define PG8_STAGE(bufoff, gbase, voff) do { _Pragma("unroll") for (int _i = 0; _i < 2; ++_i) \
;         __builtin_amdgcn_global_load_lds((const unsigned*)((const char*)(gbase) + (voff)[_i]), (LAS unsigned*)(lds + (bufoff) + ldsw + _i * 8192), 16, 0, 0); } while (0)
; #define PG8_LDA(dst, b, h) do { _Pragma("unroll") for (int m = 0; m < 4; ++m) _Pragma("unroll") for (int k = 0; k < 2; ++k) dst[m][k] = *(const LAS bf16x8*)(lds + PG8_SA(b, h) + aoff + m * 2048 + k * 1024); } while (0)
; #define PG8_LDB(dst, b, h) do { _Pragma("unroll") for (int n = 0; n < 2; ++n) _Pragma("unroll") for (int k = 0; k < 2; ++k) dst[n][k] = *(const LAS bf16x8*)(lds + PG8_SB(b, h) + boff + n * 2048 + k * 1024); } while (0)
; #define PG8_MMA(ai, bj, At, Bt) do { __builtin_amdgcn_s_setprio(1); _Pragma("unroll") for (int m = 0; m < 4; ++m) _Pragma("unroll") for (int n = 0; n < 2; ++n) _Pragma("unroll") for (int k = 0; k < 2; ++k) \
;         acc[ai][bj][m][n] = __builtin_amdgcn_mfma_f32_16x16x32_bf16(Bt[n][k], At[m][k], acc[ai][bj][m][n], 0, 0, 0); __builtin_amdgcn_s_setprio(0); } while (0)
; #define PG8_WAIT_V(n) asm volatile("s_waitcnt vmcnt(" #n ")" ::: "memory")
; #define PG8_WAIT_L(n) asm volatile("s_waitcnt lgkmcnt(" #n ")" ::: "memory")
; #define PG8_BAR __builtin_amdgcn_s_barrier()
; #define PG8_SCHED __builtin_amdgcn_sched_barrier(0)
; template <class Epi, bool ALIGN_EPI>
; __device__ __forceinline__ void gemm_phase(LAS unsigned char* lds, const Gemm g, const StaticOrder& S, const Epi& E, const int tid) {
;     ...
;             PG8_LDB(B0, 0, 0); PG8_LDB(B1, 0, 1); PG8_SCHED; PG8_LDA(At, 0, 0); PG8_STAGE(PG8_SA(1, 1), a1 + hstepA, voffA);
;             PG8_WAIT_V(8); PG8_WAIT_L(0); PG8_BAR; PG8_MMA(0, 0, At, B0); PG8_MMA(0, 1, At, B1); PG8_BAR; PG8_SCHED;
	global_load_lds_dwordx4 v148, s[48:49]
	s_add_i32 m0, s72, 0xe000
	ds_read_b128 v[218:221], v161 offset:7168
	global_load_lds_dwordx4 v150, s[48:49]
	s_waitcnt vmcnt(8)
	s_waitcnt lgkmcnt(0)
	s_barrier


; #define PG8_MMA(ai, bj, At, Bt) do { __builtin_amdgcn_s_setprio(1); _Pragma("unroll") for (int m = 0; m < 4; ++m) _Pragma("unroll") for (int n = 0; n < 2; ++n) _Pragma("unroll") for (int k = 0; k < 2; ++k) \
;         acc[ai][bj][m][n] = __builtin_amdgcn_mfma_f32_16x16x32_bf16(Bt[n][k], At[m][k], acc[ai][bj][m][n], 0, 0, 0); __builtin_amdgcn_s_setprio(0); } while (0)
; #define PG8_WAIT_V(n) asm volatile("s_waitcnt vmcnt(" #n ")" ::: "memory")
; #define PG8_WAIT_L(n) asm volatile("s_waitcnt lgkmcnt(" #n ")" ::: "memory")
; #define PG8_BAR __builtin_amdgcn_s_barrier()
; #define PG8_SCHED __builtin_amdgcn_sched_barrier(0)
; template <class Epi, bool ALIGN_EPI>
; __device__ __forceinline__ void gemm_phase(LAS unsigned char* lds, const Gemm g, const StaticOrder& S, const Epi& E, const int tid) {
;     ...
;             PG8_WAIT_V(8); PG8_WAIT_L(0); PG8_BAR; PG8_MMA(0, 0, At, B0); PG8_MMA(0, 1, At, B1); PG8_BAR; PG8_SCHED;
	v_mfma_f32_16x16x32_bf16 v[88:91], v[132:135], v[178:181], v[88:91]
	v_mfma_f32_16x16x32_bf16 v[88:91], v[136:139], v[182:185], v[88:91]
	v_mfma_f32_16x16x32_bf16 v[124:127], v[152:155], v[178:181], v[124:127]
	v_mfma_f32_16x16x32_bf16 v[124:127], v[156:159], v[182:185], v[124:127]
	v_mfma_f32_16x16x32_bf16 v[52:55], v[132:135], v[186:189], v[52:55]
	v_mfma_f32_16x16x32_bf16 v[52:55], v[136:139], v[190:193], v[52:55]
	v_mfma_f32_16x16x32_bf16 v[120:123], v[152:155], v[186:189], v[120:123]
	v_mfma_f32_16x16x32_bf16 v[120:123], v[156:159], v[190:193], v[120:123]
	v_mfma_f32_16x16x32_bf16 v[40:43], v[132:135], v[194:197], v[40:43]
	v_mfma_f32_16x16x32_bf16 v[40:43], v[136:139], v[198:201], v[40:43]
	v_mfma_f32_16x16x32_bf16 v[116:119], v[152:155], v[194:197], v[116:119]
	v_mfma_f32_16x16x32_bf16 v[116:119], v[156:159], v[198:201], v[116:119]
	v_mfma_f32_16x16x32_bf16 v[36:39], v[132:135], v[214:217], v[36:39]
	v_mfma_f32_16x16x32_bf16 v[36:39], v[136:139], v[218:221], v[36:39]
	v_mfma_f32_16x16x32_bf16 v[112:115], v[152:155], v[214:217], v[112:115]
	v_mfma_f32_16x16x32_bf16 v[112:115], v[156:159], v[218:221], v[112:115]


; #define PG8_MMA(ai, bj, At, Bt) do { __builtin_amdgcn_s_setprio(1); _Pragma("unroll") for (int m = 0; m < 4; ++m) _Pragma("unroll") for (int n = 0; n < 2; ++n) _Pragma("unroll") for (int k = 0; k < 2; ++k) \
;         acc[ai][bj][m][n] = __builtin_amdgcn_mfma_f32_16x16x32_bf16(Bt[n][k], At[m][k], acc[ai][bj][m][n], 0, 0, 0); __builtin_amdgcn_s_setprio(0); } while (0)
; #define PG8_WAIT_V(n) asm volatile("s_waitcnt vmcnt(" #n ")" ::: "memory")
; #define PG8_WAIT_L(n) asm volatile("s_waitcnt lgkmcnt(" #n ")" ::: "memory")
; #define PG8_BAR __builtin_amdgcn_s_barrier()
; #define PG8_SCHED __builtin_amdgcn_sched_barrier(0)
; template <class Epi, bool ALIGN_EPI>
; __device__ __forceinline__ void gemm_phase(LAS unsigned char* lds, const Gemm g, const StaticOrder& S, const Epi& E, const int tid) {
;     ...
;             PG8_WAIT_V(8); PG8_WAIT_L(0); PG8_BAR; PG8_MMA(0, 0, At, B0); PG8_MMA(0, 1, At, B1); PG8_BAR; PG8_SCHED;
	v_mfma_f32_16x16x32_bf16 v[80:83], v[162:165], v[178:181], v[80:83]
	v_mfma_f32_16x16x32_bf16 v[80:83], v[166:169], v[182:185], v[80:83]
	v_mfma_f32_16x16x32_bf16 v[128:131], v[170:173], v[178:181], v[128:131]
	v_mfma_f32_16x16x32_bf16 v[128:131], v[174:177], v[182:185], v[128:131]
	v_mfma_f32_16x16x32_bf16 v[68:71], v[162:165], v[186:189], v[68:71]
	v_mfma_f32_16x16x32_bf16 v[68:71], v[166:169], v[190:193], v[68:71]
	v_mfma_f32_16x16x32_bf16 v[108:111], v[170:173], v[186:189], v[108:111]
	v_mfma_f32_16x16x32_bf16 v[108:111], v[174:177], v[190:193], v[108:111]
	v_mfma_f32_16x16x32_bf16 v[60:63], v[162:165], v[194:197], v[60:63]
	v_mfma_f32_16x16x32_bf16 v[60:63], v[166:169], v[198:201], v[60:63]
	v_mfma_f32_16x16x32_bf16 v[104:107], v[170:173], v[194:197], v[104:107]
	v_mfma_f32_16x16x32_bf16 v[104:107], v[174:177], v[198:201], v[104:107]
	v_mfma_f32_16x16x32_bf16 v[48:51], v[162:165], v[214:217], v[48:51]
	v_mfma_f32_16x16x32_bf16 v[48:51], v[166:169], v[218:221], v[48:51]
	v_mfma_f32_16x16x32_bf16 v[100:103], v[170:173], v[214:217], v[100:103]
	v_mfma_f32_16x16x32_bf16 v[100:103], v[174:177], v[218:221], v[100:103]

; #define PG8_STAGE(bufoff, gbase, voff) do { _Pragma("unroll") for (int _i = 0; _i < 2; ++_i) \
;         __builtin_amdgcn_global_load_lds((const unsigned*)((const char*)(gbase) + (voff)[_i]), (LAS unsigned*)(lds + (bufoff) + ldsw + _i * 8192), 16, 0, 0); } while (0)
; #define PG8_LDA(dst, b, h) do { _Pragma("unroll") for (int m = 0; m < 4; ++m) _Pragma("unroll") for (int k = 0; k < 2; ++k) dst[m][k] = *(const LAS bf16x8*)(lds + PG8_SA(b, h) + aoff + m * 2048 + k * 1024); } while (0)
; #define PG8_MMA(ai, bj, At, Bt) do { __builtin_amdgcn_s_setprio(1); _Pragma("unroll") for (int m = 0; m < 4; ++m) _Pragma("unroll") for (int n = 0; n < 2; ++n) _Pragma("unroll") for (int k = 0; k < 2; ++k) \
;         acc[ai][bj][m][n] = __builtin_amdgcn_mfma_f32_16x16x32_bf16(Bt[n][k], At[m][k], acc[ai][bj][m][n], 0, 0, 0); __builtin_amdgcn_s_setprio(0); } while (0)
; #define PG8_WAIT_V(n) asm volatile("s_waitcnt vmcnt(" #n ")" ::: "memory")
; #define PG8_WAIT_L(n) asm volatile("s_waitcnt lgkmcnt(" #n ")" ::: "memory")
; #define PG8_BAR __builtin_amdgcn_s_barrier()
; #define PG8_SCHED __builtin_amdgcn_sched_barrier(0)
; template <class Epi, bool ALIGN_EPI>
; __device__ __forceinline__ void gemm_phase(LAS unsigned char* lds, const Gemm g, const StaticOrder& S, const Epi& E, const int tid) {
;     ...
;             PG8_WAIT_V(8); PG8_WAIT_L(0); PG8_BAR; PG8_MMA(0, 0, At, B0); PG8_MMA(0, 1, At, B1); PG8_BAR; PG8_SCHED;
;             PG8_LDA(At, 0, 1); PG8_STAGE(PG8_SB(0, 0), b2, voffB); PG8_STAGE(PG8_SB(0, 1), b2 + hstepB, voffB); PG8_STAGE(PG8_SA(0, 0), a2, voffA);
	s_barrier
	s_add_i32 s90, s90, s71
	s_mov_b32 m0, s90
	ds_read_b128 v[178:181], v161 offset:16384
	ds_read_b128 v[182:185], v161 offset:17408
	ds_read_b128 v[186:189], v161 offset:18432
	ds_read_b128 v[190:193], v161 offset:19456


; #define PG8_STAGE(bufoff, gbase, voff) do { _Pragma("unroll") for (int _i = 0; _i < 2; ++_i) \
;         __builtin_amdgcn_global_load_lds((const unsigned*)((const char*)(gbase) + (voff)[_i]), (LAS unsigned*)(lds + (bufoff) + ldsw + _i * 8192), 16, 0, 0); } while (0)
; #define PG8_LDA(dst, b, h) do { _Pragma("unroll") for (int m = 0; m < 4; ++m) _Pragma("unroll") for (int k = 0; k < 2; ++k) dst[m][k] = *(const LAS bf16x8*)(lds + PG8_SA(b, h) + aoff + m * 2048 + k * 1024); } while (0)
; #define PG8_MMA(ai, bj, At, Bt) do { __builtin_amdgcn_s_setprio(1); _Pragma("unroll") for (int m = 0; m < 4; ++m) _Pragma("unroll") for (int n = 0; n < 2; ++n) _Pragma("unroll") for (int k = 0; k < 2; ++k) \
;         acc[ai][bj][m][n] = __builtin_amdgcn_mfma_f32_16x16x32_bf16(Bt[n][k], At[m][k], acc[ai][bj][m][n], 0, 0, 0); __builtin_amdgcn_s_setprio(0); } while (0)
; #define PG8_WAIT_V(n) asm volatile("s_waitcnt vmcnt(" #n ")" ::: "memory")
; #define PG8_WAIT_L(n) asm volatile("s_waitcnt lgkmcnt(" #n ")" ::: "memory")
; #define PG8_BAR __builtin_amdgcn_s_barrier()
; #define PG8_SCHED __builtin_amdgcn_sched_barrier(0)
; template <class Epi, bool ALIGN_EPI>
; __device__ __forceinline__ void gemm_phase(LAS unsigned char* lds, const Gemm g, const StaticOrder& S, const Epi& E, const int tid) {
;     ...
;             PG8_LDA(At, 0, 1); PG8_STAGE(PG8_SB(0, 0), b2, voffB); PG8_STAGE(PG8_SB(0, 1), b2 + hstepB, voffB); PG8_STAGE(PG8_SA(0, 0), a2, voffA);
;             PG8_WAIT_V(8); PG8_WAIT_L(0); PG8_BAR; PG8_MMA(1, 0, At, B0); PG8_MMA(1, 1, At, B1); PG8_BAR; PG8_SCHED;
	global_load_lds_dwordx4 v144, s[52:53]
	s_add_i32 m0, s90, 0x2000
	s_add_u32 s90, s52, 0x4000
	s_addc_u32 s91, s53, 0
	s_add_i32 s92, s92, s71
	global_load_lds_dwordx4 v140, s[52:53]
	s_mov_b32 m0, s92
	ds_read_b128 v[218:221], v161 offset:23552
	global_load_lds_dwordx4 v144, s[90:91]
	s_add_i32 m0, s92, 0x2000
	ds_read_b128 v[214:217], v161 offset:22528
	global_load_lds_dwordx4 v140, s[90:91]
	s_mov_b32 m0, s72
	ds_read_b128 v[198:201], v161 offset:21504
	global_load_lds_dwordx4 v146, s[54:55]
	s_mov_b32 m0, s73
	ds_read_b128 v[194:197], v161 offset:20480
	global_load_lds_dwordx4 v142, s[54:55]
	s_waitcnt vmcnt(8)
	s_waitcnt lgkmcnt(0)
	s_barrier


; #define PG8_MMA(ai, bj, At, Bt) do { __builtin_amdgcn_s_setprio(1); _Pragma("unroll") for (int m = 0; m < 4; ++m) _Pragma("unroll") for (int n = 0; n < 2; ++n) _Pragma("unroll") for (int k = 0; k < 2; ++k) \
;         acc[ai][bj][m][n] = __builtin_amdgcn_mfma_f32_16x16x32_bf16(Bt[n][k], At[m][k], acc[ai][bj][m][n], 0, 0, 0); __builtin_amdgcn_s_setprio(0); } while (0)
; #define PG8_WAIT_V(n) asm volatile("s_waitcnt vmcnt(" #n ")" ::: "memory")
; #define PG8_WAIT_L(n) asm volatile("s_waitcnt lgkmcnt(" #n ")" ::: "memory")
; #define PG8_BAR __builtin_amdgcn_s_barrier()
; #define PG8_SCHED __builtin_amdgcn_sched_barrier(0)
; template <class Epi, bool ALIGN_EPI>
; __device__ __forceinline__ void gemm_phase(LAS unsigned char* lds, const Gemm g, const StaticOrder& S, const Epi& E, const int tid) {
;     ...
;             PG8_WAIT_V(8); PG8_WAIT_L(0); PG8_BAR; PG8_MMA(1, 0, At, B0); PG8_MMA(1, 1, At, B1); PG8_BAR; PG8_SCHED;
	v_mfma_f32_16x16x32_bf16 v[24:27], v[132:135], v[178:181], v[24:27]
	v_mfma_f32_16x16x32_bf16 v[24:27], v[136:139], v[182:185], v[24:27]
	v_mfma_f32_16x16x32_bf16 v[92:95], v[152:155], v[178:181], v[92:95]
	v_mfma_f32_16x16x32_bf16 v[92:95], v[156:159], v[182:185], v[92:95]
	v_mfma_f32_16x16x32_bf16 v[16:19], v[132:135], v[186:189], v[16:19]
	v_mfma_f32_16x16x32_bf16 v[16:19], v[136:139], v[190:193], v[16:19]
	v_mfma_f32_16x16x32_bf16 v[84:87], v[152:155], v[186:189], v[84:87]
	v_mfma_f32_16x16x32_bf16 v[84:87], v[156:159], v[190:193], v[84:87]
	v_mfma_f32_16x16x32_bf16 v[8:11], v[132:135], v[194:197], v[8:11]
	v_mfma_f32_16x16x32_bf16 v[8:11], v[136:139], v[198:201], v[8:11]
	v_mfma_f32_16x16x32_bf16 v[76:79], v[152:155], v[194:197], v[76:79]
	v_mfma_f32_16x16x32_bf16 v[76:79], v[156:159], v[198:201], v[76:79]
	v_mfma_f32_16x16x32_bf16 v[2:5], v[132:135], v[214:217], v[4:7]
	v_mfma_f32_16x16x32_bf16 v[2:5], v[136:139], v[218:221], v[2:5]
	v_mfma_f32_16x16x32_bf16 v[64:67], v[152:155], v[214:217], v[64:67]
	v_mfma_f32_16x16x32_bf16 v[64:67], v[156:159], v[218:221], v[64:67]


; #define PG8_MMA(ai, bj, At, Bt) do { __builtin_amdgcn_s_setprio(1); _Pragma("unroll") for (int m = 0; m < 4; ++m) _Pragma("unroll") for (int n = 0; n < 2; ++n) _Pragma("unroll") for (int k = 0; k < 2; ++k) \
;         acc[ai][bj][m][n] = __builtin_amdgcn_mfma_f32_16x16x32_bf16(Bt[n][k], At[m][k], acc[ai][bj][m][n], 0, 0, 0); __builtin_amdgcn_s_setprio(0); } while (0)
; #define PG8_WAIT_V(n) asm volatile("s_waitcnt vmcnt(" #n ")" ::: "memory")
; #define PG8_WAIT_L(n) asm volatile("s_waitcnt lgkmcnt(" #n ")" ::: "memory")
; #define PG8_BAR __builtin_amdgcn_s_barrier()
; #define PG8_SCHED __builtin_amdgcn_sched_barrier(0)
; template <class Epi, bool ALIGN_EPI>
; __device__ __forceinline__ void gemm_phase(LAS unsigned char* lds, const Gemm g, const StaticOrder& S, const Epi& E, const int tid) {
;     ...
;             PG8_WAIT_V(8); PG8_WAIT_L(0); PG8_BAR; PG8_MMA(1, 0, At, B0); PG8_MMA(1, 1, At, B1); PG8_BAR; PG8_SCHED;
	v_mfma_f32_16x16x32_bf16 v[32:35], v[162:165], v[178:181], v[32:35]
	v_mfma_f32_16x16x32_bf16 v[32:35], v[166:169], v[182:185], v[32:35]
	v_mfma_f32_16x16x32_bf16 v[72:75], v[170:173], v[178:181], v[72:75]
	v_mfma_f32_16x16x32_bf16 v[72:75], v[174:177], v[182:185], v[72:75]
	v_mfma_f32_16x16x32_bf16 v[28:31], v[162:165], v[186:189], v[28:31]
	v_mfma_f32_16x16x32_bf16 v[28:31], v[166:169], v[190:193], v[28:31]
	v_mfma_f32_16x16x32_bf16 v[96:99], v[170:173], v[186:189], v[96:99]
	v_mfma_f32_16x16x32_bf16 v[96:99], v[174:177], v[190:193], v[96:99]
	v_mfma_f32_16x16x32_bf16 v[20:23], v[162:165], v[194:197], v[20:23]
	v_mfma_f32_16x16x32_bf16 v[20:23], v[166:169], v[198:201], v[20:23]
	v_mfma_f32_16x16x32_bf16 v[56:59], v[170:173], v[194:197], v[56:59]
	v_mfma_f32_16x16x32_bf16 v[56:59], v[174:177], v[198:201], v[56:59]
	v_mfma_f32_16x16x32_bf16 v[12:15], v[162:165], v[214:217], v[12:15]
	v_mfma_f32_16x16x32_bf16 v[12:15], v[166:169], v[218:221], v[12:15]
	v_mfma_f32_16x16x32_bf16 v[44:47], v[170:173], v[214:217], v[44:47]
	v_mfma_f32_16x16x32_bf16 v[44:47], v[174:177], v[218:221], v[44:47]

; #define PG8_STAGE(bufoff, gbase, voff) do { _Pragma("unroll") for (int _i = 0; _i < 2; ++_i) \
;         __builtin_amdgcn_global_load_lds((const unsigned*)((const char*)(gbase) + (voff)[_i]), (LAS unsigned*)(lds + (bufoff) + ldsw + _i * 8192), 16, 0, 0); } while (0)
; #define PG8_LDA(dst, b, h) do { _Pragma("unroll") for (int m = 0; m < 4; ++m) _Pragma("unroll") for (int k = 0; k < 2; ++k) dst[m][k] = *(const LAS bf16x8*)(lds + PG8_SA(b, h) + aoff + m * 2048 + k * 1024); } while (0)
; #define PG8_LDB(dst, b, h) do { _Pragma("unroll") for (int n = 0; n < 2; ++n) _Pragma("unroll") for (int k = 0; k < 2; ++k) dst[n][k] = *(const LAS bf16x8*)(lds + PG8_SB(b, h) + boff + n * 2048 + k * 1024); } while (0)
; #define PG8_MMA(ai, bj, At, Bt) do { __builtin_amdgcn_s_setprio(1); _Pragma("unroll") for (int m = 0; m < 4; ++m) _Pragma("unroll") for (int n = 0; n < 2; ++n) _Pragma("unroll") for (int k = 0; k < 2; ++k) \
;         acc[ai][bj][m][n] = __builtin_amdgcn_mfma_f32_16x16x32_bf16(Bt[n][k], At[m][k], acc[ai][bj][m][n], 0, 0, 0); __builtin_amdgcn_s_setprio(0); } while (0)
; #define PG8_WAIT_V(n) asm volatile("s_waitcnt vmcnt(" #n ")" ::: "memory")
; #define PG8_WAIT_L(n) asm volatile("s_waitcnt lgkmcnt(" #n ")" ::: "memory")
; #define PG8_BAR __builtin_amdgcn_s_barrier()
; #define PG8_SCHED __builtin_amdgcn_sched_barrier(0)
; template <class Epi, bool ALIGN_EPI>
; __device__ __forceinline__ void gemm_phase(LAS unsigned char* lds, const Gemm g, const StaticOrder& S, const Epi& E, const int tid) {
;     ...
;             PG8_WAIT_V(8); PG8_WAIT_L(0); PG8_BAR; PG8_MMA(1, 0, At, B0); PG8_MMA(1, 1, At, B1); PG8_BAR; PG8_SCHED;
;             PG8_LDB(B0, 1, 0); PG8_LDB(B1, 1, 1); PG8_SCHED; PG8_LDA(At, 1, 0); PG8_STAGE(PG8_SA(0, 1), a2 + hstepA, voffA);
	s_barrier
	s_add_i32 s90, 0, 0x18000
	v_add_u32_e32 v0, s90, v160
	s_add_i32 s91, 0, 0x1c000
	ds_read_b128 v[132:135], v0
	ds_read_b128 v[136:139], v0 offset:1024
	ds_read_b128 v[152:155], v0 offset:2048
	ds_read_b128 v[156:159], v0 offset:3072
	v_add_u32_e32 v0, s91, v160
	ds_read_b128 v[162:165], v0
	ds_read_b128 v[166:169], v0 offset:1024
	ds_read_b128 v[170:173], v0 offset:2048
	ds_read_b128 v[174:177], v0 offset:3072
	s_add_u32 s54, s54, 0x4000
	s_addc_u32 s55, s55, 0
	s_mov_b32 m0, s74
	ds_read_b128 v[178:181], v161 offset:32768
	ds_read_b128 v[182:185], v161 offset:33792
	ds_read_b128 v[186:189], v161 offset:34816
	ds_read_b128 v[190:193], v161 offset:35840
	ds_read_b128 v[194:197], v161 offset:36864
	ds_read_b128 v[198:201], v161 offset:37888
	ds_read_b128 v[214:217], v161 offset:38912

; #define PG8_STAGE(bufoff, gbase, voff) do { _Pragma("unroll") for (int _i = 0; _i < 2; ++_i) \
;         __builtin_amdgcn_global_load_lds((const unsigned*)((const char*)(gbase) + (voff)[_i]), (LAS unsigned*)(lds + (bufoff) + ldsw + _i * 8192), 16, 0, 0); } while (0)
; #define PG8_LDA(dst, b, h) do { _Pragma("unroll") for (int m = 0; m < 4; ++m) _Pragma("unroll") for (int k = 0; k < 2; ++k) dst[m][k] = *(const LAS bf16x8*)(lds + PG8_SA(b, h) + aoff + m * 2048 + k * 1024); } while (0)
; #define PG8_LDB(dst, b, h) do { _Pragma("unroll") for (int n = 0; n < 2; ++n) _Pragma("unroll") for (int k = 0; k < 2; ++k) dst[n][k] = *(const LAS bf16x8*)(lds + PG8_SB(b, h) + boff + n * 2048 + k * 1024); } while (0)
; #define PG8_MMA(ai, bj, At, Bt) do { __builtin_amdgcn_s_setprio(1); _Pragma("unroll") for (int m = 0; m < 4; ++m) _Pragma("unroll") for (int n = 0; n < 2; ++n) _Pragma("unroll") for (int k = 0; k < 2; ++k) \
;         acc[ai][bj][m][n] = __builtin_amdgcn_mfma_f32_16x16x32_bf16(Bt[n][k], At[m][k], acc[ai][bj][m][n], 0, 0, 0); __builtin_amdgcn_s_setprio(0); } while (0)
; #define PG8_WAIT_V(n) asm volatile("s_waitcnt vmcnt(" #n ")" ::: "memory")
; #define PG8_WAIT_L(n) asm volatile("s_waitcnt lgkmcnt(" #n ")" ::: "memory")
; #define PG8_BAR __builtin_amdgcn_s_barrier()
; #define PG8_SCHED __builtin_amdgcn_sched_barrier(0)
; template <class Epi, bool ALIGN_EPI>
; __device__ __forceinline__ void gemm_phase(LAS unsigned char* lds, const Gemm g, const StaticOrder& S, const Epi& E, const int tid) {
;     ...
;             PG8_LDB(B0, 1, 0); PG8_LDB(B1, 1, 1); PG8_SCHED; PG8_LDA(At, 1, 0); PG8_STAGE(PG8_SA(0, 1), a2 + hstepA, voffA);
;             PG8_WAIT_V(8); PG8_WAIT_L(0); PG8_BAR; PG8_MMA(0, 0, At, B0); PG8_MMA(0, 1, At, B1); PG8_BAR; PG8_SCHED;
	global_load_lds_dwordx4 v146, s[54:55]
	s_mov_b32 m0, s75
	ds_read_b128 v[218:221], v161 offset:39936
	global_load_lds_dwordx4 v142, s[54:55]
	s_waitcnt vmcnt(8)
	s_waitcnt lgkmcnt(0)
	s_barrier


; #define PG8_MMA(ai, bj, At, Bt) do { __builtin_amdgcn_s_setprio(1); _Pragma("unroll") for (int m = 0; m < 4; ++m) _Pragma("unroll") for (int n = 0; n < 2; ++n) _Pragma("unroll") for (int k = 0; k < 2; ++k) \
;         acc[ai][bj][m][n] = __builtin_amdgcn_mfma_f32_16x16x32_bf16(Bt[n][k], At[m][k], acc[ai][bj][m][n], 0, 0, 0); __builtin_amdgcn_s_setprio(0); } while (0)
; #define PG8_WAIT_V(n) asm volatile("s_waitcnt vmcnt(" #n ")" ::: "memory")
; #define PG8_WAIT_L(n) asm volatile("s_waitcnt lgkmcnt(" #n ")" ::: "memory")
; #define PG8_BAR __builtin_amdgcn_s_barrier()
; #define PG8_SCHED __builtin_amdgcn_sched_barrier(0)
; template <class Epi, bool ALIGN_EPI>
; __device__ __forceinline__ void gemm_phase(LAS unsigned char* lds, const Gemm g, const StaticOrder& S, const Epi& E, const int tid) {
;     ...
;             PG8_WAIT_V(8); PG8_WAIT_L(0); PG8_BAR; PG8_MMA(0, 0, At, B0); PG8_MMA(0, 1, At, B1); PG8_BAR; PG8_SCHED;
	v_mfma_f32_16x16x32_bf16 v[88:91], v[132:135], v[178:181], v[88:91]
	v_mfma_f32_16x16x32_bf16 v[88:91], v[136:139], v[182:185], v[88:91]
	v_mfma_f32_16x16x32_bf16 v[124:127], v[152:155], v[178:181], v[124:127]
	v_mfma_f32_16x16x32_bf16 v[124:127], v[156:159], v[182:185], v[124:127]
	v_mfma_f32_16x16x32_bf16 v[52:55], v[132:135], v[186:189], v[52:55]
	v_mfma_f32_16x16x32_bf16 v[52:55], v[136:139], v[190:193], v[52:55]
	v_mfma_f32_16x16x32_bf16 v[120:123], v[152:155], v[186:189], v[120:123]
	v_mfma_f32_16x16x32_bf16 v[120:123], v[156:159], v[190:193], v[120:123]
	v_mfma_f32_16x16x32_bf16 v[40:43], v[132:135], v[194:197], v[40:43]
	v_mfma_f32_16x16x32_bf16 v[40:43], v[136:139], v[198:201], v[40:43]
	v_mfma_f32_16x16x32_bf16 v[116:119], v[152:155], v[194:197], v[116:119]
	v_mfma_f32_16x16x32_bf16 v[116:119], v[156:159], v[198:201], v[116:119]
	v_mfma_f32_16x16x32_bf16 v[36:39], v[132:135], v[214:217], v[36:39]
	v_mfma_f32_16x16x32_bf16 v[36:39], v[136:139], v[218:221], v[36:39]
	v_mfma_f32_16x16x32_bf16 v[112:115], v[152:155], v[214:217], v[112:115]
	v_mfma_f32_16x16x32_bf16 v[112:115], v[156:159], v[218:221], v[112:115]


; #define PG8_MMA(ai, bj, At, Bt) do { __builtin_amdgcn_s_setprio(1); _Pragma("unroll") for (int m = 0; m < 4; ++m) _Pragma("unroll") for (int n = 0; n < 2; ++n) _Pragma("unroll") for (int k = 0; k < 2; ++k) \
;         acc[ai][bj][m][n] = __builtin_amdgcn_mfma_f32_16x16x32_bf16(Bt[n][k], At[m][k], acc[ai][bj][m][n], 0, 0, 0); __builtin_amdgcn_s_setprio(0); } while (0)
; #define PG8_WAIT_V(n) asm volatile("s_waitcnt vmcnt(" #n ")" ::: "memory")
; #define PG8_WAIT_L(n) asm volatile("s_waitcnt lgkmcnt(" #n ")" ::: "memory")
; #define PG8_BAR __builtin_amdgcn_s_barrier()
; #define PG8_SCHED __builtin_amdgcn_sched_barrier(0)
; template <class Epi, bool ALIGN_EPI>
; __device__ __forceinline__ void gemm_phase(LAS unsigned char* lds, const Gemm g, const StaticOrder& S, const Epi& E, const int tid) {
;     ...
;             PG8_WAIT_V(8); PG8_WAIT_L(0); PG8_BAR; PG8_MMA(0, 0, At, B0); PG8_MMA(0, 1, At, B1); PG8_BAR; PG8_SCHED;
	v_mfma_f32_16x16x32_bf16 v[80:83], v[162:165], v[178:181], v[80:83]
	v_mfma_f32_16x16x32_bf16 v[80:83], v[166:169], v[182:185], v[80:83]
	v_mfma_f32_16x16x32_bf16 v[128:131], v[170:173], v[178:181], v[128:131]
	v_mfma_f32_16x16x32_bf16 v[128:131], v[174:177], v[182:185], v[128:131]
	v_mfma_f32_16x16x32_bf16 v[68:71], v[162:165], v[186:189], v[68:71]
	v_mfma_f32_16x16x32_bf16 v[68:71], v[166:169], v[190:193], v[68:71]
	v_mfma_f32_16x16x32_bf16 v[108:111], v[170:173], v[186:189], v[108:111]
	v_mfma_f32_16x16x32_bf16 v[108:111], v[174:177], v[190:193], v[108:111]
	v_mfma_f32_16x16x32_bf16 v[60:63], v[162:165], v[194:197], v[60:63]
	v_mfma_f32_16x16x32_bf16 v[60:63], v[166:169], v[198:201], v[60:63]
	v_mfma_f32_16x16x32_bf16 v[104:107], v[170:173], v[194:197], v[104:107]
	v_mfma_f32_16x16x32_bf16 v[104:107], v[174:177], v[198:201], v[104:107]
	v_mfma_f32_16x16x32_bf16 v[48:51], v[162:165], v[214:217], v[48:51]
	v_mfma_f32_16x16x32_bf16 v[48:51], v[166:169], v[218:221], v[48:51]
	v_mfma_f32_16x16x32_bf16 v[100:103], v[170:173], v[214:217], v[100:103]
	v_mfma_f32_16x16x32_bf16 v[100:103], v[174:177], v[218:221], v[100:103]

; #define PG8_STAGE(bufoff, gbase, voff) do { _Pragma("unroll") for (int _i = 0; _i < 2; ++_i) \
;         __builtin_amdgcn_global_load_lds((const unsigned*)((const char*)(gbase) + (voff)[_i]), (LAS unsigned*)(lds + (bufoff) + ldsw + _i * 8192), 16, 0, 0); } while (0)
; #define PG8_LDA(dst, b, h) do { _Pragma("unroll") for (int m = 0; m < 4; ++m) _Pragma("unroll") for (int k = 0; k < 2; ++k) dst[m][k] = *(const LAS bf16x8*)(lds + PG8_SA(b, h) + aoff + m * 2048 + k * 1024); } while (0)
; #define PG8_MMA(ai, bj, At, Bt) do { __builtin_amdgcn_s_setprio(1); _Pragma("unroll") for (int m = 0; m < 4; ++m) _Pragma("unroll") for (int n = 0; n < 2; ++n) _Pragma("unroll") for (int k = 0; k < 2; ++k) \
;         acc[ai][bj][m][n] = __builtin_amdgcn_mfma_f32_16x16x32_bf16(Bt[n][k], At[m][k], acc[ai][bj][m][n], 0, 0, 0); __builtin_amdgcn_s_setprio(0); } while (0)
; #define PG8_WAIT_V(n) asm volatile("s_waitcnt vmcnt(" #n ")" ::: "memory")
; #define PG8_WAIT_L(n) asm volatile("s_waitcnt lgkmcnt(" #n ")" ::: "memory")
; #define PG8_BAR __builtin_amdgcn_s_barrier()
; #define PG8_SCHED __builtin_amdgcn_sched_barrier(0)
; template <class Epi, bool ALIGN_EPI>
; __device__ __forceinline__ void gemm_phase(LAS unsigned char* lds, const Gemm g, const StaticOrder& S, const Epi& E, const int tid) {
;     ...
;             PG8_WAIT_V(8); PG8_WAIT_L(0); PG8_BAR; PG8_MMA(0, 0, At, B0); PG8_MMA(0, 1, At, B1); PG8_BAR; PG8_SCHED;
;             PG8_LDA(At, 1, 1); PG8_STAGE(PG8_SB(1, 0), b3, voffB); PG8_STAGE(PG8_SB(1, 1), b3 + hstepB, voffB); PG8_STAGE(PG8_SA(1, 0), a3, voffA);
	s_barrier
	s_add_u32 s54, s52, 0x8000
	s_addc_u32 s55, s53, 0
	s_add_i32 s90, s90, s71
	s_mov_b32 m0, s90
	ds_read_b128 v[178:181], v161 offset:49152
	ds_read_b128 v[182:185], v161 offset:50176
	ds_read_b128 v[186:189], v161 offset:51200
	ds_read_b128 v[190:193], v161 offset:52224


; #define PG8_STAGE(bufoff, gbase, voff) do { _Pragma("unroll") for (int _i = 0; _i < 2; ++_i) \
;         __builtin_amdgcn_global_load_lds((const unsigned*)((const char*)(gbase) + (voff)[_i]), (LAS unsigned*)(lds + (bufoff) + ldsw + _i * 8192), 16, 0, 0); } while (0)
; #define PG8_LDA(dst, b, h) do { _Pragma("unroll") for (int m = 0; m < 4; ++m) _Pragma("unroll") for (int k = 0; k < 2; ++k) dst[m][k] = *(const LAS bf16x8*)(lds + PG8_SA(b, h) + aoff + m * 2048 + k * 1024); } while (0)
; #define PG8_MMA(ai, bj, At, Bt) do { __builtin_amdgcn_s_setprio(1); _Pragma("unroll") for (int m = 0; m < 4; ++m) _Pragma("unroll") for (int n = 0; n < 2; ++n) _Pragma("unroll") for (int k = 0; k < 2; ++k) \
;         acc[ai][bj][m][n] = __builtin_amdgcn_mfma_f32_16x16x32_bf16(Bt[n][k], At[m][k], acc[ai][bj][m][n], 0, 0, 0); __builtin_amdgcn_s_setprio(0); } while (0)
; #define PG8_WAIT_V(n) asm volatile("s_waitcnt vmcnt(" #n ")" ::: "memory")
; #define PG8_WAIT_L(n) asm volatile("s_waitcnt lgkmcnt(" #n ")" ::: "memory")
; #define PG8_BAR __builtin_amdgcn_s_barrier()
; #define PG8_SCHED __builtin_amdgcn_sched_barrier(0)
; template <class Epi, bool ALIGN_EPI>
; __device__ __forceinline__ void gemm_phase(LAS unsigned char* lds, const Gemm g, const StaticOrder& S, const Epi& E, const int tid) {
;     ...
;             PG8_LDA(At, 1, 1); PG8_STAGE(PG8_SB(1, 0), b3, voffB); PG8_STAGE(PG8_SB(1, 1), b3 + hstepB, voffB); PG8_STAGE(PG8_SA(1, 0), a3, voffA);
;             PG8_WAIT_V(8); PG8_WAIT_L(0); PG8_BAR; PG8_MMA(1, 0, At, B0); PG8_MMA(1, 1, At, B1); PG8_BAR; PG8_SCHED;
	global_load_lds_dwordx4 v144, s[54:55]
	s_add_i32 m0, s90, 0x2000
	s_add_u32 s52, s52, 0xc000
	s_addc_u32 s53, s53, 0
	global_load_lds_dwordx4 v140, s[54:55]
	s_add_i32 s54, s91, s71
	s_mov_b32 m0, s54
	ds_read_b128 v[218:221], v161 offset:56320
	global_load_lds_dwordx4 v144, s[52:53]
	s_add_i32 m0, s54, 0x2000
	ds_read_b128 v[214:217], v161 offset:55296
	global_load_lds_dwordx4 v140, s[52:53]
	s_mov_b32 m0, s79
	ds_read_b128 v[198:201], v161 offset:54272
	global_load_lds_dwordx4 v146, s[50:51]
	s_mov_b32 m0, s80
	ds_read_b128 v[194:197], v161 offset:53248
	global_load_lds_dwordx4 v142, s[50:51]
	s_waitcnt vmcnt(8)
	s_waitcnt lgkmcnt(0)
	s_barrier


; #define PG8_MMA(ai, bj, At, Bt) do { __builtin_amdgcn_s_setprio(1); _Pragma("unroll") for (int m = 0; m < 4; ++m) _Pragma("unroll") for (int n = 0; n < 2; ++n) _Pragma("unroll") for (int k = 0; k < 2; ++k) \
;         acc[ai][bj][m][n] = __builtin_amdgcn_mfma_f32_16x16x32_bf16(Bt[n][k], At[m][k], acc[ai][bj][m][n], 0, 0, 0); __builtin_amdgcn_s_setprio(0); } while (0)
; #define PG8_WAIT_V(n) asm volatile("s_waitcnt vmcnt(" #n ")" ::: "memory")
; #define PG8_WAIT_L(n) asm volatile("s_waitcnt lgkmcnt(" #n ")" ::: "memory")
; #define PG8_BAR __builtin_amdgcn_s_barrier()
; #define PG8_SCHED __builtin_amdgcn_sched_barrier(0)
; template <class Epi, bool ALIGN_EPI>
; __device__ __forceinline__ void gemm_phase(LAS unsigned char* lds, const Gemm g, const StaticOrder& S, const Epi& E, const int tid) {
;     ...
;             PG8_WAIT_V(8); PG8_WAIT_L(0); PG8_BAR; PG8_MMA(1, 0, At, B0); PG8_MMA(1, 1, At, B1); PG8_BAR; PG8_SCHED;
	v_mfma_f32_16x16x32_bf16 v[24:27], v[132:135], v[178:181], v[24:27]
	v_mfma_f32_16x16x32_bf16 v[24:27], v[136:139], v[182:185], v[24:27]
	v_mfma_f32_16x16x32_bf16 v[92:95], v[152:155], v[178:181], v[92:95]
	v_mfma_f32_16x16x32_bf16 v[92:95], v[156:159], v[182:185], v[92:95]
	v_mfma_f32_16x16x32_bf16 v[16:19], v[132:135], v[186:189], v[16:19]
	v_mfma_f32_16x16x32_bf16 v[16:19], v[136:139], v[190:193], v[16:19]
	v_mfma_f32_16x16x32_bf16 v[84:87], v[152:155], v[186:189], v[84:87]
	v_mfma_f32_16x16x32_bf16 v[84:87], v[156:159], v[190:193], v[84:87]
	v_mfma_f32_16x16x32_bf16 v[6:9], v[132:135], v[194:197], v[8:11]
	v_mfma_f32_16x16x32_bf16 v[8:11], v[136:139], v[198:201], v[6:9]
	v_mfma_f32_16x16x32_bf16 v[76:79], v[152:155], v[194:197], v[76:79]
	v_mfma_f32_16x16x32_bf16 v[76:79], v[156:159], v[198:201], v[76:79]
	v_mfma_f32_16x16x32_bf16 v[2:5], v[132:135], v[214:217], v[2:5]
	v_mfma_f32_16x16x32_bf16 v[4:7], v[136:139], v[218:221], v[2:5]
	v_mfma_f32_16x16x32_bf16 v[64:67], v[152:155], v[214:217], v[64:67]
	v_mfma_f32_16x16x32_bf16 v[64:67], v[156:159], v[218:221], v[64:67]


; #define PG8_MMA(ai, bj, At, Bt) do { __builtin_amdgcn_s_setprio(1); _Pragma("unroll") for (int m = 0; m < 4; ++m) _Pragma("unroll") for (int n = 0; n < 2; ++n) _Pragma("unroll") for (int k = 0; k < 2; ++k) \
;         acc[ai][bj][m][n] = __builtin_amdgcn_mfma_f32_16x16x32_bf16(Bt[n][k], At[m][k], acc[ai][bj][m][n], 0, 0, 0); __builtin_amdgcn_s_setprio(0); } while (0)
; #define PG8_WAIT_V(n) asm volatile("s_waitcnt vmcnt(" #n ")" ::: "memory")
; #define PG8_WAIT_L(n) asm volatile("s_waitcnt lgkmcnt(" #n ")" ::: "memory")
; #define PG8_BAR __builtin_amdgcn_s_barrier()
; #define PG8_SCHED __builtin_amdgcn_sched_barrier(0)
; template <class Epi, bool ALIGN_EPI>
; __device__ __forceinline__ void gemm_phase(LAS unsigned char* lds, const Gemm g, const StaticOrder& S, const Epi& E, const int tid) {
;     ...
;             PG8_WAIT_V(8); PG8_WAIT_L(0); PG8_BAR; PG8_MMA(1, 0, At, B0); PG8_MMA(1, 1, At, B1); PG8_BAR; PG8_SCHED;
	v_mfma_f32_16x16x32_bf16 v[32:35], v[162:165], v[178:181], v[32:35]
	v_mfma_f32_16x16x32_bf16 v[32:35], v[166:169], v[182:185], v[32:35]
	v_mfma_f32_16x16x32_bf16 v[72:75], v[170:173], v[178:181], v[72:75]
	v_mfma_f32_16x16x32_bf16 v[72:75], v[174:177], v[182:185], v[72:75]
	v_mfma_f32_16x16x32_bf16 v[28:31], v[162:165], v[186:189], v[28:31]
	v_mfma_f32_16x16x32_bf16 v[28:31], v[166:169], v[190:193], v[28:31]
	v_mfma_f32_16x16x32_bf16 v[96:99], v[170:173], v[186:189], v[96:99]
	v_mfma_f32_16x16x32_bf16 v[96:99], v[174:177], v[190:193], v[96:99]
	v_mfma_f32_16x16x32_bf16 v[20:23], v[162:165], v[194:197], v[20:23]
	v_mfma_f32_16x16x32_bf16 v[20:23], v[166:169], v[198:201], v[20:23]
	v_mfma_f32_16x16x32_bf16 v[56:59], v[170:173], v[194:197], v[56:59]
	v_mfma_f32_16x16x32_bf16 v[56:59], v[174:177], v[198:201], v[56:59]
	v_mfma_f32_16x16x32_bf16 v[12:15], v[162:165], v[214:217], v[12:15]
	v_mfma_f32_16x16x32_bf16 v[12:15], v[166:169], v[218:221], v[12:15]
	v_mfma_f32_16x16x32_bf16 v[44:47], v[170:173], v[214:217], v[44:47]
	v_mfma_f32_16x16x32_bf16 v[44:47], v[174:177], v[218:221], v[44:47]

; #define PG8_MMA(ai, bj, At, Bt) do { __builtin_amdgcn_s_setprio(1); _Pragma("unroll") for (int m = 0; m < 4; ++m) _Pragma("unroll") for (int n = 0; n < 2; ++n) _Pragma("unroll") for (int k = 0; k < 2; ++k) \
;         acc[ai][bj][m][n] = __builtin_amdgcn_mfma_f32_16x16x32_bf16(Bt[n][k], At[m][k], acc[ai][bj][m][n], 0, 0, 0); __builtin_amdgcn_s_setprio(0); } while (0)
; #define PG8_WAIT_V(n) asm volatile("s_waitcnt vmcnt(" #n ")" ::: "memory")
; #define PG8_WAIT_L(n) asm volatile("s_waitcnt lgkmcnt(" #n ")" ::: "memory")
; #define PG8_BAR __builtin_amdgcn_s_barrier()
; #define PG8_SCHED __builtin_amdgcn_sched_barrier(0)
; template <class Epi, bool ALIGN_EPI>
; __device__ __forceinline__ void gemm_phase(LAS unsigned char* lds, const Gemm g, const StaticOrder& S, const Epi& E, const int tid) {
;     ...
;             PG8_WAIT_V(8); PG8_WAIT_L(0); PG8_BAR; PG8_MMA(1, 0, At, B0); PG8_MMA(1, 1, At, B1); PG8_BAR; PG8_SCHED;
;         }
;         if constexpr (ALIGN_EPI) { if (wr == 0) PG8_BAR; }
	s_barrier
	s_add_i32 s89, s89, 2
	s_add_u32 s48, s48, 0x10000
	s_addc_u32 s49, s49, 0
	s_add_u32 vcc_hi, vcc_hi, 0x10000
	s_addc_u32 s88, s88, 0
	s_cmp_gt_u32 s89, 29
	s_cbranch_scc0 .LBB0_211
	s_and_b64 vcc, exec, s[22:23]
	s_cbranch_vccz .LBB0_214
	s_barrier

; #define PG8_STAGE(bufoff, gbase, voff) do { _Pragma("unroll") for (int _i = 0; _i < 2; ++_i) \
;         __builtin_amdgcn_global_load_lds((const unsigned*)((const char*)(gbase) + (voff)[_i]), (LAS unsigned*)(lds + (bufoff) + ldsw + _i * 8192), 16, 0, 0); } while (0)
; #define PG8_LDA(dst, b, h) do { _Pragma("unroll") for (int m = 0; m < 4; ++m) _Pragma("unroll") for (int k = 0; k < 2; ++k) dst[m][k] = *(const LAS bf16x8*)(lds + PG8_SA(b, h) + aoff + m * 2048 + k * 1024); } while (0)
; #define PG8_LDB(dst, b, h) do { _Pragma("unroll") for (int n = 0; n < 2; ++n) _Pragma("unroll") for (int k = 0; k < 2; ++k) dst[n][k] = *(const LAS bf16x8*)(lds + PG8_SB(b, h) + boff + n * 2048 + k * 1024); } while (0)
; #define PG8_SCHED __builtin_amdgcn_sched_barrier(0)
; template <class Epi, bool ALIGN_EPI>
; __device__ __forceinline__ void gemm_phase(LAS unsigned char* lds, const Gemm g, const StaticOrder& S, const Epi& E, const int tid) {
;     ...
;             const bool last = (t == nt - 2);
;             const char* a1 = cA + (size_t)(t + 1) * kstepA;
;             const char* a2 = last ? nA : cA + (size_t)(t + 2) * kstepA; const char* b2 = last ? nB : cB + (size_t)(t + 2) * kstepB;
;             const char* a3 = a2 + kstepA; const char* b3 = b2 + kstepB;
;             PG8_LDB(B0, 0, 0); PG8_LDB(B1, 0, 1); PG8_SCHED; PG8_LDA(At, 0, 0); PG8_STAGE(PG8_SA(1, 1), a1 + hstepA, voffA);
.LBB0_294:
	s_add_u32 s22, s10, 0x4000
	s_addc_u32 s23, s11, 0
	s_cmpk_eq_i32 s86, 0x54
	s_cselect_b32 s42, s48, s22
	s_cselect_b32 s43, s49, s23
	s_cselect_b32 s34, s50, s84
	s_cselect_b32 s35, s51, s85
	s_add_u32 s22, s42, 0x8000
	s_addc_u32 s23, s43, 0
	s_add_i32 s87, 0, 0x10000
	v_add_u32_e32 v0, s87, v154
	s_add_i32 s90, 0, 0x14000
	s_waitcnt lgkmcnt(0)
	ds_read_b128 v[132:135], v0
	ds_read_b128 v[148:151], v0 offset:1024
	ds_read_b128 v[156:159], v0 offset:2048
	ds_read_b128 v[160:163], v0 offset:3072
	v_add_u32_e32 v0, s90, v154
	ds_read_b128 v[164:167], v0
	ds_read_b128 v[168:171], v0 offset:1024
	ds_read_b128 v[172:175], v0 offset:2048
	ds_read_b128 v[176:179], v0 offset:3072
	s_add_i32 m0, s57, 0xc000
	ds_read_b128 v[180:183], v155
	ds_read_b128 v[184:187], v155 offset:1024
	ds_read_b128 v[188:191], v155 offset:2048
	ds_read_b128 v[192:195], v155 offset:3072
	ds_read_b128 v[196:199], v155 offset:4096
	ds_read_b128 v[214:217], v155 offset:5120
	ds_read_b128 v[218:221], v155 offset:6144

; #define PG8_STAGE(bufoff, gbase, voff) do { _Pragma("unroll") for (int _i = 0; _i < 2; ++_i) \
;         __builtin_amdgcn_global_load_lds((const unsigned*)((const char*)(gbase) + (voff)[_i]), (LAS unsigned*)(lds + (bufoff) + ldsw + _i * 8192), 16, 0, 0); } while (0)
; #define PG8_LDA(dst, b, h) do { _Pragma("unroll") for (int m = 0; m < 4; ++m) _Pragma("unroll") for (int k = 0; k < 2; ++k) dst[m][k] = *(const LAS bf16x8*)(lds + PG8_SA(b, h) + aoff + m * 2048 + k * 1024); } while (0)
; #define PG8_LDB(dst, b, h) do { _Pragma("unroll") for (int n = 0; n < 2; ++n) _Pragma("unroll") for (int k = 0; k < 2; ++k) dst[n][k] = *(const LAS bf16x8*)(lds + PG8_SB(b, h) + boff + n * 2048 + k * 1024); } while (0)
; #define PG8_MMA(ai, bj, At, Bt) do { __builtin_amdgcn_s_setprio(1); _Pragma("unroll") for (int m = 0; m < 4; ++m) _Pragma("unroll") for (int n = 0; n < 2; ++n) _Pragma("unroll") for (int k = 0; k < 2; ++k) \
;         acc[ai][bj][m][n] = __builtin_amdgcn_mfma_f32_16x16x32_bf16(Bt[n][k], At[m][k], acc[ai][bj][m][n], 0, 0, 0); __builtin_amdgcn_s_setprio(0); } while (0)
; #define PG8_WAIT_V(n) asm volatile("s_waitcnt vmcnt(" #n ")" ::: "memory")
; #define PG8_WAIT_L(n) asm volatile("s_waitcnt lgkmcnt(" #n ")" ::: "memory")
; #define PG8_BAR __builtin_amdgcn_s_barrier()
; #define PG8_SCHED __builtin_amdgcn_sched_barrier(0)
; template <class Epi, bool ALIGN_EPI>
; __device__ __forceinline__ void gemm_phase(LAS unsigned char* lds, const Gemm g, const StaticOrder& S, const Epi& E, const int tid) {
;     ...
;             PG8_LDB(B0, 0, 0); PG8_LDB(B1, 0, 1); PG8_SCHED; PG8_LDA(At, 0, 0); PG8_STAGE(PG8_SA(1, 1), a1 + hstepA, voffA);
;             PG8_WAIT_V(8); PG8_WAIT_L(0); PG8_BAR; PG8_MMA(0, 0, At, B0); PG8_MMA(0, 1, At, B1); PG8_BAR; PG8_SCHED;
	global_load_lds_dwordx4 v144, s[10:11]
	s_add_i32 m0, s57, 0xe000
	ds_read_b128 v[222:225], v155 offset:7168
	global_load_lds_dwordx4 v146, s[10:11]
	s_waitcnt vmcnt(8)
	s_waitcnt lgkmcnt(0)
	s_barrier


; #define PG8_MMA(ai, bj, At, Bt) do { __builtin_amdgcn_s_setprio(1); _Pragma("unroll") for (int m = 0; m < 4; ++m) _Pragma("unroll") for (int n = 0; n < 2; ++n) _Pragma("unroll") for (int k = 0; k < 2; ++k) \
;         acc[ai][bj][m][n] = __builtin_amdgcn_mfma_f32_16x16x32_bf16(Bt[n][k], At[m][k], acc[ai][bj][m][n], 0, 0, 0); __builtin_amdgcn_s_setprio(0); } while (0)
; #define PG8_WAIT_V(n) asm volatile("s_waitcnt vmcnt(" #n ")" ::: "memory")
; #define PG8_WAIT_L(n) asm volatile("s_waitcnt lgkmcnt(" #n ")" ::: "memory")
; #define PG8_BAR __builtin_amdgcn_s_barrier()
; #define PG8_SCHED __builtin_amdgcn_sched_barrier(0)
; template <class Epi, bool ALIGN_EPI>
; __device__ __forceinline__ void gemm_phase(LAS unsigned char* lds, const Gemm g, const StaticOrder& S, const Epi& E, const int tid) {
;     ...
;             PG8_WAIT_V(8); PG8_WAIT_L(0); PG8_BAR; PG8_MMA(0, 0, At, B0); PG8_MMA(0, 1, At, B1); PG8_BAR; PG8_SCHED;
	v_mfma_f32_16x16x32_bf16 v[8:11], v[132:135], v[180:183], v[8:11]
	v_mfma_f32_16x16x32_bf16 v[8:11], v[148:151], v[184:187], v[8:11]
	v_mfma_f32_16x16x32_bf16 v[56:59], v[156:159], v[180:183], v[56:59]
	v_mfma_f32_16x16x32_bf16 v[56:59], v[160:163], v[184:187], v[56:59]
	v_mfma_f32_16x16x32_bf16 v[52:55], v[132:135], v[188:191], v[52:55]
	v_mfma_f32_16x16x32_bf16 v[52:55], v[148:151], v[192:195], v[52:55]
	v_mfma_f32_16x16x32_bf16 v[48:51], v[156:159], v[188:191], v[48:51]
	v_mfma_f32_16x16x32_bf16 v[48:51], v[160:163], v[192:195], v[48:51]
	v_mfma_f32_16x16x32_bf16 v[44:47], v[132:135], v[196:199], v[44:47]
	v_mfma_f32_16x16x32_bf16 v[44:47], v[148:151], v[214:217], v[44:47]
	v_mfma_f32_16x16x32_bf16 v[40:43], v[156:159], v[196:199], v[40:43]
	v_mfma_f32_16x16x32_bf16 v[40:43], v[160:163], v[214:217], v[40:43]
	v_mfma_f32_16x16x32_bf16 v[36:39], v[132:135], v[218:221], v[36:39]
	v_mfma_f32_16x16x32_bf16 v[36:39], v[148:151], v[222:225], v[36:39]
	v_mfma_f32_16x16x32_bf16 v[32:35], v[156:159], v[218:221], v[32:35]
	v_mfma_f32_16x16x32_bf16 v[32:35], v[160:163], v[222:225], v[32:35]


; #define PG8_MMA(ai, bj, At, Bt) do { __builtin_amdgcn_s_setprio(1); _Pragma("unroll") for (int m = 0; m < 4; ++m) _Pragma("unroll") for (int n = 0; n < 2; ++n) _Pragma("unroll") for (int k = 0; k < 2; ++k) \
;         acc[ai][bj][m][n] = __builtin_amdgcn_mfma_f32_16x16x32_bf16(Bt[n][k], At[m][k], acc[ai][bj][m][n], 0, 0, 0); __builtin_amdgcn_s_setprio(0); } while (0)
; #define PG8_WAIT_V(n) asm volatile("s_waitcnt vmcnt(" #n ")" ::: "memory")
; #define PG8_WAIT_L(n) asm volatile("s_waitcnt lgkmcnt(" #n ")" ::: "memory")
; #define PG8_BAR __builtin_amdgcn_s_barrier()
; #define PG8_SCHED __builtin_amdgcn_sched_barrier(0)
; template <class Epi, bool ALIGN_EPI>
; __device__ __forceinline__ void gemm_phase(LAS unsigned char* lds, const Gemm g, const StaticOrder& S, const Epi& E, const int tid) {
;     ...
;             PG8_WAIT_V(8); PG8_WAIT_L(0); PG8_BAR; PG8_MMA(0, 0, At, B0); PG8_MMA(0, 1, At, B1); PG8_BAR; PG8_SCHED;
	v_mfma_f32_16x16x32_bf16 v[2:5], v[164:167], v[180:183], v[4:7]
	v_mfma_f32_16x16x32_bf16 v[2:5], v[168:171], v[184:187], v[2:5]
	v_mfma_f32_16x16x32_bf16 v[28:31], v[172:175], v[180:183], v[28:31]
	v_mfma_f32_16x16x32_bf16 v[28:31], v[176:179], v[184:187], v[28:31]
	v_mfma_f32_16x16x32_bf16 v[96:99], v[164:167], v[188:191], v[96:99]
	v_mfma_f32_16x16x32_bf16 v[96:99], v[168:171], v[192:195], v[96:99]
	v_mfma_f32_16x16x32_bf16 v[92:95], v[172:175], v[188:191], v[92:95]
	v_mfma_f32_16x16x32_bf16 v[92:95], v[176:179], v[192:195], v[92:95]
	v_mfma_f32_16x16x32_bf16 v[88:91], v[164:167], v[196:199], v[88:91]
	v_mfma_f32_16x16x32_bf16 v[88:91], v[168:171], v[214:217], v[88:91]
	v_mfma_f32_16x16x32_bf16 v[84:87], v[172:175], v[196:199], v[84:87]
	v_mfma_f32_16x16x32_bf16 v[84:87], v[176:179], v[214:217], v[84:87]
	v_mfma_f32_16x16x32_bf16 v[80:83], v[164:167], v[218:221], v[80:83]
	v_mfma_f32_16x16x32_bf16 v[80:83], v[168:171], v[222:225], v[80:83]
	v_mfma_f32_16x16x32_bf16 v[76:79], v[172:175], v[218:221], v[76:79]
	v_mfma_f32_16x16x32_bf16 v[76:79], v[176:179], v[222:225], v[76:79]

; #define PG8_STAGE(bufoff, gbase, voff) do { _Pragma("unroll") for (int _i = 0; _i < 2; ++_i) \
;         __builtin_amdgcn_global_load_lds((const unsigned*)((const char*)(gbase) + (voff)[_i]), (LAS unsigned*)(lds + (bufoff) + ldsw + _i * 8192), 16, 0, 0); } while (0)
; #define PG8_LDA(dst, b, h) do { _Pragma("unroll") for (int m = 0; m < 4; ++m) _Pragma("unroll") for (int k = 0; k < 2; ++k) dst[m][k] = *(const LAS bf16x8*)(lds + PG8_SA(b, h) + aoff + m * 2048 + k * 1024); } while (0)
; #define PG8_MMA(ai, bj, At, Bt) do { __builtin_amdgcn_s_setprio(1); _Pragma("unroll") for (int m = 0; m < 4; ++m) _Pragma("unroll") for (int n = 0; n < 2; ++n) _Pragma("unroll") for (int k = 0; k < 2; ++k) \
;         acc[ai][bj][m][n] = __builtin_amdgcn_mfma_f32_16x16x32_bf16(Bt[n][k], At[m][k], acc[ai][bj][m][n], 0, 0, 0); __builtin_amdgcn_s_setprio(0); } while (0)
; #define PG8_WAIT_V(n) asm volatile("s_waitcnt vmcnt(" #n ")" ::: "memory")
; #define PG8_WAIT_L(n) asm volatile("s_waitcnt lgkmcnt(" #n ")" ::: "memory")
; #define PG8_BAR __builtin_amdgcn_s_barrier()
; #define PG8_SCHED __builtin_amdgcn_sched_barrier(0)
; template <class Epi, bool ALIGN_EPI>
; __device__ __forceinline__ void gemm_phase(LAS unsigned char* lds, const Gemm g, const StaticOrder& S, const Epi& E, const int tid) {
;     ...
;             PG8_WAIT_V(8); PG8_WAIT_L(0); PG8_BAR; PG8_MMA(0, 0, At, B0); PG8_MMA(0, 1, At, B1); PG8_BAR; PG8_SCHED;
;             PG8_LDA(At, 0, 1); PG8_STAGE(PG8_SB(0, 0), b2, voffB); PG8_STAGE(PG8_SB(0, 1), b2 + hstepB, voffB); PG8_STAGE(PG8_SA(0, 0), a2, voffA);
	s_barrier
	s_add_i32 s87, s87, s56
	s_mov_b32 m0, s87
	ds_read_b128 v[180:183], v155 offset:16384
	ds_read_b128 v[184:187], v155 offset:17408
	ds_read_b128 v[188:191], v155 offset:18432
	ds_read_b128 v[192:195], v155 offset:19456


; #define PG8_STAGE(bufoff, gbase, voff) do { _Pragma("unroll") for (int _i = 0; _i < 2; ++_i) \
;         __builtin_amdgcn_global_load_lds((const unsigned*)((const char*)(gbase) + (voff)[_i]), (LAS unsigned*)(lds + (bufoff) + ldsw + _i * 8192), 16, 0, 0); } while (0)
; #define PG8_LDA(dst, b, h) do { _Pragma("unroll") for (int m = 0; m < 4; ++m) _Pragma("unroll") for (int k = 0; k < 2; ++k) dst[m][k] = *(const LAS bf16x8*)(lds + PG8_SA(b, h) + aoff + m * 2048 + k * 1024); } while (0)
; #define PG8_MMA(ai, bj, At, Bt) do { __builtin_amdgcn_s_setprio(1); _Pragma("unroll") for (int m = 0; m < 4; ++m) _Pragma("unroll") for (int n = 0; n < 2; ++n) _Pragma("unroll") for (int k = 0; k < 2; ++k) \
;         acc[ai][bj][m][n] = __builtin_amdgcn_mfma_f32_16x16x32_bf16(Bt[n][k], At[m][k], acc[ai][bj][m][n], 0, 0, 0); __builtin_amdgcn_s_setprio(0); } while (0)
; #define PG8_WAIT_V(n) asm volatile("s_waitcnt vmcnt(" #n ")" ::: "memory")
; #define PG8_WAIT_L(n) asm volatile("s_waitcnt lgkmcnt(" #n ")" ::: "memory")
; #define PG8_BAR __builtin_amdgcn_s_barrier()
; #define PG8_SCHED __builtin_amdgcn_sched_barrier(0)
; template <class Epi, bool ALIGN_EPI>
; __device__ __forceinline__ void gemm_phase(LAS unsigned char* lds, const Gemm g, const StaticOrder& S, const Epi& E, const int tid) {
;     ...
;             PG8_LDA(At, 0, 1); PG8_STAGE(PG8_SB(0, 0), b2, voffB); PG8_STAGE(PG8_SB(0, 1), b2 + hstepB, voffB); PG8_STAGE(PG8_SA(0, 0), a2, voffA);
;             PG8_WAIT_V(8); PG8_WAIT_L(0); PG8_BAR; PG8_MMA(1, 0, At, B0); PG8_MMA(1, 1, At, B1); PG8_BAR; PG8_SCHED;
	global_load_lds_dwordx4 v140, s[34:35]
	s_add_i32 m0, s87, 0x2000
	s_add_u32 s88, s34, 0x4000
	s_addc_u32 s89, s35, 0
	s_add_i32 s87, s90, s56
	global_load_lds_dwordx4 v136, s[34:35]
	s_mov_b32 m0, s87
	ds_read_b128 v[222:225], v155 offset:23552
	global_load_lds_dwordx4 v140, s[88:89]
	s_add_i32 m0, s87, 0x2000
	ds_read_b128 v[218:221], v155 offset:22528
	global_load_lds_dwordx4 v136, s[88:89]
	s_mov_b32 m0, s57
	ds_read_b128 v[214:217], v155 offset:21504
	global_load_lds_dwordx4 v142, s[42:43]
	s_mov_b32 m0, s60
	ds_read_b128 v[196:199], v155 offset:20480
	global_load_lds_dwordx4 v138, s[42:43]
	s_waitcnt vmcnt(8)
	s_waitcnt lgkmcnt(0)
	s_barrier


; #define PG8_MMA(ai, bj, At, Bt) do { __builtin_amdgcn_s_setprio(1); _Pragma("unroll") for (int m = 0; m < 4; ++m) _Pragma("unroll") for (int n = 0; n < 2; ++n) _Pragma("unroll") for (int k = 0; k < 2; ++k) \
;         acc[ai][bj][m][n] = __builtin_amdgcn_mfma_f32_16x16x32_bf16(Bt[n][k], At[m][k], acc[ai][bj][m][n], 0, 0, 0); __builtin_amdgcn_s_setprio(0); } while (0)
; #define PG8_WAIT_V(n) asm volatile("s_waitcnt vmcnt(" #n ")" ::: "memory")
; #define PG8_WAIT_L(n) asm volatile("s_waitcnt lgkmcnt(" #n ")" ::: "memory")
; #define PG8_BAR __builtin_amdgcn_s_barrier()
; #define PG8_SCHED __builtin_amdgcn_sched_barrier(0)
; template <class Epi, bool ALIGN_EPI>
; __device__ __forceinline__ void gemm_phase(LAS unsigned char* lds, const Gemm g, const StaticOrder& S, const Epi& E, const int tid) {
;     ...
;             PG8_WAIT_V(8); PG8_WAIT_L(0); PG8_BAR; PG8_MMA(1, 0, At, B0); PG8_MMA(1, 1, At, B1); PG8_BAR; PG8_SCHED;
	v_mfma_f32_16x16x32_bf16 v[24:27], v[132:135], v[180:183], v[24:27]
	v_mfma_f32_16x16x32_bf16 v[24:27], v[148:151], v[184:187], v[24:27]
	v_mfma_f32_16x16x32_bf16 v[20:23], v[156:159], v[180:183], v[20:23]
	v_mfma_f32_16x16x32_bf16 v[20:23], v[160:163], v[184:187], v[20:23]
	v_mfma_f32_16x16x32_bf16 v[64:67], v[132:135], v[188:191], v[64:67]
	v_mfma_f32_16x16x32_bf16 v[64:67], v[148:151], v[192:195], v[64:67]
	v_mfma_f32_16x16x32_bf16 v[72:75], v[156:159], v[188:191], v[72:75]
	v_mfma_f32_16x16x32_bf16 v[72:75], v[160:163], v[192:195], v[72:75]
	v_mfma_f32_16x16x32_bf16 v[16:19], v[132:135], v[196:199], v[16:19]
	v_mfma_f32_16x16x32_bf16 v[16:19], v[148:151], v[214:217], v[16:19]
	v_mfma_f32_16x16x32_bf16 v[12:15], v[156:159], v[196:199], v[12:15]
	v_mfma_f32_16x16x32_bf16 v[12:15], v[160:163], v[214:217], v[12:15]
	v_mfma_f32_16x16x32_bf16 v[60:63], v[132:135], v[218:221], v[60:63]
	v_mfma_f32_16x16x32_bf16 v[60:63], v[148:151], v[222:225], v[60:63]
	v_mfma_f32_16x16x32_bf16 v[68:71], v[156:159], v[218:221], v[68:71]
	v_mfma_f32_16x16x32_bf16 v[68:71], v[160:163], v[222:225], v[68:71]


; #define PG8_MMA(ai, bj, At, Bt) do { __builtin_amdgcn_s_setprio(1); _Pragma("unroll") for (int m = 0; m < 4; ++m) _Pragma("unroll") for (int n = 0; n < 2; ++n) _Pragma("unroll") for (int k = 0; k < 2; ++k) \
;         acc[ai][bj][m][n] = __builtin_amdgcn_mfma_f32_16x16x32_bf16(Bt[n][k], At[m][k], acc[ai][bj][m][n], 0, 0, 0); __builtin_amdgcn_s_setprio(0); } while (0)
; #define PG8_WAIT_V(n) asm volatile("s_waitcnt vmcnt(" #n ")" ::: "memory")
; #define PG8_WAIT_L(n) asm volatile("s_waitcnt lgkmcnt(" #n ")" ::: "memory")
; #define PG8_BAR __builtin_amdgcn_s_barrier()
; #define PG8_SCHED __builtin_amdgcn_sched_barrier(0)
; template <class Epi, bool ALIGN_EPI>
; __device__ __forceinline__ void gemm_phase(LAS unsigned char* lds, const Gemm g, const StaticOrder& S, const Epi& E, const int tid) {
;     ...
;             PG8_WAIT_V(8); PG8_WAIT_L(0); PG8_BAR; PG8_MMA(1, 0, At, B0); PG8_MMA(1, 1, At, B1); PG8_BAR; PG8_SCHED;
	v_mfma_f32_16x16x32_bf16 v[128:131], v[164:167], v[180:183], v[128:131]
	v_mfma_f32_16x16x32_bf16 v[128:131], v[168:171], v[184:187], v[128:131]
	v_mfma_f32_16x16x32_bf16 v[124:127], v[172:175], v[180:183], v[124:127]
	v_mfma_f32_16x16x32_bf16 v[124:127], v[176:179], v[184:187], v[124:127]
	v_mfma_f32_16x16x32_bf16 v[120:123], v[164:167], v[188:191], v[120:123]
	v_mfma_f32_16x16x32_bf16 v[120:123], v[168:171], v[192:195], v[120:123]
	v_mfma_f32_16x16x32_bf16 v[116:119], v[172:175], v[188:191], v[116:119]
	v_mfma_f32_16x16x32_bf16 v[116:119], v[176:179], v[192:195], v[116:119]
	v_mfma_f32_16x16x32_bf16 v[112:115], v[164:167], v[196:199], v[112:115]
	v_mfma_f32_16x16x32_bf16 v[112:115], v[168:171], v[214:217], v[112:115]
	v_mfma_f32_16x16x32_bf16 v[108:111], v[172:175], v[196:199], v[108:111]
	v_mfma_f32_16x16x32_bf16 v[108:111], v[176:179], v[214:217], v[108:111]
	v_mfma_f32_16x16x32_bf16 v[104:107], v[164:167], v[218:221], v[104:107]
	v_mfma_f32_16x16x32_bf16 v[104:107], v[168:171], v[222:225], v[104:107]
	v_mfma_f32_16x16x32_bf16 v[100:103], v[172:175], v[218:221], v[100:103]
	v_mfma_f32_16x16x32_bf16 v[100:103], v[176:179], v[222:225], v[100:103]

; #define PG8_STAGE(bufoff, gbase, voff) do { _Pragma("unroll") for (int _i = 0; _i < 2; ++_i) \
;         __builtin_amdgcn_global_load_lds((const unsigned*)((const char*)(gbase) + (voff)[_i]), (LAS unsigned*)(lds + (bufoff) + ldsw + _i * 8192), 16, 0, 0); } while (0)
; #define PG8_LDA(dst, b, h) do { _Pragma("unroll") for (int m = 0; m < 4; ++m) _Pragma("unroll") for (int k = 0; k < 2; ++k) dst[m][k] = *(const LAS bf16x8*)(lds + PG8_SA(b, h) + aoff + m * 2048 + k * 1024); } while (0)
; #define PG8_LDB(dst, b, h) do { _Pragma("unroll") for (int n = 0; n < 2; ++n) _Pragma("unroll") for (int k = 0; k < 2; ++k) dst[n][k] = *(const LAS bf16x8*)(lds + PG8_SB(b, h) + boff + n * 2048 + k * 1024); } while (0)
; #define PG8_MMA(ai, bj, At, Bt) do { __builtin_amdgcn_s_setprio(1); _Pragma("unroll") for (int m = 0; m < 4; ++m) _Pragma("unroll") for (int n = 0; n < 2; ++n) _Pragma("unroll") for (int k = 0; k < 2; ++k) \
;         acc[ai][bj][m][n] = __builtin_amdgcn_mfma_f32_16x16x32_bf16(Bt[n][k], At[m][k], acc[ai][bj][m][n], 0, 0, 0); __builtin_amdgcn_s_setprio(0); } while (0)
; #define PG8_WAIT_V(n) asm volatile("s_waitcnt vmcnt(" #n ")" ::: "memory")
; #define PG8_WAIT_L(n) asm volatile("s_waitcnt lgkmcnt(" #n ")" ::: "memory")
; #define PG8_BAR __builtin_amdgcn_s_barrier()
; #define PG8_SCHED __builtin_amdgcn_sched_barrier(0)
; template <class Epi, bool ALIGN_EPI>
; __device__ __forceinline__ void gemm_phase(LAS unsigned char* lds, const Gemm g, const StaticOrder& S, const Epi& E, const int tid) {
;     ...
;             PG8_WAIT_V(8); PG8_WAIT_L(0); PG8_BAR; PG8_MMA(1, 0, At, B0); PG8_MMA(1, 1, At, B1); PG8_BAR; PG8_SCHED;
;             PG8_LDB(B0, 1, 0); PG8_LDB(B1, 1, 1); PG8_SCHED; PG8_LDA(At, 1, 0); PG8_STAGE(PG8_SA(0, 1), a2 + hstepA, voffA);
	s_barrier
	s_add_i32 s87, 0, 0x18000
	v_add_u32_e32 v0, s87, v154
	s_add_i32 s88, 0, 0x1c000
	ds_read_b128 v[132:135], v0
	ds_read_b128 v[148:151], v0 offset:1024
	ds_read_b128 v[156:159], v0 offset:2048
	ds_read_b128 v[160:163], v0 offset:3072
	v_add_u32_e32 v0, s88, v154
	ds_read_b128 v[164:167], v0
	ds_read_b128 v[168:171], v0 offset:1024
	ds_read_b128 v[172:175], v0 offset:2048
	ds_read_b128 v[176:179], v0 offset:3072
	s_add_u32 s42, s42, 0x4000
	s_addc_u32 s43, s43, 0
	s_mov_b32 m0, s61
	ds_read_b128 v[180:183], v155 offset:32768
	ds_read_b128 v[184:187], v155 offset:33792
	ds_read_b128 v[188:191], v155 offset:34816
	ds_read_b128 v[192:195], v155 offset:35840
	ds_read_b128 v[196:199], v155 offset:36864
	ds_read_b128 v[214:217], v155 offset:37888
	ds_read_b128 v[218:221], v155 offset:38912

; #define PG8_STAGE(bufoff, gbase, voff) do { _Pragma("unroll") for (int _i = 0; _i < 2; ++_i) \
;         __builtin_amdgcn_global_load_lds((const unsigned*)((const char*)(gbase) + (voff)[_i]), (LAS unsigned*)(lds + (bufoff) + ldsw + _i * 8192), 16, 0, 0); } while (0)
; #define PG8_LDA(dst, b, h) do { _Pragma("unroll") for (int m = 0; m < 4; ++m) _Pragma("unroll") for (int k = 0; k < 2; ++k) dst[m][k] = *(const LAS bf16x8*)(lds + PG8_SA(b, h) + aoff + m * 2048 + k * 1024); } while (0)
; #define PG8_LDB(dst, b, h) do { _Pragma("unroll") for (int n = 0; n < 2; ++n) _Pragma("unroll") for (int k = 0; k < 2; ++k) dst[n][k] = *(const LAS bf16x8*)(lds + PG8_SB(b, h) + boff + n * 2048 + k * 1024); } while (0)
; #define PG8_MMA(ai, bj, At, Bt) do { __builtin_amdgcn_s_setprio(1); _Pragma("unroll") for (int m = 0; m < 4; ++m) _Pragma("unroll") for (int n = 0; n < 2; ++n) _Pragma("unroll") for (int k = 0; k < 2; ++k) \
;         acc[ai][bj][m][n] = __builtin_amdgcn_mfma_f32_16x16x32_bf16(Bt[n][k], At[m][k], acc[ai][bj][m][n], 0, 0, 0); __builtin_amdgcn_s_setprio(0); } while (0)
; #define PG8_WAIT_V(n) asm volatile("s_waitcnt vmcnt(" #n ")" ::: "memory")
; #define PG8_WAIT_L(n) asm volatile("s_waitcnt lgkmcnt(" #n ")" ::: "memory")
; #define PG8_BAR __builtin_amdgcn_s_barrier()
; #define PG8_SCHED __builtin_amdgcn_sched_barrier(0)
; template <class Epi, bool ALIGN_EPI>
; __device__ __forceinline__ void gemm_phase(LAS unsigned char* lds, const Gemm g, const StaticOrder& S, const Epi& E, const int tid) {
;     ...
;             PG8_LDB(B0, 1, 0); PG8_LDB(B1, 1, 1); PG8_SCHED; PG8_LDA(At, 1, 0); PG8_STAGE(PG8_SA(0, 1), a2 + hstepA, voffA);
;             PG8_WAIT_V(8); PG8_WAIT_L(0); PG8_BAR; PG8_MMA(0, 0, At, B0); PG8_MMA(0, 1, At, B1); PG8_BAR; PG8_SCHED;
	global_load_lds_dwordx4 v142, s[42:43]
	s_mov_b32 m0, s71
	ds_read_b128 v[222:225], v155 offset:39936
	global_load_lds_dwordx4 v138, s[42:43]
	s_waitcnt vmcnt(8)
	s_waitcnt lgkmcnt(0)
	s_barrier


; #define PG8_MMA(ai, bj, At, Bt) do { __builtin_amdgcn_s_setprio(1); _Pragma("unroll") for (int m = 0; m < 4; ++m) _Pragma("unroll") for (int n = 0; n < 2; ++n) _Pragma("unroll") for (int k = 0; k < 2; ++k) \
;         acc[ai][bj][m][n] = __builtin_amdgcn_mfma_f32_16x16x32_bf16(Bt[n][k], At[m][k], acc[ai][bj][m][n], 0, 0, 0); __builtin_amdgcn_s_setprio(0); } while (0)
; #define PG8_WAIT_V(n) asm volatile("s_waitcnt vmcnt(" #n ")" ::: "memory")
; #define PG8_WAIT_L(n) asm volatile("s_waitcnt lgkmcnt(" #n ")" ::: "memory")
; #define PG8_BAR __builtin_amdgcn_s_barrier()
; #define PG8_SCHED __builtin_amdgcn_sched_barrier(0)
; template <class Epi, bool ALIGN_EPI>
; __device__ __forceinline__ void gemm_phase(LAS unsigned char* lds, const Gemm g, const StaticOrder& S, const Epi& E, const int tid) {
;     ...
;             PG8_WAIT_V(8); PG8_WAIT_L(0); PG8_BAR; PG8_MMA(0, 0, At, B0); PG8_MMA(0, 1, At, B1); PG8_BAR; PG8_SCHED;
	v_mfma_f32_16x16x32_bf16 v[6:9], v[132:135], v[180:183], v[8:11]
	v_mfma_f32_16x16x32_bf16 v[8:11], v[148:151], v[184:187], v[6:9]
	v_mfma_f32_16x16x32_bf16 v[56:59], v[156:159], v[180:183], v[56:59]
	v_mfma_f32_16x16x32_bf16 v[56:59], v[160:163], v[184:187], v[56:59]
	v_mfma_f32_16x16x32_bf16 v[52:55], v[132:135], v[188:191], v[52:55]
	v_mfma_f32_16x16x32_bf16 v[52:55], v[148:151], v[192:195], v[52:55]
	v_mfma_f32_16x16x32_bf16 v[48:51], v[156:159], v[188:191], v[48:51]
	v_mfma_f32_16x16x32_bf16 v[48:51], v[160:163], v[192:195], v[48:51]
	v_mfma_f32_16x16x32_bf16 v[44:47], v[132:135], v[196:199], v[44:47]
	v_mfma_f32_16x16x32_bf16 v[44:47], v[148:151], v[214:217], v[44:47]
	v_mfma_f32_16x16x32_bf16 v[40:43], v[156:159], v[196:199], v[40:43]
	v_mfma_f32_16x16x32_bf16 v[40:43], v[160:163], v[214:217], v[40:43]
	v_mfma_f32_16x16x32_bf16 v[36:39], v[132:135], v[218:221], v[36:39]
	v_mfma_f32_16x16x32_bf16 v[36:39], v[148:151], v[222:225], v[36:39]
	v_mfma_f32_16x16x32_bf16 v[32:35], v[156:159], v[218:221], v[32:35]
	v_mfma_f32_16x16x32_bf16 v[32:35], v[160:163], v[222:225], v[32:35]


; #define PG8_MMA(ai, bj, At, Bt) do { __builtin_amdgcn_s_setprio(1); _Pragma("unroll") for (int m = 0; m < 4; ++m) _Pragma("unroll") for (int n = 0; n < 2; ++n) _Pragma("unroll") for (int k = 0; k < 2; ++k) \
;         acc[ai][bj][m][n] = __builtin_amdgcn_mfma_f32_16x16x32_bf16(Bt[n][k], At[m][k], acc[ai][bj][m][n], 0, 0, 0); __builtin_amdgcn_s_setprio(0); } while (0)
; #define PG8_WAIT_V(n) asm volatile("s_waitcnt vmcnt(" #n ")" ::: "memory")
; #define PG8_WAIT_L(n) asm volatile("s_waitcnt lgkmcnt(" #n ")" ::: "memory")
; #define PG8_BAR __builtin_amdgcn_s_barrier()
; #define PG8_SCHED __builtin_amdgcn_sched_barrier(0)
; template <class Epi, bool ALIGN_EPI>
; __device__ __forceinline__ void gemm_phase(LAS unsigned char* lds, const Gemm g, const StaticOrder& S, const Epi& E, const int tid) {
;     ...
;             PG8_WAIT_V(8); PG8_WAIT_L(0); PG8_BAR; PG8_MMA(0, 0, At, B0); PG8_MMA(0, 1, At, B1); PG8_BAR; PG8_SCHED;
	v_mfma_f32_16x16x32_bf16 v[2:5], v[164:167], v[180:183], v[2:5]
	v_mfma_f32_16x16x32_bf16 v[4:7], v[168:171], v[184:187], v[2:5]
	v_mfma_f32_16x16x32_bf16 v[28:31], v[172:175], v[180:183], v[28:31]
	v_mfma_f32_16x16x32_bf16 v[28:31], v[176:179], v[184:187], v[28:31]
	v_mfma_f32_16x16x32_bf16 v[96:99], v[164:167], v[188:191], v[96:99]
	v_mfma_f32_16x16x32_bf16 v[96:99], v[168:171], v[192:195], v[96:99]
	v_mfma_f32_16x16x32_bf16 v[92:95], v[172:175], v[188:191], v[92:95]
	v_mfma_f32_16x16x32_bf16 v[92:95], v[176:179], v[192:195], v[92:95]
	v_mfma_f32_16x16x32_bf16 v[88:91], v[164:167], v[196:199], v[88:91]
	v_mfma_f32_16x16x32_bf16 v[88:91], v[168:171], v[214:217], v[88:91]
	v_mfma_f32_16x16x32_bf16 v[84:87], v[172:175], v[196:199], v[84:87]
	v_mfma_f32_16x16x32_bf16 v[84:87], v[176:179], v[214:217], v[84:87]
	v_mfma_f32_16x16x32_bf16 v[80:83], v[164:167], v[218:221], v[80:83]
	v_mfma_f32_16x16x32_bf16 v[80:83], v[168:171], v[222:225], v[80:83]
	v_mfma_f32_16x16x32_bf16 v[76:79], v[172:175], v[218:221], v[76:79]
	v_mfma_f32_16x16x32_bf16 v[76:79], v[176:179], v[222:225], v[76:79]

; #define PG8_STAGE(bufoff, gbase, voff) do { _Pragma("unroll") for (int _i = 0; _i < 2; ++_i) \
;         __builtin_amdgcn_global_load_lds((const unsigned*)((const char*)(gbase) + (voff)[_i]), (LAS unsigned*)(lds + (bufoff) + ldsw + _i * 8192), 16, 0, 0); } while (0)
; #define PG8_LDA(dst, b, h) do { _Pragma("unroll") for (int m = 0; m < 4; ++m) _Pragma("unroll") for (int k = 0; k < 2; ++k) dst[m][k] = *(const LAS bf16x8*)(lds + PG8_SA(b, h) + aoff + m * 2048 + k * 1024); } while (0)
; #define PG8_MMA(ai, bj, At, Bt) do { __builtin_amdgcn_s_setprio(1); _Pragma("unroll") for (int m = 0; m < 4; ++m) _Pragma("unroll") for (int n = 0; n < 2; ++n) _Pragma("unroll") for (int k = 0; k < 2; ++k) \
;         acc[ai][bj][m][n] = __builtin_amdgcn_mfma_f32_16x16x32_bf16(Bt[n][k], At[m][k], acc[ai][bj][m][n], 0, 0, 0); __builtin_amdgcn_s_setprio(0); } while (0)
; #define PG8_WAIT_V(n) asm volatile("s_waitcnt vmcnt(" #n ")" ::: "memory")
; #define PG8_WAIT_L(n) asm volatile("s_waitcnt lgkmcnt(" #n ")" ::: "memory")
; #define PG8_BAR __builtin_amdgcn_s_barrier()
; #define PG8_SCHED __builtin_amdgcn_sched_barrier(0)
; template <class Epi, bool ALIGN_EPI>
; __device__ __forceinline__ void gemm_phase(LAS unsigned char* lds, const Gemm g, const StaticOrder& S, const Epi& E, const int tid) {
;     ...
;             PG8_WAIT_V(8); PG8_WAIT_L(0); PG8_BAR; PG8_MMA(0, 0, At, B0); PG8_MMA(0, 1, At, B1); PG8_BAR; PG8_SCHED;
;             PG8_LDA(At, 1, 1); PG8_STAGE(PG8_SB(1, 0), b3, voffB); PG8_STAGE(PG8_SB(1, 1), b3 + hstepB, voffB); PG8_STAGE(PG8_SA(1, 0), a3, voffA);
	s_barrier
	s_add_u32 s42, s34, 0x8000
	s_addc_u32 s43, s35, 0
	s_add_i32 s87, s87, s56
	s_mov_b32 m0, s87
	ds_read_b128 v[180:183], v155 offset:49152
	ds_read_b128 v[184:187], v155 offset:50176
	ds_read_b128 v[188:191], v155 offset:51200
	ds_read_b128 v[192:195], v155 offset:52224


; #define PG8_STAGE(bufoff, gbase, voff) do { _Pragma("unroll") for (int _i = 0; _i < 2; ++_i) \
;         __builtin_amdgcn_global_load_lds((const unsigned*)((const char*)(gbase) + (voff)[_i]), (LAS unsigned*)(lds + (bufoff) + ldsw + _i * 8192), 16, 0, 0); } while (0)
; #define PG8_LDA(dst, b, h) do { _Pragma("unroll") for (int m = 0; m < 4; ++m) _Pragma("unroll") for (int k = 0; k < 2; ++k) dst[m][k] = *(const LAS bf16x8*)(lds + PG8_SA(b, h) + aoff + m * 2048 + k * 1024); } while (0)
; #define PG8_MMA(ai, bj, At, Bt) do { __builtin_amdgcn_s_setprio(1); _Pragma("unroll") for (int m = 0; m < 4; ++m) _Pragma("unroll") for (int n = 0; n < 2; ++n) _Pragma("unroll") for (int k = 0; k < 2; ++k) \
;         acc[ai][bj][m][n] = __builtin_amdgcn_mfma_f32_16x16x32_bf16(Bt[n][k], At[m][k], acc[ai][bj][m][n], 0, 0, 0); __builtin_amdgcn_s_setprio(0); } while (0)
; #define PG8_WAIT_V(n) asm volatile("s_waitcnt vmcnt(" #n ")" ::: "memory")
; #define PG8_WAIT_L(n) asm volatile("s_waitcnt lgkmcnt(" #n ")" ::: "memory")
; #define PG8_BAR __builtin_amdgcn_s_barrier()
; #define PG8_SCHED __builtin_amdgcn_sched_barrier(0)
; template <class Epi, bool ALIGN_EPI>
; __device__ __forceinline__ void gemm_phase(LAS unsigned char* lds, const Gemm g, const StaticOrder& S, const Epi& E, const int tid) {
;     ...
;             PG8_LDA(At, 1, 1); PG8_STAGE(PG8_SB(1, 0), b3, voffB); PG8_STAGE(PG8_SB(1, 1), b3 + hstepB, voffB); PG8_STAGE(PG8_SA(1, 0), a3, voffA);
;             PG8_WAIT_V(8); PG8_WAIT_L(0); PG8_BAR; PG8_MMA(1, 0, At, B0); PG8_MMA(1, 1, At, B1); PG8_BAR; PG8_SCHED;
	global_load_lds_dwordx4 v140, s[42:43]
	s_add_i32 m0, s87, 0x2000
	s_add_u32 s34, s34, 0xc000
	s_addc_u32 s35, s35, 0
	global_load_lds_dwordx4 v136, s[42:43]
	s_add_i32 s42, s88, s56
	s_mov_b32 m0, s42
	ds_read_b128 v[222:225], v155 offset:56320
	global_load_lds_dwordx4 v140, s[34:35]
	s_add_i32 m0, s42, 0x2000
	ds_read_b128 v[218:221], v155 offset:55296
	global_load_lds_dwordx4 v136, s[34:35]
	s_mov_b32 m0, s76
	ds_read_b128 v[214:217], v155 offset:54272
	global_load_lds_dwordx4 v142, s[22:23]
	s_mov_b32 m0, s77
	ds_read_b128 v[196:199], v155 offset:53248
	global_load_lds_dwordx4 v138, s[22:23]
	s_waitcnt vmcnt(8)
	s_waitcnt lgkmcnt(0)
	s_barrier


; #define PG8_MMA(ai, bj, At, Bt) do { __builtin_amdgcn_s_setprio(1); _Pragma("unroll") for (int m = 0; m < 4; ++m) _Pragma("unroll") for (int n = 0; n < 2; ++n) _Pragma("unroll") for (int k = 0; k < 2; ++k) \
;         acc[ai][bj][m][n] = __builtin_amdgcn_mfma_f32_16x16x32_bf16(Bt[n][k], At[m][k], acc[ai][bj][m][n], 0, 0, 0); __builtin_amdgcn_s_setprio(0); } while (0)
; #define PG8_WAIT_V(n) asm volatile("s_waitcnt vmcnt(" #n ")" ::: "memory")
; #define PG8_WAIT_L(n) asm volatile("s_waitcnt lgkmcnt(" #n ")" ::: "memory")
; #define PG8_BAR __builtin_amdgcn_s_barrier()
; #define PG8_SCHED __builtin_amdgcn_sched_barrier(0)
; template <class Epi, bool ALIGN_EPI>
; __device__ __forceinline__ void gemm_phase(LAS unsigned char* lds, const Gemm g, const StaticOrder& S, const Epi& E, const int tid) {
;     ...
;             PG8_WAIT_V(8); PG8_WAIT_L(0); PG8_BAR; PG8_MMA(1, 0, At, B0); PG8_MMA(1, 1, At, B1); PG8_BAR; PG8_SCHED;
	v_mfma_f32_16x16x32_bf16 v[24:27], v[132:135], v[180:183], v[24:27]
	v_mfma_f32_16x16x32_bf16 v[24:27], v[148:151], v[184:187], v[24:27]
	v_mfma_f32_16x16x32_bf16 v[20:23], v[156:159], v[180:183], v[20:23]
	v_mfma_f32_16x16x32_bf16 v[20:23], v[160:163], v[184:187], v[20:23]
	v_mfma_f32_16x16x32_bf16 v[64:67], v[132:135], v[188:191], v[64:67]
	v_mfma_f32_16x16x32_bf16 v[64:67], v[148:151], v[192:195], v[64:67]
	v_mfma_f32_16x16x32_bf16 v[72:75], v[156:159], v[188:191], v[72:75]
	v_mfma_f32_16x16x32_bf16 v[72:75], v[160:163], v[192:195], v[72:75]
	v_mfma_f32_16x16x32_bf16 v[16:19], v[132:135], v[196:199], v[16:19]
	v_mfma_f32_16x16x32_bf16 v[16:19], v[148:151], v[214:217], v[16:19]
	v_mfma_f32_16x16x32_bf16 v[12:15], v[156:159], v[196:199], v[12:15]
	v_mfma_f32_16x16x32_bf16 v[12:15], v[160:163], v[214:217], v[12:15]
	v_mfma_f32_16x16x32_bf16 v[60:63], v[132:135], v[218:221], v[60:63]
	v_mfma_f32_16x16x32_bf16 v[60:63], v[148:151], v[222:225], v[60:63]
	v_mfma_f32_16x16x32_bf16 v[68:71], v[156:159], v[218:221], v[68:71]
	v_mfma_f32_16x16x32_bf16 v[68:71], v[160:163], v[222:225], v[68:71]


; #define PG8_MMA(ai, bj, At, Bt) do { __builtin_amdgcn_s_setprio(1); _Pragma("unroll") for (int m = 0; m < 4; ++m) _Pragma("unroll") for (int n = 0; n < 2; ++n) _Pragma("unroll") for (int k = 0; k < 2; ++k) \
;         acc[ai][bj][m][n] = __builtin_amdgcn_mfma_f32_16x16x32_bf16(Bt[n][k], At[m][k], acc[ai][bj][m][n], 0, 0, 0); __builtin_amdgcn_s_setprio(0); } while (0)
; #define PG8_WAIT_V(n) asm volatile("s_waitcnt vmcnt(" #n ")" ::: "memory")
; #define PG8_WAIT_L(n) asm volatile("s_waitcnt lgkmcnt(" #n ")" ::: "memory")
; #define PG8_BAR __builtin_amdgcn_s_barrier()
; #define PG8_SCHED __builtin_amdgcn_sched_barrier(0)
; template <class Epi, bool ALIGN_EPI>
; __device__ __forceinline__ void gemm_phase(LAS unsigned char* lds, const Gemm g, const StaticOrder& S, const Epi& E, const int tid) {
;     ...
;             PG8_WAIT_V(8); PG8_WAIT_L(0); PG8_BAR; PG8_MMA(1, 0, At, B0); PG8_MMA(1, 1, At, B1); PG8_BAR; PG8_SCHED;
	v_mfma_f32_16x16x32_bf16 v[128:131], v[164:167], v[180:183], v[128:131]
	v_mfma_f32_16x16x32_bf16 v[128:131], v[168:171], v[184:187], v[128:131]
	v_mfma_f32_16x16x32_bf16 v[124:127], v[172:175], v[180:183], v[124:127]
	v_mfma_f32_16x16x32_bf16 v[124:127], v[176:179], v[184:187], v[124:127]
	v_mfma_f32_16x16x32_bf16 v[120:123], v[164:167], v[188:191], v[120:123]
	v_mfma_f32_16x16x32_bf16 v[120:123], v[168:171], v[192:195], v[120:123]
	v_mfma_f32_16x16x32_bf16 v[116:119], v[172:175], v[188:191], v[116:119]
	v_mfma_f32_16x16x32_bf16 v[116:119], v[176:179], v[192:195], v[116:119]
	v_mfma_f32_16x16x32_bf16 v[112:115], v[164:167], v[196:199], v[112:115]
	v_mfma_f32_16x16x32_bf16 v[112:115], v[168:171], v[214:217], v[112:115]
	v_mfma_f32_16x16x32_bf16 v[108:111], v[172:175], v[196:199], v[108:111]
	v_mfma_f32_16x16x32_bf16 v[108:111], v[176:179], v[214:217], v[108:111]
	v_mfma_f32_16x16x32_bf16 v[104:107], v[164:167], v[218:221], v[104:107]
	v_mfma_f32_16x16x32_bf16 v[104:107], v[168:171], v[222:225], v[104:107]
	v_mfma_f32_16x16x32_bf16 v[100:103], v[172:175], v[218:221], v[100:103]
	v_mfma_f32_16x16x32_bf16 v[100:103], v[176:179], v[222:225], v[100:103]

; #define PG8_MMA(ai, bj, At, Bt) do { __builtin_amdgcn_s_setprio(1); _Pragma("unroll") for (int m = 0; m < 4; ++m) _Pragma("unroll") for (int n = 0; n < 2; ++n) _Pragma("unroll") for (int k = 0; k < 2; ++k) \
;         acc[ai][bj][m][n] = __builtin_amdgcn_mfma_f32_16x16x32_bf16(Bt[n][k], At[m][k], acc[ai][bj][m][n], 0, 0, 0); __builtin_amdgcn_s_setprio(0); } while (0)
; #define PG8_WAIT_V(n) asm volatile("s_waitcnt vmcnt(" #n ")" ::: "memory")
; #define PG8_WAIT_L(n) asm volatile("s_waitcnt lgkmcnt(" #n ")" ::: "memory")
; #define PG8_BAR __builtin_amdgcn_s_barrier()
; #define PG8_SCHED __builtin_amdgcn_sched_barrier(0)
; __device__ __forceinline__ u32x4 zero_frag() { unsigned z_ = 0u; asm volatile("" : "+v"(z_)); return (u32x4){z_, z_, z_, z_}; }
; __device__ __forceinline__ void epi_lane(int& fr, int& fq) { unsigned ones = ~0u; asm volatile("" : "+s"(ones)); const int ln = (int)__builtin_amdgcn_mbcnt_hi(ones, __builtin_amdgcn_mbcnt_lo(ones, 0u)); fr = ln & 15; fq = ln >> 4; }
; template <class Epi, bool ALIGN_EPI>
; __device__ __forceinline__ void gemm_phase(LAS unsigned char* lds, const Gemm g, const StaticOrder& S, const Epi& E, const int tid) {
;     ...
;             PG8_WAIT_V(8); PG8_WAIT_L(0); PG8_BAR; PG8_MMA(1, 0, At, B0); PG8_MMA(1, 1, At, B1); PG8_BAR; PG8_SCHED;
;         }
;         if constexpr (ALIGN_EPI) { if (wr == 0) PG8_BAR; }
;     __device__ __forceinline__ void operator()(f32x4 (&acc)[2][2][4][2], const Unit& u, int wr, int wc, LAS unsigned char* lds, int& rs_pm) const {
;         int fr, fq; epi_lane(fr, fq);
;         const int row0 = u.pm * BM + wr * 64 + fr, col0 = u.pn * BM + wc * 32 + 8 * fq; u32x4 zb = zero_frag();
; #pragma unroll
;         for (int ai = 0; ai < 2; ++ai)
; #pragma unroll
;             for (int m = 0; m < 4; ++m) { float ss = 0.f;
;                 bf16* const xrow = xb + (((size_t)(u.pm * 32 + u.pn * 4 + (wc >> 1)) * BM + (wr * 64 + fr + ai * HALF + m * 16)) * 64 + (wc & 1) * 32 + 8 * fq);
; #pragma unroll
;                 for (int bj = 0; bj < 2; ++bj) {
;                     const u32x4 xw = *(const u32x4*)(xrow + (size_t)bj * (2 * BM * 64));
	s_barrier
	s_add_i32 s86, s86, 2
	s_add_u32 s84, s84, 0x10000
	s_addc_u32 s85, s85, 0
	s_add_u32 s10, s10, 0x10000
	s_addc_u32 s11, s11, 0
	s_cmpk_gt_u32 s86, 0x55
	s_cbranch_scc0 .LBB0_294
	v_and_b32_e32 v222, 15, v238
	v_lshrrev_b32_e32 v156, 4, v238
	s_lshl_b32 s100, s82, 5
	s_lshl_b32 s101, s83, 2
	v_lshlrev_b32_e32 v222, 7, v222
	s_add_i32 s100, s100, s101
	s_or_b32 s100, s100, s78
	v_lshl_or_b32 v222, v156, 4, v222
	s_ashr_i32 s101, s100, 31
	s_lshl_b64 s[100:101], s[100:101], 15
	s_add_u32 s98, s72, s100
	s_addc_u32 s99, s73, s101
	s_add_u32 s98, s98, s30
	s_addc_u32 s99, s99, s31
	s_lshl_b32 s100, s75, 7
	s_add_u32 s98, s98, s100
	s_addc_u32 s99, s99, 0
	s_lshl_b32 s100, s82, 15
	s_lshl_b32 s101, s75, 7
	s_add_i32 s100, s100, s101
	s_lshl_b32 s101, s83, 4
	s_add_i32 s100, s100, s101
	s_lshl_b32 s101, s74, 2
	s_add_i32 s100, s100, s101
	s_add_u32 s22, s44, s100
	s_addc_u32 s23, s45, 0
	global_load_dwordx4 v[176:179], v222, s[98:99]
	s_add_u32 s100, s98, 0x10000
	s_addc_u32 s101, s99, 0
	global_load_dwordx4 v[180:183], v222, s[100:101]
	global_load_dwordx4 v[184:187], v222, s[98:99] offset:2048
	s_add_u32 s100, s98, 0x10000
	s_addc_u32 s101, s99, 0
	global_load_dwordx4 v[188:191], v222, s[100:101] offset:2048
	s_add_u32 s100, s98, 0x1000
	s_addc_u32 s101, s99, 0
	global_load_dwordx4 v[192:195], v222, s[100:101]
	s_add_u32 s100, s98, 0x11000
	s_addc_u32 s101, s99, 0
	global_load_dwordx4 v[196:199], v222, s[100:101]
	s_add_u32 s100, s98, 0x1000
	s_addc_u32 s101, s99, 0
	global_load_dwordx4 v[214:217], v222, s[100:101] offset:2048
	s_add_u32 s100, s98, 0x11000
	s_addc_u32 s101, s99, 0
	global_load_dwordx4 v[218:221], v222, s[100:101] offset:2048
	s_and_b64 vcc, exec, s[46:47]
	s_cbranch_vccz .LBB0_297
	s_barrier

; #define PG8_STAGE(bufoff, gbase, voff) do { _Pragma("unroll") for (int _i = 0; _i < 2; ++_i) \
;         __builtin_amdgcn_global_load_lds((const unsigned*)((const char*)(gbase) + (voff)[_i]), (LAS unsigned*)(lds + (bufoff) + ldsw + _i * 8192), 16, 0, 0); } while (0)
; #define PG8_LDA(dst, b, h) do { _Pragma("unroll") for (int m = 0; m < 4; ++m) _Pragma("unroll") for (int k = 0; k < 2; ++k) dst[m][k] = *(const LAS bf16x8*)(lds + PG8_SA(b, h) + aoff + m * 2048 + k * 1024); } while (0)
; #define PG8_LDB(dst, b, h) do { _Pragma("unroll") for (int n = 0; n < 2; ++n) _Pragma("unroll") for (int k = 0; k < 2; ++k) dst[n][k] = *(const LAS bf16x8*)(lds + PG8_SB(b, h) + boff + n * 2048 + k * 1024); } while (0)
; #define PG8_SCHED __builtin_amdgcn_sched_barrier(0)
; template <class Epi, bool ALIGN_EPI>
; __device__ __forceinline__ void gemm_phase(LAS unsigned char* lds, const Gemm g, const StaticOrder& S, const Epi& E, const int tid) {
;     ...
;             const bool last = (t == nt - 2);
;             const char* a1 = cA + (size_t)(t + 1) * kstepA;
;             const char* a2 = last ? nA : cA + (size_t)(t + 2) * kstepA; const char* b2 = last ? nB : cB + (size_t)(t + 2) * kstepB;
;             const char* a3 = a2 + kstepA; const char* b3 = b2 + kstepB;
;             PG8_LDB(B0, 0, 0); PG8_LDB(B1, 0, 1); PG8_SCHED; PG8_LDA(At, 0, 0); PG8_STAGE(PG8_SA(1, 1), a1 + hstepA, voffA);
.LBB0_385:
	s_add_u32 s50, s48, 0x4000
	s_addc_u32 s51, s49, 0
	s_cmp_eq_u32 s88, 28
	s_cselect_b32 s54, s84, s50
	s_cselect_b32 s55, s43, s51
	s_cselect_b32 s52, s85, s86
	s_cselect_b32 s53, s41, s87
	s_add_u32 s50, s54, 0x8000
	s_addc_u32 s51, s55, 0
	s_add_i32 s89, 0, 0x10000
	v_add_u32_e32 v0, s89, v167
	s_add_i32 s92, 0, 0x14000
	ds_read_b128 v[132:135], v0
	ds_read_b128 v[136:139], v0 offset:1024
	ds_read_b128 v[152:155], v0 offset:2048
	ds_read_b128 v[156:159], v0 offset:3072
	v_add_u32_e32 v0, s92, v167
	ds_read_b128 v[160:163], v0
	ds_read_b128 v[172:175], v0 offset:1024
	ds_read_b128 v[176:179], v0 offset:2048
	ds_read_b128 v[180:183], v0 offset:3072
	s_add_i32 m0, s71, 0xc000
	ds_read_b128 v[184:187], v171
	ds_read_b128 v[188:191], v171 offset:1024
	ds_read_b128 v[192:195], v171 offset:2048
	ds_read_b128 v[196:199], v171 offset:3072
	ds_read_b128 v[214:217], v171 offset:4096
	ds_read_b128 v[218:221], v171 offset:5120
	ds_read_b128 v[222:225], v171 offset:6144

; #define PG8_STAGE(bufoff, gbase, voff) do { _Pragma("unroll") for (int _i = 0; _i < 2; ++_i) \
;         __builtin_amdgcn_global_load_lds((const unsigned*)((const char*)(gbase) + (voff)[_i]), (LAS unsigned*)(lds + (bufoff) + ldsw + _i * 8192), 16, 0, 0); } while (0)
; #define PG8_LDA(dst, b, h) do { _Pragma("unroll") for (int m = 0; m < 4; ++m) _Pragma("unroll") for (int k = 0; k < 2; ++k) dst[m][k] = *(const LAS bf16x8*)(lds + PG8_SA(b, h) + aoff + m * 2048 + k * 1024); } while (0)
; #define PG8_LDB(dst, b, h) do { _Pragma("unroll") for (int n = 0; n < 2; ++n) _Pragma("unroll") for (int k = 0; k < 2; ++k) dst[n][k] = *(const LAS bf16x8*)(lds + PG8_SB(b, h) + boff + n * 2048 + k * 1024); } while (0)
; #define PG8_MMA(ai, bj, At, Bt) do { __builtin_amdgcn_s_setprio(1); _Pragma("unroll") for (int m = 0; m < 4; ++m) _Pragma("unroll") for (int n = 0; n < 2; ++n) _Pragma("unroll") for (int k = 0; k < 2; ++k) \
;         acc[ai][bj][m][n] = __builtin_amdgcn_mfma_f32_16x16x32_bf16(Bt[n][k], At[m][k], acc[ai][bj][m][n], 0, 0, 0); __builtin_amdgcn_s_setprio(0); } while (0)
; #define PG8_WAIT_V(n) asm volatile("s_waitcnt vmcnt(" #n ")" ::: "memory")
; #define PG8_WAIT_L(n) asm volatile("s_waitcnt lgkmcnt(" #n ")" ::: "memory")
; #define PG8_BAR __builtin_amdgcn_s_barrier()
; #define PG8_SCHED __builtin_amdgcn_sched_barrier(0)
; template <class Epi, bool ALIGN_EPI>
; __device__ __forceinline__ void gemm_phase(LAS unsigned char* lds, const Gemm g, const StaticOrder& S, const Epi& E, const int tid) {
;     ...
;             PG8_LDB(B0, 0, 0); PG8_LDB(B1, 0, 1); PG8_SCHED; PG8_LDA(At, 0, 0); PG8_STAGE(PG8_SA(1, 1), a1 + hstepA, voffA);
;             PG8_WAIT_V(8); PG8_WAIT_L(0); PG8_BAR; PG8_MMA(0, 0, At, B0); PG8_MMA(0, 1, At, B1); PG8_BAR; PG8_SCHED;
	global_load_lds_dwordx4 v148, s[48:49]
	s_add_i32 m0, s71, 0xe000
	ds_read_b128 v[226:229], v171 offset:7168
	global_load_lds_dwordx4 v150, s[48:49]
	s_waitcnt vmcnt(8)
	s_waitcnt lgkmcnt(0)
	s_barrier


; #define PG8_MMA(ai, bj, At, Bt) do { __builtin_amdgcn_s_setprio(1); _Pragma("unroll") for (int m = 0; m < 4; ++m) _Pragma("unroll") for (int n = 0; n < 2; ++n) _Pragma("unroll") for (int k = 0; k < 2; ++k) \
;         acc[ai][bj][m][n] = __builtin_amdgcn_mfma_f32_16x16x32_bf16(Bt[n][k], At[m][k], acc[ai][bj][m][n], 0, 0, 0); __builtin_amdgcn_s_setprio(0); } while (0)
; #define PG8_WAIT_V(n) asm volatile("s_waitcnt vmcnt(" #n ")" ::: "memory")
; #define PG8_WAIT_L(n) asm volatile("s_waitcnt lgkmcnt(" #n ")" ::: "memory")
; #define PG8_BAR __builtin_amdgcn_s_barrier()
; #define PG8_SCHED __builtin_amdgcn_sched_barrier(0)
; template <class Epi, bool ALIGN_EPI>
; __device__ __forceinline__ void gemm_phase(LAS unsigned char* lds, const Gemm g, const StaticOrder& S, const Epi& E, const int tid) {
;     ...
;             PG8_WAIT_V(8); PG8_WAIT_L(0); PG8_BAR; PG8_MMA(0, 0, At, B0); PG8_MMA(0, 1, At, B1); PG8_BAR; PG8_SCHED;
	v_mfma_f32_16x16x32_bf16 v[128:131], v[132:135], v[184:187], v[128:131]
	v_mfma_f32_16x16x32_bf16 v[128:131], v[136:139], v[188:191], v[128:131]
	v_mfma_f32_16x16x32_bf16 v[116:119], v[152:155], v[184:187], v[116:119]
	v_mfma_f32_16x16x32_bf16 v[116:119], v[156:159], v[188:191], v[116:119]
	v_mfma_f32_16x16x32_bf16 v[124:127], v[132:135], v[192:195], v[124:127]
	v_mfma_f32_16x16x32_bf16 v[124:127], v[136:139], v[196:199], v[124:127]
	v_mfma_f32_16x16x32_bf16 v[108:111], v[152:155], v[192:195], v[108:111]
	v_mfma_f32_16x16x32_bf16 v[108:111], v[156:159], v[196:199], v[108:111]
	v_mfma_f32_16x16x32_bf16 v[120:123], v[132:135], v[214:217], v[120:123]
	v_mfma_f32_16x16x32_bf16 v[120:123], v[136:139], v[218:221], v[120:123]
	v_mfma_f32_16x16x32_bf16 v[100:103], v[152:155], v[214:217], v[100:103]
	v_mfma_f32_16x16x32_bf16 v[100:103], v[156:159], v[218:221], v[100:103]
	v_mfma_f32_16x16x32_bf16 v[112:115], v[132:135], v[222:225], v[112:115]
	v_mfma_f32_16x16x32_bf16 v[112:115], v[136:139], v[226:229], v[112:115]
	v_mfma_f32_16x16x32_bf16 v[92:95], v[152:155], v[222:225], v[92:95]
	v_mfma_f32_16x16x32_bf16 v[92:95], v[156:159], v[226:229], v[92:95]


; #define PG8_MMA(ai, bj, At, Bt) do { __builtin_amdgcn_s_setprio(1); _Pragma("unroll") for (int m = 0; m < 4; ++m) _Pragma("unroll") for (int n = 0; n < 2; ++n) _Pragma("unroll") for (int k = 0; k < 2; ++k) \
;         acc[ai][bj][m][n] = __builtin_amdgcn_mfma_f32_16x16x32_bf16(Bt[n][k], At[m][k], acc[ai][bj][m][n], 0, 0, 0); __builtin_amdgcn_s_setprio(0); } while (0)
; #define PG8_WAIT_V(n) asm volatile("s_waitcnt vmcnt(" #n ")" ::: "memory")
; #define PG8_WAIT_L(n) asm volatile("s_waitcnt lgkmcnt(" #n ")" ::: "memory")
; #define PG8_BAR __builtin_amdgcn_s_barrier()
; #define PG8_SCHED __builtin_amdgcn_sched_barrier(0)
; template <class Epi, bool ALIGN_EPI>
; __device__ __forceinline__ void gemm_phase(LAS unsigned char* lds, const Gemm g, const StaticOrder& S, const Epi& E, const int tid) {
;     ...
;             PG8_WAIT_V(8); PG8_WAIT_L(0); PG8_BAR; PG8_MMA(0, 0, At, B0); PG8_MMA(0, 1, At, B1); PG8_BAR; PG8_SCHED;
	v_mfma_f32_16x16x32_bf16 v[104:107], v[160:163], v[184:187], v[104:107]
	v_mfma_f32_16x16x32_bf16 v[104:107], v[172:175], v[188:191], v[104:107]
	v_mfma_f32_16x16x32_bf16 v[80:83], v[176:179], v[184:187], v[80:83]
	v_mfma_f32_16x16x32_bf16 v[80:83], v[180:183], v[188:191], v[80:83]
	v_mfma_f32_16x16x32_bf16 v[96:99], v[160:163], v[192:195], v[96:99]
	v_mfma_f32_16x16x32_bf16 v[96:99], v[172:175], v[196:199], v[96:99]
	v_mfma_f32_16x16x32_bf16 v[68:71], v[176:179], v[192:195], v[68:71]
	v_mfma_f32_16x16x32_bf16 v[68:71], v[180:183], v[196:199], v[68:71]
	v_mfma_f32_16x16x32_bf16 v[88:91], v[160:163], v[214:217], v[88:91]
	v_mfma_f32_16x16x32_bf16 v[88:91], v[172:175], v[218:221], v[88:91]
	v_mfma_f32_16x16x32_bf16 v[60:63], v[176:179], v[214:217], v[60:63]
	v_mfma_f32_16x16x32_bf16 v[60:63], v[180:183], v[218:221], v[60:63]
	v_mfma_f32_16x16x32_bf16 v[76:79], v[160:163], v[222:225], v[76:79]
	v_mfma_f32_16x16x32_bf16 v[76:79], v[172:175], v[226:229], v[76:79]
	v_mfma_f32_16x16x32_bf16 v[48:51], v[176:179], v[222:225], v[48:51]
	v_mfma_f32_16x16x32_bf16 v[48:51], v[180:183], v[226:229], v[48:51]

; #define PG8_STAGE(bufoff, gbase, voff) do { _Pragma("unroll") for (int _i = 0; _i < 2; ++_i) \
;         __builtin_amdgcn_global_load_lds((const unsigned*)((const char*)(gbase) + (voff)[_i]), (LAS unsigned*)(lds + (bufoff) + ldsw + _i * 8192), 16, 0, 0); } while (0)
; #define PG8_LDA(dst, b, h) do { _Pragma("unroll") for (int m = 0; m < 4; ++m) _Pragma("unroll") for (int k = 0; k < 2; ++k) dst[m][k] = *(const LAS bf16x8*)(lds + PG8_SA(b, h) + aoff + m * 2048 + k * 1024); } while (0)
; #define PG8_MMA(ai, bj, At, Bt) do { __builtin_amdgcn_s_setprio(1); _Pragma("unroll") for (int m = 0; m < 4; ++m) _Pragma("unroll") for (int n = 0; n < 2; ++n) _Pragma("unroll") for (int k = 0; k < 2; ++k) \
;         acc[ai][bj][m][n] = __builtin_amdgcn_mfma_f32_16x16x32_bf16(Bt[n][k], At[m][k], acc[ai][bj][m][n], 0, 0, 0); __builtin_amdgcn_s_setprio(0); } while (0)
; #define PG8_WAIT_V(n) asm volatile("s_waitcnt vmcnt(" #n ")" ::: "memory")
; #define PG8_WAIT_L(n) asm volatile("s_waitcnt lgkmcnt(" #n ")" ::: "memory")
; #define PG8_BAR __builtin_amdgcn_s_barrier()
; #define PG8_SCHED __builtin_amdgcn_sched_barrier(0)
; template <class Epi, bool ALIGN_EPI>
; __device__ __forceinline__ void gemm_phase(LAS unsigned char* lds, const Gemm g, const StaticOrder& S, const Epi& E, const int tid) {
;     ...
;             PG8_WAIT_V(8); PG8_WAIT_L(0); PG8_BAR; PG8_MMA(0, 0, At, B0); PG8_MMA(0, 1, At, B1); PG8_BAR; PG8_SCHED;
;             PG8_LDA(At, 0, 1); PG8_STAGE(PG8_SB(0, 0), b2, voffB); PG8_STAGE(PG8_SB(0, 1), b2 + hstepB, voffB); PG8_STAGE(PG8_SA(0, 0), a2, voffA);
	s_barrier
	s_add_i32 s89, s89, s61
	s_mov_b32 m0, s89
	ds_read_b128 v[184:187], v171 offset:16384
	ds_read_b128 v[188:191], v171 offset:17408
	ds_read_b128 v[192:195], v171 offset:18432
	ds_read_b128 v[196:199], v171 offset:19456


; #define PG8_STAGE(bufoff, gbase, voff) do { _Pragma("unroll") for (int _i = 0; _i < 2; ++_i) \
;         __builtin_amdgcn_global_load_lds((const unsigned*)((const char*)(gbase) + (voff)[_i]), (LAS unsigned*)(lds + (bufoff) + ldsw + _i * 8192), 16, 0, 0); } while (0)
; #define PG8_LDA(dst, b, h) do { _Pragma("unroll") for (int m = 0; m < 4; ++m) _Pragma("unroll") for (int k = 0; k < 2; ++k) dst[m][k] = *(const LAS bf16x8*)(lds + PG8_SA(b, h) + aoff + m * 2048 + k * 1024); } while (0)
; #define PG8_MMA(ai, bj, At, Bt) do { __builtin_amdgcn_s_setprio(1); _Pragma("unroll") for (int m = 0; m < 4; ++m) _Pragma("unroll") for (int n = 0; n < 2; ++n) _Pragma("unroll") for (int k = 0; k < 2; ++k) \
;         acc[ai][bj][m][n] = __builtin_amdgcn_mfma_f32_16x16x32_bf16(Bt[n][k], At[m][k], acc[ai][bj][m][n], 0, 0, 0); __builtin_amdgcn_s_setprio(0); } while (0)
; #define PG8_WAIT_V(n) asm volatile("s_waitcnt vmcnt(" #n ")" ::: "memory")
; #define PG8_WAIT_L(n) asm volatile("s_waitcnt lgkmcnt(" #n ")" ::: "memory")
; #define PG8_BAR __builtin_amdgcn_s_barrier()
; #define PG8_SCHED __builtin_amdgcn_sched_barrier(0)
; template <class Epi, bool ALIGN_EPI>
; __device__ __forceinline__ void gemm_phase(LAS unsigned char* lds, const Gemm g, const StaticOrder& S, const Epi& E, const int tid) {
;     ...
;             PG8_LDA(At, 0, 1); PG8_STAGE(PG8_SB(0, 0), b2, voffB); PG8_STAGE(PG8_SB(0, 1), b2 + hstepB, voffB); PG8_STAGE(PG8_SA(0, 0), a2, voffA);
;             PG8_WAIT_V(8); PG8_WAIT_L(0); PG8_BAR; PG8_MMA(1, 0, At, B0); PG8_MMA(1, 1, At, B1); PG8_BAR; PG8_SCHED;
	global_load_lds_dwordx4 v144, s[52:53]
	s_add_i32 m0, s89, 0x2000
	s_add_u32 s90, s52, 0x4000
	s_addc_u32 s91, s53, 0
	s_add_i32 s89, s92, s61
	global_load_lds_dwordx4 v140, s[52:53]
	s_mov_b32 m0, s89
	ds_read_b128 v[226:229], v171 offset:23552
	global_load_lds_dwordx4 v144, s[90:91]
	s_add_i32 m0, s89, 0x2000
	ds_read_b128 v[222:225], v171 offset:22528
	global_load_lds_dwordx4 v140, s[90:91]
	s_mov_b32 m0, s71
	ds_read_b128 v[218:221], v171 offset:21504
	global_load_lds_dwordx4 v146, s[54:55]
	s_mov_b32 m0, s72
	ds_read_b128 v[214:217], v171 offset:20480
	global_load_lds_dwordx4 v142, s[54:55]
	s_waitcnt vmcnt(8)
	s_waitcnt lgkmcnt(0)
	s_barrier


; #define PG8_MMA(ai, bj, At, Bt) do { __builtin_amdgcn_s_setprio(1); _Pragma("unroll") for (int m = 0; m < 4; ++m) _Pragma("unroll") for (int n = 0; n < 2; ++n) _Pragma("unroll") for (int k = 0; k < 2; ++k) \
;         acc[ai][bj][m][n] = __builtin_amdgcn_mfma_f32_16x16x32_bf16(Bt[n][k], At[m][k], acc[ai][bj][m][n], 0, 0, 0); __builtin_amdgcn_s_setprio(0); } while (0)
; #define PG8_WAIT_V(n) asm volatile("s_waitcnt vmcnt(" #n ")" ::: "memory")
; #define PG8_WAIT_L(n) asm volatile("s_waitcnt lgkmcnt(" #n ")" ::: "memory")
; #define PG8_BAR __builtin_amdgcn_s_barrier()
; #define PG8_SCHED __builtin_amdgcn_sched_barrier(0)
; template <class Epi, bool ALIGN_EPI>
; __device__ __forceinline__ void gemm_phase(LAS unsigned char* lds, const Gemm g, const StaticOrder& S, const Epi& E, const int tid) {
;     ...
;             PG8_WAIT_V(8); PG8_WAIT_L(0); PG8_BAR; PG8_MMA(1, 0, At, B0); PG8_MMA(1, 1, At, B1); PG8_BAR; PG8_SCHED;
	v_mfma_f32_16x16x32_bf16 v[84:87], v[132:135], v[184:187], v[84:87]
	v_mfma_f32_16x16x32_bf16 v[84:87], v[136:139], v[188:191], v[84:87]
	v_mfma_f32_16x16x32_bf16 v[56:59], v[152:155], v[184:187], v[56:59]
	v_mfma_f32_16x16x32_bf16 v[56:59], v[156:159], v[188:191], v[56:59]
	v_mfma_f32_16x16x32_bf16 v[72:75], v[132:135], v[192:195], v[72:75]
	v_mfma_f32_16x16x32_bf16 v[72:75], v[136:139], v[196:199], v[72:75]
	v_mfma_f32_16x16x32_bf16 v[44:47], v[152:155], v[192:195], v[44:47]
	v_mfma_f32_16x16x32_bf16 v[44:47], v[156:159], v[196:199], v[44:47]
	v_mfma_f32_16x16x32_bf16 v[64:67], v[132:135], v[214:217], v[64:67]
	v_mfma_f32_16x16x32_bf16 v[64:67], v[136:139], v[218:221], v[64:67]
	v_mfma_f32_16x16x32_bf16 v[36:39], v[152:155], v[214:217], v[36:39]
	v_mfma_f32_16x16x32_bf16 v[36:39], v[156:159], v[218:221], v[36:39]
	v_mfma_f32_16x16x32_bf16 v[52:55], v[132:135], v[222:225], v[52:55]
	v_mfma_f32_16x16x32_bf16 v[52:55], v[136:139], v[226:229], v[52:55]
	v_mfma_f32_16x16x32_bf16 v[28:31], v[152:155], v[222:225], v[28:31]
	v_mfma_f32_16x16x32_bf16 v[28:31], v[156:159], v[226:229], v[28:31]


; #define PG8_MMA(ai, bj, At, Bt) do { __builtin_amdgcn_s_setprio(1); _Pragma("unroll") for (int m = 0; m < 4; ++m) _Pragma("unroll") for (int n = 0; n < 2; ++n) _Pragma("unroll") for (int k = 0; k < 2; ++k) \
;         acc[ai][bj][m][n] = __builtin_amdgcn_mfma_f32_16x16x32_bf16(Bt[n][k], At[m][k], acc[ai][bj][m][n], 0, 0, 0); __builtin_amdgcn_s_setprio(0); } while (0)
; #define PG8_WAIT_V(n) asm volatile("s_waitcnt vmcnt(" #n ")" ::: "memory")
; #define PG8_WAIT_L(n) asm volatile("s_waitcnt lgkmcnt(" #n ")" ::: "memory")
; #define PG8_BAR __builtin_amdgcn_s_barrier()
; #define PG8_SCHED __builtin_amdgcn_sched_barrier(0)
; template <class Epi, bool ALIGN_EPI>
; __device__ __forceinline__ void gemm_phase(LAS unsigned char* lds, const Gemm g, const StaticOrder& S, const Epi& E, const int tid) {
;     ...
;             PG8_WAIT_V(8); PG8_WAIT_L(0); PG8_BAR; PG8_MMA(1, 0, At, B0); PG8_MMA(1, 1, At, B1); PG8_BAR; PG8_SCHED;
	v_mfma_f32_16x16x32_bf16 v[40:43], v[160:163], v[184:187], v[40:43]
	v_mfma_f32_16x16x32_bf16 v[40:43], v[172:175], v[188:191], v[40:43]
	v_mfma_f32_16x16x32_bf16 v[20:23], v[176:179], v[184:187], v[20:23]
	v_mfma_f32_16x16x32_bf16 v[20:23], v[180:183], v[188:191], v[20:23]
	v_mfma_f32_16x16x32_bf16 v[32:35], v[160:163], v[192:195], v[32:35]
	v_mfma_f32_16x16x32_bf16 v[32:35], v[172:175], v[196:199], v[32:35]
	v_mfma_f32_16x16x32_bf16 v[12:15], v[176:179], v[192:195], v[12:15]
	v_mfma_f32_16x16x32_bf16 v[12:15], v[180:183], v[196:199], v[12:15]
	v_mfma_f32_16x16x32_bf16 v[24:27], v[160:163], v[214:217], v[24:27]
	v_mfma_f32_16x16x32_bf16 v[24:27], v[172:175], v[218:221], v[24:27]
	v_mfma_f32_16x16x32_bf16 v[8:11], v[176:179], v[214:217], v[8:11]
	v_mfma_f32_16x16x32_bf16 v[8:11], v[180:183], v[218:221], v[8:11]
	v_mfma_f32_16x16x32_bf16 v[16:19], v[160:163], v[222:225], v[16:19]
	v_mfma_f32_16x16x32_bf16 v[16:19], v[172:175], v[226:229], v[16:19]
	v_mfma_f32_16x16x32_bf16 v[2:5], v[176:179], v[222:225], v[4:7]
	v_mfma_f32_16x16x32_bf16 v[2:5], v[180:183], v[226:229], v[2:5]

; #define PG8_STAGE(bufoff, gbase, voff) do { _Pragma("unroll") for (int _i = 0; _i < 2; ++_i) \
;         __builtin_amdgcn_global_load_lds((const unsigned*)((const char*)(gbase) + (voff)[_i]), (LAS unsigned*)(lds + (bufoff) + ldsw + _i * 8192), 16, 0, 0); } while (0)
; #define PG8_LDA(dst, b, h) do { _Pragma("unroll") for (int m = 0; m < 4; ++m) _Pragma("unroll") for (int k = 0; k < 2; ++k) dst[m][k] = *(const LAS bf16x8*)(lds + PG8_SA(b, h) + aoff + m * 2048 + k * 1024); } while (0)
; #define PG8_LDB(dst, b, h) do { _Pragma("unroll") for (int n = 0; n < 2; ++n) _Pragma("unroll") for (int k = 0; k < 2; ++k) dst[n][k] = *(const LAS bf16x8*)(lds + PG8_SB(b, h) + boff + n * 2048 + k * 1024); } while (0)
; #define PG8_MMA(ai, bj, At, Bt) do { __builtin_amdgcn_s_setprio(1); _Pragma("unroll") for (int m = 0; m < 4; ++m) _Pragma("unroll") for (int n = 0; n < 2; ++n) _Pragma("unroll") for (int k = 0; k < 2; ++k) \
;         acc[ai][bj][m][n] = __builtin_amdgcn_mfma_f32_16x16x32_bf16(Bt[n][k], At[m][k], acc[ai][bj][m][n], 0, 0, 0); __builtin_amdgcn_s_setprio(0); } while (0)
; #define PG8_WAIT_V(n) asm volatile("s_waitcnt vmcnt(" #n ")" ::: "memory")
; #define PG8_WAIT_L(n) asm volatile("s_waitcnt lgkmcnt(" #n ")" ::: "memory")
; #define PG8_BAR __builtin_amdgcn_s_barrier()
; #define PG8_SCHED __builtin_amdgcn_sched_barrier(0)
; template <class Epi, bool ALIGN_EPI>
; __device__ __forceinline__ void gemm_phase(LAS unsigned char* lds, const Gemm g, const StaticOrder& S, const Epi& E, const int tid) {
;     ...
;             PG8_LDB(B0, 1, 0); PG8_LDB(B1, 1, 1); PG8_SCHED; PG8_LDA(At, 1, 0); PG8_STAGE(PG8_SA(0, 1), a2 + hstepA, voffA);
;             PG8_WAIT_V(8); PG8_WAIT_L(0); PG8_BAR; PG8_MMA(0, 0, At, B0); PG8_MMA(0, 1, At, B1); PG8_BAR; PG8_SCHED;
	s_barrier
	s_add_i32 s89, 0, 0x18000
	v_add_u32_e32 v0, s89, v167
	s_add_i32 s90, 0, 0x1c000
	ds_read_b128 v[132:135], v0
	ds_read_b128 v[136:139], v0 offset:1024
	ds_read_b128 v[152:155], v0 offset:2048
	ds_read_b128 v[156:159], v0 offset:3072
	v_add_u32_e32 v0, s90, v167
	ds_read_b128 v[160:163], v0
	ds_read_b128 v[172:175], v0 offset:1024
	ds_read_b128 v[176:179], v0 offset:2048
	ds_read_b128 v[180:183], v0 offset:3072
	s_add_u32 s54, s54, 0x4000
	s_addc_u32 s55, s55, 0
	s_mov_b32 m0, s73
	ds_read_b128 v[184:187], v171 offset:32768
	ds_read_b128 v[188:191], v171 offset:33792
	ds_read_b128 v[192:195], v171 offset:34816
	ds_read_b128 v[196:199], v171 offset:35840
	ds_read_b128 v[214:217], v171 offset:36864
	ds_read_b128 v[218:221], v171 offset:37888
	ds_read_b128 v[222:225], v171 offset:38912

; #define PG8_STAGE(bufoff, gbase, voff) do { _Pragma("unroll") for (int _i = 0; _i < 2; ++_i) \
;         __builtin_amdgcn_global_load_lds((const unsigned*)((const char*)(gbase) + (voff)[_i]), (LAS unsigned*)(lds + (bufoff) + ldsw + _i * 8192), 16, 0, 0); } while (0)
; #define PG8_LDA(dst, b, h) do { _Pragma("unroll") for (int m = 0; m < 4; ++m) _Pragma("unroll") for (int k = 0; k < 2; ++k) dst[m][k] = *(const LAS bf16x8*)(lds + PG8_SA(b, h) + aoff + m * 2048 + k * 1024); } while (0)
; #define PG8_LDB(dst, b, h) do { _Pragma("unroll") for (int n = 0; n < 2; ++n) _Pragma("unroll") for (int k = 0; k < 2; ++k) dst[n][k] = *(const LAS bf16x8*)(lds + PG8_SB(b, h) + boff + n * 2048 + k * 1024); } while (0)
; #define PG8_MMA(ai, bj, At, Bt) do { __builtin_amdgcn_s_setprio(1); _Pragma("unroll") for (int m = 0; m < 4; ++m) _Pragma("unroll") for (int n = 0; n < 2; ++n) _Pragma("unroll") for (int k = 0; k < 2; ++k) \
;         acc[ai][bj][m][n] = __builtin_amdgcn_mfma_f32_16x16x32_bf16(Bt[n][k], At[m][k], acc[ai][bj][m][n], 0, 0, 0); __builtin_amdgcn_s_setprio(0); } while (0)
; #define PG8_WAIT_V(n) asm volatile("s_waitcnt vmcnt(" #n ")" ::: "memory")
; #define PG8_WAIT_L(n) asm volatile("s_waitcnt lgkmcnt(" #n ")" ::: "memory")
; #define PG8_BAR __builtin_amdgcn_s_barrier()
; #define PG8_SCHED __builtin_amdgcn_sched_barrier(0)
; template <class Epi, bool ALIGN_EPI>
; __device__ __forceinline__ void gemm_phase(LAS unsigned char* lds, const Gemm g, const StaticOrder& S, const Epi& E, const int tid) {
;     ...
;             PG8_LDB(B0, 1, 0); PG8_LDB(B1, 1, 1); PG8_SCHED; PG8_LDA(At, 1, 0); PG8_STAGE(PG8_SA(0, 1), a2 + hstepA, voffA);
;             PG8_WAIT_V(8); PG8_WAIT_L(0); PG8_BAR; PG8_MMA(0, 0, At, B0); PG8_MMA(0, 1, At, B1); PG8_BAR; PG8_SCHED;
	global_load_lds_dwordx4 v146, s[54:55]
	s_mov_b32 m0, s74
	ds_read_b128 v[226:229], v171 offset:39936
	global_load_lds_dwordx4 v142, s[54:55]
	s_waitcnt vmcnt(8)
	s_waitcnt lgkmcnt(0)
	s_barrier


; #define PG8_MMA(ai, bj, At, Bt) do { __builtin_amdgcn_s_setprio(1); _Pragma("unroll") for (int m = 0; m < 4; ++m) _Pragma("unroll") for (int n = 0; n < 2; ++n) _Pragma("unroll") for (int k = 0; k < 2; ++k) \
;         acc[ai][bj][m][n] = __builtin_amdgcn_mfma_f32_16x16x32_bf16(Bt[n][k], At[m][k], acc[ai][bj][m][n], 0, 0, 0); __builtin_amdgcn_s_setprio(0); } while (0)
; #define PG8_WAIT_V(n) asm volatile("s_waitcnt vmcnt(" #n ")" ::: "memory")
; #define PG8_WAIT_L(n) asm volatile("s_waitcnt lgkmcnt(" #n ")" ::: "memory")
; #define PG8_BAR __builtin_amdgcn_s_barrier()
; #define PG8_SCHED __builtin_amdgcn_sched_barrier(0)
; template <class Epi, bool ALIGN_EPI>
; __device__ __forceinline__ void gemm_phase(LAS unsigned char* lds, const Gemm g, const StaticOrder& S, const Epi& E, const int tid) {
;     ...
;             PG8_WAIT_V(8); PG8_WAIT_L(0); PG8_BAR; PG8_MMA(0, 0, At, B0); PG8_MMA(0, 1, At, B1); PG8_BAR; PG8_SCHED;
	v_mfma_f32_16x16x32_bf16 v[128:131], v[132:135], v[184:187], v[128:131]
	v_mfma_f32_16x16x32_bf16 v[128:131], v[136:139], v[188:191], v[128:131]
	v_mfma_f32_16x16x32_bf16 v[116:119], v[152:155], v[184:187], v[116:119]
	v_mfma_f32_16x16x32_bf16 v[116:119], v[156:159], v[188:191], v[116:119]
	v_mfma_f32_16x16x32_bf16 v[124:127], v[132:135], v[192:195], v[124:127]
	v_mfma_f32_16x16x32_bf16 v[124:127], v[136:139], v[196:199], v[124:127]
	v_mfma_f32_16x16x32_bf16 v[108:111], v[152:155], v[192:195], v[108:111]
	v_mfma_f32_16x16x32_bf16 v[108:111], v[156:159], v[196:199], v[108:111]
	v_mfma_f32_16x16x32_bf16 v[120:123], v[132:135], v[214:217], v[120:123]
	v_mfma_f32_16x16x32_bf16 v[120:123], v[136:139], v[218:221], v[120:123]
	v_mfma_f32_16x16x32_bf16 v[100:103], v[152:155], v[214:217], v[100:103]
	v_mfma_f32_16x16x32_bf16 v[100:103], v[156:159], v[218:221], v[100:103]
	v_mfma_f32_16x16x32_bf16 v[112:115], v[132:135], v[222:225], v[112:115]
	v_mfma_f32_16x16x32_bf16 v[112:115], v[136:139], v[226:229], v[112:115]
	v_mfma_f32_16x16x32_bf16 v[92:95], v[152:155], v[222:225], v[92:95]
	v_mfma_f32_16x16x32_bf16 v[92:95], v[156:159], v[226:229], v[92:95]


; #define PG8_MMA(ai, bj, At, Bt) do { __builtin_amdgcn_s_setprio(1); _Pragma("unroll") for (int m = 0; m < 4; ++m) _Pragma("unroll") for (int n = 0; n < 2; ++n) _Pragma("unroll") for (int k = 0; k < 2; ++k) \
;         acc[ai][bj][m][n] = __builtin_amdgcn_mfma_f32_16x16x32_bf16(Bt[n][k], At[m][k], acc[ai][bj][m][n], 0, 0, 0); __builtin_amdgcn_s_setprio(0); } while (0)
; #define PG8_WAIT_V(n) asm volatile("s_waitcnt vmcnt(" #n ")" ::: "memory")
; #define PG8_WAIT_L(n) asm volatile("s_waitcnt lgkmcnt(" #n ")" ::: "memory")
; #define PG8_BAR __builtin_amdgcn_s_barrier()
; #define PG8_SCHED __builtin_amdgcn_sched_barrier(0)
; template <class Epi, bool ALIGN_EPI>
; __device__ __forceinline__ void gemm_phase(LAS unsigned char* lds, const Gemm g, const StaticOrder& S, const Epi& E, const int tid) {
;     ...
;             PG8_WAIT_V(8); PG8_WAIT_L(0); PG8_BAR; PG8_MMA(0, 0, At, B0); PG8_MMA(0, 1, At, B1); PG8_BAR; PG8_SCHED;
	v_mfma_f32_16x16x32_bf16 v[104:107], v[160:163], v[184:187], v[104:107]
	v_mfma_f32_16x16x32_bf16 v[104:107], v[172:175], v[188:191], v[104:107]
	v_mfma_f32_16x16x32_bf16 v[80:83], v[176:179], v[184:187], v[80:83]
	v_mfma_f32_16x16x32_bf16 v[80:83], v[180:183], v[188:191], v[80:83]
	v_mfma_f32_16x16x32_bf16 v[96:99], v[160:163], v[192:195], v[96:99]
	v_mfma_f32_16x16x32_bf16 v[96:99], v[172:175], v[196:199], v[96:99]
	v_mfma_f32_16x16x32_bf16 v[68:71], v[176:179], v[192:195], v[68:71]
	v_mfma_f32_16x16x32_bf16 v[68:71], v[180:183], v[196:199], v[68:71]
	v_mfma_f32_16x16x32_bf16 v[88:91], v[160:163], v[214:217], v[88:91]
	v_mfma_f32_16x16x32_bf16 v[88:91], v[172:175], v[218:221], v[88:91]
	v_mfma_f32_16x16x32_bf16 v[60:63], v[176:179], v[214:217], v[60:63]
	v_mfma_f32_16x16x32_bf16 v[60:63], v[180:183], v[218:221], v[60:63]
	v_mfma_f32_16x16x32_bf16 v[76:79], v[160:163], v[222:225], v[76:79]
	v_mfma_f32_16x16x32_bf16 v[76:79], v[172:175], v[226:229], v[76:79]
	v_mfma_f32_16x16x32_bf16 v[48:51], v[176:179], v[222:225], v[48:51]
	v_mfma_f32_16x16x32_bf16 v[48:51], v[180:183], v[226:229], v[48:51]

; #define PG8_STAGE(bufoff, gbase, voff) do { _Pragma("unroll") for (int _i = 0; _i < 2; ++_i) \
;         __builtin_amdgcn_global_load_lds((const unsigned*)((const char*)(gbase) + (voff)[_i]), (LAS unsigned*)(lds + (bufoff) + ldsw + _i * 8192), 16, 0, 0); } while (0)
; #define PG8_LDA(dst, b, h) do { _Pragma("unroll") for (int m = 0; m < 4; ++m) _Pragma("unroll") for (int k = 0; k < 2; ++k) dst[m][k] = *(const LAS bf16x8*)(lds + PG8_SA(b, h) + aoff + m * 2048 + k * 1024); } while (0)
; template <class Epi, bool ALIGN_EPI>
; __device__ __forceinline__ void gemm_phase(LAS unsigned char* lds, const Gemm g, const StaticOrder& S, const Epi& E, const int tid) {
;     ...
;             PG8_LDA(At, 1, 1); PG8_STAGE(PG8_SB(1, 0), b3, voffB); PG8_STAGE(PG8_SB(1, 1), b3 + hstepB, voffB); PG8_STAGE(PG8_SA(1, 0), a3, voffA);
	s_barrier
	s_add_u32 s54, s52, 0x8000
	s_addc_u32 s55, s53, 0
	s_add_i32 s89, s89, s61
	s_mov_b32 m0, s89
	ds_read_b128 v[184:187], v171 offset:49152
	ds_read_b128 v[188:191], v171 offset:50176
	ds_read_b128 v[192:195], v171 offset:51200
	ds_read_b128 v[196:199], v171 offset:52224


; #define PG8_STAGE(bufoff, gbase, voff) do { _Pragma("unroll") for (int _i = 0; _i < 2; ++_i) \
;         __builtin_amdgcn_global_load_lds((const unsigned*)((const char*)(gbase) + (voff)[_i]), (LAS unsigned*)(lds + (bufoff) + ldsw + _i * 8192), 16, 0, 0); } while (0)
; #define PG8_LDA(dst, b, h) do { _Pragma("unroll") for (int m = 0; m < 4; ++m) _Pragma("unroll") for (int k = 0; k < 2; ++k) dst[m][k] = *(const LAS bf16x8*)(lds + PG8_SA(b, h) + aoff + m * 2048 + k * 1024); } while (0)
; #define PG8_MMA(ai, bj, At, Bt) do { __builtin_amdgcn_s_setprio(1); _Pragma("unroll") for (int m = 0; m < 4; ++m) _Pragma("unroll") for (int n = 0; n < 2; ++n) _Pragma("unroll") for (int k = 0; k < 2; ++k) \
;         acc[ai][bj][m][n] = __builtin_amdgcn_mfma_f32_16x16x32_bf16(Bt[n][k], At[m][k], acc[ai][bj][m][n], 0, 0, 0); __builtin_amdgcn_s_setprio(0); } while (0)
; #define PG8_WAIT_V(n) asm volatile("s_waitcnt vmcnt(" #n ")" ::: "memory")
; #define PG8_WAIT_L(n) asm volatile("s_waitcnt lgkmcnt(" #n ")" ::: "memory")
; #define PG8_BAR __builtin_amdgcn_s_barrier()
; #define PG8_SCHED __builtin_amdgcn_sched_barrier(0)
; template <class Epi, bool ALIGN_EPI>
; __device__ __forceinline__ void gemm_phase(LAS unsigned char* lds, const Gemm g, const StaticOrder& S, const Epi& E, const int tid) {
;     ...
;             PG8_LDA(At, 1, 1); PG8_STAGE(PG8_SB(1, 0), b3, voffB); PG8_STAGE(PG8_SB(1, 1), b3 + hstepB, voffB); PG8_STAGE(PG8_SA(1, 0), a3, voffA);
;             PG8_WAIT_V(8); PG8_WAIT_L(0); PG8_BAR; PG8_MMA(1, 0, At, B0); PG8_MMA(1, 1, At, B1); PG8_BAR; PG8_SCHED;
	global_load_lds_dwordx4 v144, s[54:55]
	s_add_i32 m0, s89, 0x2000
	s_add_u32 s52, s52, 0xc000
	s_addc_u32 s53, s53, 0
	global_load_lds_dwordx4 v140, s[54:55]
	s_add_i32 s54, s90, s61
	s_mov_b32 m0, s54
	ds_read_b128 v[226:229], v171 offset:56320
	global_load_lds_dwordx4 v144, s[52:53]
	s_add_i32 m0, s54, 0x2000
	ds_read_b128 v[222:225], v171 offset:55296
	global_load_lds_dwordx4 v140, s[52:53]
	s_mov_b32 m0, s77
	ds_read_b128 v[218:221], v171 offset:54272
	global_load_lds_dwordx4 v146, s[50:51]
	s_mov_b32 m0, s78
	ds_read_b128 v[214:217], v171 offset:53248
	global_load_lds_dwordx4 v142, s[50:51]
	s_waitcnt vmcnt(8)
	s_waitcnt lgkmcnt(0)
	s_barrier


; #define PG8_MMA(ai, bj, At, Bt) do { __builtin_amdgcn_s_setprio(1); _Pragma("unroll") for (int m = 0; m < 4; ++m) _Pragma("unroll") for (int n = 0; n < 2; ++n) _Pragma("unroll") for (int k = 0; k < 2; ++k) \
;         acc[ai][bj][m][n] = __builtin_amdgcn_mfma_f32_16x16x32_bf16(Bt[n][k], At[m][k], acc[ai][bj][m][n], 0, 0, 0); __builtin_amdgcn_s_setprio(0); } while (0)
; #define PG8_WAIT_V(n) asm volatile("s_waitcnt vmcnt(" #n ")" ::: "memory")
; #define PG8_WAIT_L(n) asm volatile("s_waitcnt lgkmcnt(" #n ")" ::: "memory")
; #define PG8_BAR __builtin_amdgcn_s_barrier()
; #define PG8_SCHED __builtin_amdgcn_sched_barrier(0)
; template <class Epi, bool ALIGN_EPI>
; __device__ __forceinline__ void gemm_phase(LAS unsigned char* lds, const Gemm g, const StaticOrder& S, const Epi& E, const int tid) {
;     ...
;             PG8_WAIT_V(8); PG8_WAIT_L(0); PG8_BAR; PG8_MMA(1, 0, At, B0); PG8_MMA(1, 1, At, B1); PG8_BAR; PG8_SCHED;
	v_mfma_f32_16x16x32_bf16 v[84:87], v[132:135], v[184:187], v[84:87]
	v_mfma_f32_16x16x32_bf16 v[84:87], v[136:139], v[188:191], v[84:87]
	v_mfma_f32_16x16x32_bf16 v[56:59], v[152:155], v[184:187], v[56:59]
	v_mfma_f32_16x16x32_bf16 v[56:59], v[156:159], v[188:191], v[56:59]
	v_mfma_f32_16x16x32_bf16 v[72:75], v[132:135], v[192:195], v[72:75]
	v_mfma_f32_16x16x32_bf16 v[72:75], v[136:139], v[196:199], v[72:75]
	v_mfma_f32_16x16x32_bf16 v[44:47], v[152:155], v[192:195], v[44:47]
	v_mfma_f32_16x16x32_bf16 v[44:47], v[156:159], v[196:199], v[44:47]
	v_mfma_f32_16x16x32_bf16 v[64:67], v[132:135], v[214:217], v[64:67]
	v_mfma_f32_16x16x32_bf16 v[64:67], v[136:139], v[218:221], v[64:67]
	v_mfma_f32_16x16x32_bf16 v[36:39], v[152:155], v[214:217], v[36:39]
	v_mfma_f32_16x16x32_bf16 v[36:39], v[156:159], v[218:221], v[36:39]
	v_mfma_f32_16x16x32_bf16 v[52:55], v[132:135], v[222:225], v[52:55]
	v_mfma_f32_16x16x32_bf16 v[52:55], v[136:139], v[226:229], v[52:55]
	v_mfma_f32_16x16x32_bf16 v[28:31], v[152:155], v[222:225], v[28:31]
	v_mfma_f32_16x16x32_bf16 v[28:31], v[156:159], v[226:229], v[28:31]


; #define PG8_MMA(ai, bj, At, Bt) do { __builtin_amdgcn_s_setprio(1); _Pragma("unroll") for (int m = 0; m < 4; ++m) _Pragma("unroll") for (int n = 0; n < 2; ++n) _Pragma("unroll") for (int k = 0; k < 2; ++k) \
;         acc[ai][bj][m][n] = __builtin_amdgcn_mfma_f32_16x16x32_bf16(Bt[n][k], At[m][k], acc[ai][bj][m][n], 0, 0, 0); __builtin_amdgcn_s_setprio(0); } while (0)
; #define PG8_WAIT_V(n) asm volatile("s_waitcnt vmcnt(" #n ")" ::: "memory")
; #define PG8_WAIT_L(n) asm volatile("s_waitcnt lgkmcnt(" #n ")" ::: "memory")
; #define PG8_BAR __builtin_amdgcn_s_barrier()
; #define PG8_SCHED __builtin_amdgcn_sched_barrier(0)
; template <class Epi, bool ALIGN_EPI>
; __device__ __forceinline__ void gemm_phase(LAS unsigned char* lds, const Gemm g, const StaticOrder& S, const Epi& E, const int tid) {
;     ...
;             PG8_WAIT_V(8); PG8_WAIT_L(0); PG8_BAR; PG8_MMA(1, 0, At, B0); PG8_MMA(1, 1, At, B1); PG8_BAR; PG8_SCHED;
	v_mfma_f32_16x16x32_bf16 v[40:43], v[160:163], v[184:187], v[40:43]
	v_mfma_f32_16x16x32_bf16 v[40:43], v[172:175], v[188:191], v[40:43]
	v_mfma_f32_16x16x32_bf16 v[20:23], v[176:179], v[184:187], v[20:23]
	v_mfma_f32_16x16x32_bf16 v[20:23], v[180:183], v[188:191], v[20:23]
	v_mfma_f32_16x16x32_bf16 v[32:35], v[160:163], v[192:195], v[32:35]
	v_mfma_f32_16x16x32_bf16 v[32:35], v[172:175], v[196:199], v[32:35]
	v_mfma_f32_16x16x32_bf16 v[12:15], v[176:179], v[192:195], v[12:15]
	v_mfma_f32_16x16x32_bf16 v[12:15], v[180:183], v[196:199], v[12:15]
	v_mfma_f32_16x16x32_bf16 v[24:27], v[160:163], v[214:217], v[24:27]
	v_mfma_f32_16x16x32_bf16 v[24:27], v[172:175], v[218:221], v[24:27]
	v_mfma_f32_16x16x32_bf16 v[6:9], v[176:179], v[214:217], v[8:11]
	v_mfma_f32_16x16x32_bf16 v[8:11], v[180:183], v[218:221], v[6:9]
	v_mfma_f32_16x16x32_bf16 v[16:19], v[160:163], v[222:225], v[16:19]
	v_mfma_f32_16x16x32_bf16 v[16:19], v[172:175], v[226:229], v[16:19]
	v_mfma_f32_16x16x32_bf16 v[2:5], v[176:179], v[222:225], v[2:5]
	v_mfma_f32_16x16x32_bf16 v[4:7], v[180:183], v[226:229], v[2:5]

; #define PG8_MMA(ai, bj, At, Bt) do { __builtin_amdgcn_s_setprio(1); _Pragma("unroll") for (int m = 0; m < 4; ++m) _Pragma("unroll") for (int n = 0; n < 2; ++n) _Pragma("unroll") for (int k = 0; k < 2; ++k) \
;         acc[ai][bj][m][n] = __builtin_amdgcn_mfma_f32_16x16x32_bf16(Bt[n][k], At[m][k], acc[ai][bj][m][n], 0, 0, 0); __builtin_amdgcn_s_setprio(0); } while (0)
; #define PG8_WAIT_V(n) asm volatile("s_waitcnt vmcnt(" #n ")" ::: "memory")
; #define PG8_WAIT_L(n) asm volatile("s_waitcnt lgkmcnt(" #n ")" ::: "memory")
; #define PG8_BAR __builtin_amdgcn_s_barrier()
; #define PG8_SCHED __builtin_amdgcn_sched_barrier(0)
; template <class Epi, bool ALIGN_EPI>
; __device__ __forceinline__ void gemm_phase(LAS unsigned char* lds, const Gemm g, const StaticOrder& S, const Epi& E, const int tid) {
;     ...
;             PG8_WAIT_V(8); PG8_WAIT_L(0); PG8_BAR; PG8_MMA(1, 0, At, B0); PG8_MMA(1, 1, At, B1); PG8_BAR; PG8_SCHED;
;         }
;         if constexpr (ALIGN_EPI) { if (wr == 0) PG8_BAR; }
	s_barrier
	s_add_i32 s88, s88, 2
	s_add_u32 s48, s48, 0x10000
	s_addc_u32 s49, s49, 0
	s_add_u32 s86, s86, 0x10000
	s_addc_u32 s87, s87, 0
	s_cmp_gt_u32 s88, 29
	s_cbranch_scc0 .LBB0_385
	s_and_b64 vcc, exec, s[34:35]
	s_cbranch_vccz .LBB0_388
	s_barrier

; #define PG8_STAGE(bufoff, gbase, voff) do { _Pragma("unroll") for (int _i = 0; _i < 2; ++_i) \
;         __builtin_amdgcn_global_load_lds((const unsigned*)((const char*)(gbase) + (voff)[_i]), (LAS unsigned*)(lds + (bufoff) + ldsw + _i * 8192), 16, 0, 0); } while (0)
; #define PG8_LDA(dst, b, h) do { _Pragma("unroll") for (int m = 0; m < 4; ++m) _Pragma("unroll") for (int k = 0; k < 2; ++k) dst[m][k] = *(const LAS bf16x8*)(lds + PG8_SA(b, h) + aoff + m * 2048 + k * 1024); } while (0)
; #define PG8_LDB(dst, b, h) do { _Pragma("unroll") for (int n = 0; n < 2; ++n) _Pragma("unroll") for (int k = 0; k < 2; ++k) dst[n][k] = *(const LAS bf16x8*)(lds + PG8_SB(b, h) + boff + n * 2048 + k * 1024); } while (0)
; #define PG8_SCHED __builtin_amdgcn_sched_barrier(0)
; template <class Epi, bool ALIGN_EPI>
; __device__ __forceinline__ void gemm_phase(LAS unsigned char* lds, const Gemm g, const StaticOrder& S, const Epi& E, const int tid) {
;     ...
;         const char* nA = has_next ? (const char*)g.A + (size_t)nxt.pm * tstepA + (size_t)nxt.pn * g.acs : cA; const char* nB = has_next ? (const char*)g.Bt + (size_t)nxt.pn * tstepB : cB;
;         for (int t = 0; t < nt; t += 2) {
;             const bool last = (t == nt - 2);
;             const char* a1 = cA + (size_t)(t + 1) * kstepA;
;             const char* a2 = last ? nA : cA + (size_t)(t + 2) * kstepA; const char* b2 = last ? nB : cB + (size_t)(t + 2) * kstepB;
;             const char* a3 = a2 + kstepA; const char* b3 = b2 + kstepB;
;             PG8_LDB(B0, 0, 0); PG8_LDB(B1, 0, 1); PG8_SCHED; PG8_LDA(At, 0, 0); PG8_STAGE(PG8_SA(1, 1), a1 + hstepA, voffA);
.LBB0_847:
	s_add_u32 s22, s10, 0xfff80080
	s_addc_u32 s23, s11, -1
	s_add_i32 s87, 0, 0x10000
	s_cmp_eq_u32 s86, 28
	s_cselect_b32 s35, s49, s23
	s_cselect_b32 s34, s82, s22
	v_add_u32_e32 v0, s87, v154
	s_cselect_b32 s23, s47, s85
	s_cselect_b32 s22, s83, s84
	s_add_i32 s90, 0, 0x14000
	s_waitcnt lgkmcnt(0)
	ds_read_b128 v[132:135], v0
	ds_read_b128 v[148:151], v0 offset:1024
	ds_read_b128 v[156:159], v0 offset:2048
	ds_read_b128 v[160:163], v0 offset:3072
	v_add_u32_e32 v0, s90, v154
	ds_read_b128 v[164:167], v0
	ds_read_b128 v[168:171], v0 offset:1024
	ds_read_b128 v[172:175], v0 offset:2048
	ds_read_b128 v[176:179], v0 offset:3072
	s_add_i32 m0, s70, 0xc000
	ds_read_b128 v[180:183], v155
	ds_read_b128 v[184:187], v155 offset:1024
	ds_read_b128 v[188:191], v155 offset:2048
	ds_read_b128 v[192:195], v155 offset:3072
	ds_read_b128 v[196:199], v155 offset:4096
	ds_read_b128 v[214:217], v155 offset:5120
	ds_read_b128 v[218:221], v155 offset:6144

; #define PG8_STAGE(bufoff, gbase, voff) do { _Pragma("unroll") for (int _i = 0; _i < 2; ++_i) \
;         __builtin_amdgcn_global_load_lds((const unsigned*)((const char*)(gbase) + (voff)[_i]), (LAS unsigned*)(lds + (bufoff) + ldsw + _i * 8192), 16, 0, 0); } while (0)
; #define PG8_LDA(dst, b, h) do { _Pragma("unroll") for (int m = 0; m < 4; ++m) _Pragma("unroll") for (int k = 0; k < 2; ++k) dst[m][k] = *(const LAS bf16x8*)(lds + PG8_SA(b, h) + aoff + m * 2048 + k * 1024); } while (0)
; #define PG8_LDB(dst, b, h) do { _Pragma("unroll") for (int n = 0; n < 2; ++n) _Pragma("unroll") for (int k = 0; k < 2; ++k) dst[n][k] = *(const LAS bf16x8*)(lds + PG8_SB(b, h) + boff + n * 2048 + k * 1024); } while (0)
; #define PG8_MMA(ai, bj, At, Bt) do { __builtin_amdgcn_s_setprio(1); _Pragma("unroll") for (int m = 0; m < 4; ++m) _Pragma("unroll") for (int n = 0; n < 2; ++n) _Pragma("unroll") for (int k = 0; k < 2; ++k) \
;         acc[ai][bj][m][n] = __builtin_amdgcn_mfma_f32_16x16x32_bf16(Bt[n][k], At[m][k], acc[ai][bj][m][n], 0, 0, 0); __builtin_amdgcn_s_setprio(0); } while (0)
; #define PG8_WAIT_V(n) asm volatile("s_waitcnt vmcnt(" #n ")" ::: "memory")
; #define PG8_WAIT_L(n) asm volatile("s_waitcnt lgkmcnt(" #n ")" ::: "memory")
; #define PG8_BAR __builtin_amdgcn_s_barrier()
; #define PG8_SCHED __builtin_amdgcn_sched_barrier(0)
; template <class Epi, bool ALIGN_EPI>
; __device__ __forceinline__ void gemm_phase(LAS unsigned char* lds, const Gemm g, const StaticOrder& S, const Epi& E, const int tid) {
;     ...
;             PG8_LDB(B0, 0, 0); PG8_LDB(B1, 0, 1); PG8_SCHED; PG8_LDA(At, 0, 0); PG8_STAGE(PG8_SA(1, 1), a1 + hstepA, voffA);
;             PG8_WAIT_V(8); PG8_WAIT_L(0); PG8_BAR; PG8_MMA(0, 0, At, B0); PG8_MMA(0, 1, At, B1); PG8_BAR; PG8_SCHED;
	global_load_lds_dwordx4 v144, s[10:11]
	s_add_i32 m0, s70, 0xe000
	ds_read_b128 v[222:225], v155 offset:7168
	global_load_lds_dwordx4 v146, s[10:11]
	s_waitcnt vmcnt(8)
	s_waitcnt lgkmcnt(0)
	s_barrier


; #define PG8_MMA(ai, bj, At, Bt) do { __builtin_amdgcn_s_setprio(1); _Pragma("unroll") for (int m = 0; m < 4; ++m) _Pragma("unroll") for (int n = 0; n < 2; ++n) _Pragma("unroll") for (int k = 0; k < 2; ++k) \
;         acc[ai][bj][m][n] = __builtin_amdgcn_mfma_f32_16x16x32_bf16(Bt[n][k], At[m][k], acc[ai][bj][m][n], 0, 0, 0); __builtin_amdgcn_s_setprio(0); } while (0)
; #define PG8_WAIT_V(n) asm volatile("s_waitcnt vmcnt(" #n ")" ::: "memory")
; #define PG8_WAIT_L(n) asm volatile("s_waitcnt lgkmcnt(" #n ")" ::: "memory")
; #define PG8_BAR __builtin_amdgcn_s_barrier()
; #define PG8_SCHED __builtin_amdgcn_sched_barrier(0)
; template <class Epi, bool ALIGN_EPI>
; __device__ __forceinline__ void gemm_phase(LAS unsigned char* lds, const Gemm g, const StaticOrder& S, const Epi& E, const int tid) {
;     ...
;             PG8_WAIT_V(8); PG8_WAIT_L(0); PG8_BAR; PG8_MMA(0, 0, At, B0); PG8_MMA(0, 1, At, B1); PG8_BAR; PG8_SCHED;
	v_mfma_f32_16x16x32_bf16 v[8:11], v[132:135], v[180:183], v[8:11]
	v_mfma_f32_16x16x32_bf16 v[8:11], v[148:151], v[184:187], v[8:11]
	v_mfma_f32_16x16x32_bf16 v[56:59], v[156:159], v[180:183], v[56:59]
	v_mfma_f32_16x16x32_bf16 v[56:59], v[160:163], v[184:187], v[56:59]
	v_mfma_f32_16x16x32_bf16 v[52:55], v[132:135], v[188:191], v[52:55]
	v_mfma_f32_16x16x32_bf16 v[52:55], v[148:151], v[192:195], v[52:55]
	v_mfma_f32_16x16x32_bf16 v[48:51], v[156:159], v[188:191], v[48:51]
	v_mfma_f32_16x16x32_bf16 v[48:51], v[160:163], v[192:195], v[48:51]
	v_mfma_f32_16x16x32_bf16 v[44:47], v[132:135], v[196:199], v[44:47]
	v_mfma_f32_16x16x32_bf16 v[44:47], v[148:151], v[214:217], v[44:47]
	v_mfma_f32_16x16x32_bf16 v[40:43], v[156:159], v[196:199], v[40:43]
	v_mfma_f32_16x16x32_bf16 v[40:43], v[160:163], v[214:217], v[40:43]
	v_mfma_f32_16x16x32_bf16 v[36:39], v[132:135], v[218:221], v[36:39]
	v_mfma_f32_16x16x32_bf16 v[36:39], v[148:151], v[222:225], v[36:39]
	v_mfma_f32_16x16x32_bf16 v[32:35], v[156:159], v[218:221], v[32:35]
	v_mfma_f32_16x16x32_bf16 v[32:35], v[160:163], v[222:225], v[32:35]


; #define PG8_MMA(ai, bj, At, Bt) do { __builtin_amdgcn_s_setprio(1); _Pragma("unroll") for (int m = 0; m < 4; ++m) _Pragma("unroll") for (int n = 0; n < 2; ++n) _Pragma("unroll") for (int k = 0; k < 2; ++k) \
;         acc[ai][bj][m][n] = __builtin_amdgcn_mfma_f32_16x16x32_bf16(Bt[n][k], At[m][k], acc[ai][bj][m][n], 0, 0, 0); __builtin_amdgcn_s_setprio(0); } while (0)
; #define PG8_WAIT_V(n) asm volatile("s_waitcnt vmcnt(" #n ")" ::: "memory")
; #define PG8_WAIT_L(n) asm volatile("s_waitcnt lgkmcnt(" #n ")" ::: "memory")
; #define PG8_BAR __builtin_amdgcn_s_barrier()
; #define PG8_SCHED __builtin_amdgcn_sched_barrier(0)
; template <class Epi, bool ALIGN_EPI>
; __device__ __forceinline__ void gemm_phase(LAS unsigned char* lds, const Gemm g, const StaticOrder& S, const Epi& E, const int tid) {
;     ...
;             PG8_WAIT_V(8); PG8_WAIT_L(0); PG8_BAR; PG8_MMA(0, 0, At, B0); PG8_MMA(0, 1, At, B1); PG8_BAR; PG8_SCHED;
	v_mfma_f32_16x16x32_bf16 v[2:5], v[164:167], v[180:183], v[4:7]
	v_mfma_f32_16x16x32_bf16 v[2:5], v[168:171], v[184:187], v[2:5]
	v_mfma_f32_16x16x32_bf16 v[28:31], v[172:175], v[180:183], v[28:31]
	v_mfma_f32_16x16x32_bf16 v[28:31], v[176:179], v[184:187], v[28:31]
	v_mfma_f32_16x16x32_bf16 v[96:99], v[164:167], v[188:191], v[96:99]
	v_mfma_f32_16x16x32_bf16 v[96:99], v[168:171], v[192:195], v[96:99]
	v_mfma_f32_16x16x32_bf16 v[92:95], v[172:175], v[188:191], v[92:95]
	v_mfma_f32_16x16x32_bf16 v[92:95], v[176:179], v[192:195], v[92:95]
	v_mfma_f32_16x16x32_bf16 v[88:91], v[164:167], v[196:199], v[88:91]
	v_mfma_f32_16x16x32_bf16 v[88:91], v[168:171], v[214:217], v[88:91]
	v_mfma_f32_16x16x32_bf16 v[84:87], v[172:175], v[196:199], v[84:87]
	v_mfma_f32_16x16x32_bf16 v[84:87], v[176:179], v[214:217], v[84:87]
	v_mfma_f32_16x16x32_bf16 v[80:83], v[164:167], v[218:221], v[80:83]
	v_mfma_f32_16x16x32_bf16 v[80:83], v[168:171], v[222:225], v[80:83]
	v_mfma_f32_16x16x32_bf16 v[76:79], v[172:175], v[218:221], v[76:79]
	v_mfma_f32_16x16x32_bf16 v[76:79], v[176:179], v[222:225], v[76:79]

; #define PG8_STAGE(bufoff, gbase, voff) do { _Pragma("unroll") for (int _i = 0; _i < 2; ++_i) \
;         __builtin_amdgcn_global_load_lds((const unsigned*)((const char*)(gbase) + (voff)[_i]), (LAS unsigned*)(lds + (bufoff) + ldsw + _i * 8192), 16, 0, 0); } while (0)
; #define PG8_LDA(dst, b, h) do { _Pragma("unroll") for (int m = 0; m < 4; ++m) _Pragma("unroll") for (int k = 0; k < 2; ++k) dst[m][k] = *(const LAS bf16x8*)(lds + PG8_SA(b, h) + aoff + m * 2048 + k * 1024); } while (0)
; #define PG8_MMA(ai, bj, At, Bt) do { __builtin_amdgcn_s_setprio(1); _Pragma("unroll") for (int m = 0; m < 4; ++m) _Pragma("unroll") for (int n = 0; n < 2; ++n) _Pragma("unroll") for (int k = 0; k < 2; ++k) \
;         acc[ai][bj][m][n] = __builtin_amdgcn_mfma_f32_16x16x32_bf16(Bt[n][k], At[m][k], acc[ai][bj][m][n], 0, 0, 0); __builtin_amdgcn_s_setprio(0); } while (0)
; #define PG8_WAIT_V(n) asm volatile("s_waitcnt vmcnt(" #n ")" ::: "memory")
; #define PG8_WAIT_L(n) asm volatile("s_waitcnt lgkmcnt(" #n ")" ::: "memory")
; #define PG8_BAR __builtin_amdgcn_s_barrier()
; #define PG8_SCHED __builtin_amdgcn_sched_barrier(0)
; template <class Epi, bool ALIGN_EPI>
; __device__ __forceinline__ void gemm_phase(LAS unsigned char* lds, const Gemm g, const StaticOrder& S, const Epi& E, const int tid) {
;     ...
;             PG8_WAIT_V(8); PG8_WAIT_L(0); PG8_BAR; PG8_MMA(0, 0, At, B0); PG8_MMA(0, 1, At, B1); PG8_BAR; PG8_SCHED;
;             PG8_LDA(At, 0, 1); PG8_STAGE(PG8_SB(0, 0), b2, voffB); PG8_STAGE(PG8_SB(0, 1), b2 + hstepB, voffB); PG8_STAGE(PG8_SA(0, 0), a2, voffA);
	s_barrier
	s_add_i32 s87, s87, s61
	s_mov_b32 m0, s87
	ds_read_b128 v[180:183], v155 offset:16384
	ds_read_b128 v[184:187], v155 offset:17408
	ds_read_b128 v[188:191], v155 offset:18432
	ds_read_b128 v[192:195], v155 offset:19456
	ds_read_b128 v[196:199], v155 offset:20480
	ds_read_b128 v[214:217], v155 offset:21504


; #define PG8_STAGE(bufoff, gbase, voff) do { _Pragma("unroll") for (int _i = 0; _i < 2; ++_i) \
;         __builtin_amdgcn_global_load_lds((const unsigned*)((const char*)(gbase) + (voff)[_i]), (LAS unsigned*)(lds + (bufoff) + ldsw + _i * 8192), 16, 0, 0); } while (0)
; #define PG8_LDA(dst, b, h) do { _Pragma("unroll") for (int m = 0; m < 4; ++m) _Pragma("unroll") for (int k = 0; k < 2; ++k) dst[m][k] = *(const LAS bf16x8*)(lds + PG8_SA(b, h) + aoff + m * 2048 + k * 1024); } while (0)
; #define PG8_MMA(ai, bj, At, Bt) do { __builtin_amdgcn_s_setprio(1); _Pragma("unroll") for (int m = 0; m < 4; ++m) _Pragma("unroll") for (int n = 0; n < 2; ++n) _Pragma("unroll") for (int k = 0; k < 2; ++k) \
;         acc[ai][bj][m][n] = __builtin_amdgcn_mfma_f32_16x16x32_bf16(Bt[n][k], At[m][k], acc[ai][bj][m][n], 0, 0, 0); __builtin_amdgcn_s_setprio(0); } while (0)
; #define PG8_WAIT_V(n) asm volatile("s_waitcnt vmcnt(" #n ")" ::: "memory")
; #define PG8_WAIT_L(n) asm volatile("s_waitcnt lgkmcnt(" #n ")" ::: "memory")
; #define PG8_BAR __builtin_amdgcn_s_barrier()
; #define PG8_SCHED __builtin_amdgcn_sched_barrier(0)
; template <class Epi, bool ALIGN_EPI>
; __device__ __forceinline__ void gemm_phase(LAS unsigned char* lds, const Gemm g, const StaticOrder& S, const Epi& E, const int tid) {
;     ...
;             PG8_LDA(At, 0, 1); PG8_STAGE(PG8_SB(0, 0), b2, voffB); PG8_STAGE(PG8_SB(0, 1), b2 + hstepB, voffB); PG8_STAGE(PG8_SA(0, 0), a2, voffA);
;             PG8_WAIT_V(8); PG8_WAIT_L(0); PG8_BAR; PG8_MMA(1, 0, At, B0); PG8_MMA(1, 1, At, B1); PG8_BAR; PG8_SCHED;
	global_load_lds_dwordx4 v140, s[22:23]
	s_add_i32 m0, s87, 0x2000
	s_add_u32 s88, s22, 0x4000
	s_addc_u32 s89, s23, 0
	s_add_i32 s87, s90, s61
	global_load_lds_dwordx4 v136, s[22:23]
	s_mov_b32 m0, s87
	v_lshl_add_u64 v[152:153], s[34:35], 0, v[142:143]
	global_load_lds_dwordx4 v140, s[88:89]
	s_add_i32 m0, s87, 0x2000
	v_lshl_add_u64 v[200:201], s[34:35], 0, v[138:139]
	global_load_lds_dwordx4 v136, s[88:89]
	s_mov_b32 m0, s70
	ds_read_b128 v[222:225], v155 offset:23552
	global_load_lds_dwordx4 v[152:153], off
	s_mov_b32 m0, s71
	ds_read_b128 v[218:221], v155 offset:22528
	global_load_lds_dwordx4 v[200:201], off
	s_waitcnt vmcnt(8)
	s_waitcnt lgkmcnt(0)
	s_barrier


; #define PG8_MMA(ai, bj, At, Bt) do { __builtin_amdgcn_s_setprio(1); _Pragma("unroll") for (int m = 0; m < 4; ++m) _Pragma("unroll") for (int n = 0; n < 2; ++n) _Pragma("unroll") for (int k = 0; k < 2; ++k) \
;         acc[ai][bj][m][n] = __builtin_amdgcn_mfma_f32_16x16x32_bf16(Bt[n][k], At[m][k], acc[ai][bj][m][n], 0, 0, 0); __builtin_amdgcn_s_setprio(0); } while (0)
; #define PG8_WAIT_V(n) asm volatile("s_waitcnt vmcnt(" #n ")" ::: "memory")
; #define PG8_WAIT_L(n) asm volatile("s_waitcnt lgkmcnt(" #n ")" ::: "memory")
; #define PG8_BAR __builtin_amdgcn_s_barrier()
; #define PG8_SCHED __builtin_amdgcn_sched_barrier(0)
; template <class Epi, bool ALIGN_EPI>
; __device__ __forceinline__ void gemm_phase(LAS unsigned char* lds, const Gemm g, const StaticOrder& S, const Epi& E, const int tid) {
;     ...
;             PG8_WAIT_V(8); PG8_WAIT_L(0); PG8_BAR; PG8_MMA(1, 0, At, B0); PG8_MMA(1, 1, At, B1); PG8_BAR; PG8_SCHED;
	v_mfma_f32_16x16x32_bf16 v[24:27], v[132:135], v[180:183], v[24:27]
	v_mfma_f32_16x16x32_bf16 v[24:27], v[148:151], v[184:187], v[24:27]
	v_mfma_f32_16x16x32_bf16 v[20:23], v[156:159], v[180:183], v[20:23]
	v_mfma_f32_16x16x32_bf16 v[20:23], v[160:163], v[184:187], v[20:23]
	v_mfma_f32_16x16x32_bf16 v[64:67], v[132:135], v[188:191], v[64:67]
	v_mfma_f32_16x16x32_bf16 v[64:67], v[148:151], v[192:195], v[64:67]
	v_mfma_f32_16x16x32_bf16 v[72:75], v[156:159], v[188:191], v[72:75]
	v_mfma_f32_16x16x32_bf16 v[72:75], v[160:163], v[192:195], v[72:75]
	v_mfma_f32_16x16x32_bf16 v[16:19], v[132:135], v[196:199], v[16:19]
	v_mfma_f32_16x16x32_bf16 v[16:19], v[148:151], v[214:217], v[16:19]
	v_mfma_f32_16x16x32_bf16 v[12:15], v[156:159], v[196:199], v[12:15]
	v_mfma_f32_16x16x32_bf16 v[12:15], v[160:163], v[214:217], v[12:15]
	v_mfma_f32_16x16x32_bf16 v[60:63], v[132:135], v[218:221], v[60:63]
	v_mfma_f32_16x16x32_bf16 v[60:63], v[148:151], v[222:225], v[60:63]
	v_mfma_f32_16x16x32_bf16 v[68:71], v[156:159], v[218:221], v[68:71]
	v_mfma_f32_16x16x32_bf16 v[68:71], v[160:163], v[222:225], v[68:71]


; #define PG8_MMA(ai, bj, At, Bt) do { __builtin_amdgcn_s_setprio(1); _Pragma("unroll") for (int m = 0; m < 4; ++m) _Pragma("unroll") for (int n = 0; n < 2; ++n) _Pragma("unroll") for (int k = 0; k < 2; ++k) \
;         acc[ai][bj][m][n] = __builtin_amdgcn_mfma_f32_16x16x32_bf16(Bt[n][k], At[m][k], acc[ai][bj][m][n], 0, 0, 0); __builtin_amdgcn_s_setprio(0); } while (0)
; #define PG8_WAIT_V(n) asm volatile("s_waitcnt vmcnt(" #n ")" ::: "memory")
; #define PG8_WAIT_L(n) asm volatile("s_waitcnt lgkmcnt(" #n ")" ::: "memory")
; #define PG8_BAR __builtin_amdgcn_s_barrier()
; #define PG8_SCHED __builtin_amdgcn_sched_barrier(0)
; template <class Epi, bool ALIGN_EPI>
; __device__ __forceinline__ void gemm_phase(LAS unsigned char* lds, const Gemm g, const StaticOrder& S, const Epi& E, const int tid) {
;     ...
;             PG8_WAIT_V(8); PG8_WAIT_L(0); PG8_BAR; PG8_MMA(1, 0, At, B0); PG8_MMA(1, 1, At, B1); PG8_BAR; PG8_SCHED;
	v_mfma_f32_16x16x32_bf16 v[128:131], v[164:167], v[180:183], v[128:131]
	v_mfma_f32_16x16x32_bf16 v[128:131], v[168:171], v[184:187], v[128:131]
	v_mfma_f32_16x16x32_bf16 v[124:127], v[172:175], v[180:183], v[124:127]
	v_mfma_f32_16x16x32_bf16 v[124:127], v[176:179], v[184:187], v[124:127]
	v_mfma_f32_16x16x32_bf16 v[120:123], v[164:167], v[188:191], v[120:123]
	v_mfma_f32_16x16x32_bf16 v[120:123], v[168:171], v[192:195], v[120:123]
	v_mfma_f32_16x16x32_bf16 v[116:119], v[172:175], v[188:191], v[116:119]
	v_mfma_f32_16x16x32_bf16 v[116:119], v[176:179], v[192:195], v[116:119]
	v_mfma_f32_16x16x32_bf16 v[112:115], v[164:167], v[196:199], v[112:115]
	v_mfma_f32_16x16x32_bf16 v[112:115], v[168:171], v[214:217], v[112:115]
	v_mfma_f32_16x16x32_bf16 v[108:111], v[172:175], v[196:199], v[108:111]
	v_mfma_f32_16x16x32_bf16 v[108:111], v[176:179], v[214:217], v[108:111]
	v_mfma_f32_16x16x32_bf16 v[104:107], v[164:167], v[218:221], v[104:107]
	v_mfma_f32_16x16x32_bf16 v[104:107], v[168:171], v[222:225], v[104:107]
	v_mfma_f32_16x16x32_bf16 v[100:103], v[172:175], v[218:221], v[100:103]
	v_mfma_f32_16x16x32_bf16 v[100:103], v[176:179], v[222:225], v[100:103]

; #define PG8_STAGE(bufoff, gbase, voff) do { _Pragma("unroll") for (int _i = 0; _i < 2; ++_i) \
;         __builtin_amdgcn_global_load_lds((const unsigned*)((const char*)(gbase) + (voff)[_i]), (LAS unsigned*)(lds + (bufoff) + ldsw + _i * 8192), 16, 0, 0); } while (0)
; #define PG8_LDA(dst, b, h) do { _Pragma("unroll") for (int m = 0; m < 4; ++m) _Pragma("unroll") for (int k = 0; k < 2; ++k) dst[m][k] = *(const LAS bf16x8*)(lds + PG8_SA(b, h) + aoff + m * 2048 + k * 1024); } while (0)
; #define PG8_LDB(dst, b, h) do { _Pragma("unroll") for (int n = 0; n < 2; ++n) _Pragma("unroll") for (int k = 0; k < 2; ++k) dst[n][k] = *(const LAS bf16x8*)(lds + PG8_SB(b, h) + boff + n * 2048 + k * 1024); } while (0)
; #define PG8_MMA(ai, bj, At, Bt) do { __builtin_amdgcn_s_setprio(1); _Pragma("unroll") for (int m = 0; m < 4; ++m) _Pragma("unroll") for (int n = 0; n < 2; ++n) _Pragma("unroll") for (int k = 0; k < 2; ++k) \
;         acc[ai][bj][m][n] = __builtin_amdgcn_mfma_f32_16x16x32_bf16(Bt[n][k], At[m][k], acc[ai][bj][m][n], 0, 0, 0); __builtin_amdgcn_s_setprio(0); } while (0)
; #define PG8_WAIT_V(n) asm volatile("s_waitcnt vmcnt(" #n ")" ::: "memory")
; #define PG8_WAIT_L(n) asm volatile("s_waitcnt lgkmcnt(" #n ")" ::: "memory")
; #define PG8_BAR __builtin_amdgcn_s_barrier()
; #define PG8_SCHED __builtin_amdgcn_sched_barrier(0)
; template <class Epi, bool ALIGN_EPI>
; __device__ __forceinline__ void gemm_phase(LAS unsigned char* lds, const Gemm g, const StaticOrder& S, const Epi& E, const int tid) {
;     ...
;             PG8_LDB(B0, 1, 0); PG8_LDB(B1, 1, 1); PG8_SCHED; PG8_LDA(At, 1, 0); PG8_STAGE(PG8_SA(0, 1), a2 + hstepA, voffA);
;             PG8_WAIT_V(8); PG8_WAIT_L(0); PG8_BAR; PG8_MMA(0, 0, At, B0); PG8_MMA(0, 1, At, B1); PG8_BAR; PG8_SCHED;
	s_barrier
	s_add_i32 s87, 0, 0x18000
	v_add_u32_e32 v0, s87, v154
	s_add_i32 s88, 0, 0x1c000
	ds_read_b128 v[132:135], v0
	ds_read_b128 v[148:151], v0 offset:1024
	ds_read_b128 v[156:159], v0 offset:2048
	ds_read_b128 v[160:163], v0 offset:3072
	v_add_u32_e32 v0, s88, v154
	ds_read_b128 v[164:167], v0
	ds_read_b128 v[168:171], v0 offset:1024
	ds_read_b128 v[172:175], v0 offset:2048
	ds_read_b128 v[176:179], v0 offset:3072
	s_add_u32 s34, s34, 0x80000
	s_addc_u32 s35, s35, 0
	s_mov_b32 m0, s72
	ds_read_b128 v[180:183], v155 offset:32768
	ds_read_b128 v[184:187], v155 offset:33792
	ds_read_b128 v[188:191], v155 offset:34816
	ds_read_b128 v[192:195], v155 offset:35840
	ds_read_b128 v[196:199], v155 offset:36864
	ds_read_b128 v[214:217], v155 offset:37888
	ds_read_b128 v[218:221], v155 offset:38912

; #define PG8_STAGE(bufoff, gbase, voff) do { _Pragma("unroll") for (int _i = 0; _i < 2; ++_i) \
;         __builtin_amdgcn_global_load_lds((const unsigned*)((const char*)(gbase) + (voff)[_i]), (LAS unsigned*)(lds + (bufoff) + ldsw + _i * 8192), 16, 0, 0); } while (0)
; #define PG8_LDA(dst, b, h) do { _Pragma("unroll") for (int m = 0; m < 4; ++m) _Pragma("unroll") for (int k = 0; k < 2; ++k) dst[m][k] = *(const LAS bf16x8*)(lds + PG8_SA(b, h) + aoff + m * 2048 + k * 1024); } while (0)
; #define PG8_LDB(dst, b, h) do { _Pragma("unroll") for (int n = 0; n < 2; ++n) _Pragma("unroll") for (int k = 0; k < 2; ++k) dst[n][k] = *(const LAS bf16x8*)(lds + PG8_SB(b, h) + boff + n * 2048 + k * 1024); } while (0)
; #define PG8_MMA(ai, bj, At, Bt) do { __builtin_amdgcn_s_setprio(1); _Pragma("unroll") for (int m = 0; m < 4; ++m) _Pragma("unroll") for (int n = 0; n < 2; ++n) _Pragma("unroll") for (int k = 0; k < 2; ++k) \
;         acc[ai][bj][m][n] = __builtin_amdgcn_mfma_f32_16x16x32_bf16(Bt[n][k], At[m][k], acc[ai][bj][m][n], 0, 0, 0); __builtin_amdgcn_s_setprio(0); } while (0)
; #define PG8_WAIT_V(n) asm volatile("s_waitcnt vmcnt(" #n ")" ::: "memory")
; #define PG8_WAIT_L(n) asm volatile("s_waitcnt lgkmcnt(" #n ")" ::: "memory")
; #define PG8_BAR __builtin_amdgcn_s_barrier()
; #define PG8_SCHED __builtin_amdgcn_sched_barrier(0)
; template <class Epi, bool ALIGN_EPI>
; __device__ __forceinline__ void gemm_phase(LAS unsigned char* lds, const Gemm g, const StaticOrder& S, const Epi& E, const int tid) {
;     ...
;             PG8_LDB(B0, 1, 0); PG8_LDB(B1, 1, 1); PG8_SCHED; PG8_LDA(At, 1, 0); PG8_STAGE(PG8_SA(0, 1), a2 + hstepA, voffA);
;             PG8_WAIT_V(8); PG8_WAIT_L(0); PG8_BAR; PG8_MMA(0, 0, At, B0); PG8_MMA(0, 1, At, B1); PG8_BAR; PG8_SCHED;
	global_load_lds_dwordx4 v142, s[34:35]
	s_mov_b32 m0, s73
	ds_read_b128 v[222:225], v155 offset:39936
	global_load_lds_dwordx4 v138, s[34:35]
	s_waitcnt vmcnt(8)
	s_waitcnt lgkmcnt(0)
	s_barrier


; #define PG8_MMA(ai, bj, At, Bt) do { __builtin_amdgcn_s_setprio(1); _Pragma("unroll") for (int m = 0; m < 4; ++m) _Pragma("unroll") for (int n = 0; n < 2; ++n) _Pragma("unroll") for (int k = 0; k < 2; ++k) \
;         acc[ai][bj][m][n] = __builtin_amdgcn_mfma_f32_16x16x32_bf16(Bt[n][k], At[m][k], acc[ai][bj][m][n], 0, 0, 0); __builtin_amdgcn_s_setprio(0); } while (0)
; #define PG8_WAIT_V(n) asm volatile("s_waitcnt vmcnt(" #n ")" ::: "memory")
; #define PG8_WAIT_L(n) asm volatile("s_waitcnt lgkmcnt(" #n ")" ::: "memory")
; #define PG8_BAR __builtin_amdgcn_s_barrier()
; #define PG8_SCHED __builtin_amdgcn_sched_barrier(0)
; template <class Epi, bool ALIGN_EPI>
; __device__ __forceinline__ void gemm_phase(LAS unsigned char* lds, const Gemm g, const StaticOrder& S, const Epi& E, const int tid) {
;     ...
;             PG8_WAIT_V(8); PG8_WAIT_L(0); PG8_BAR; PG8_MMA(0, 0, At, B0); PG8_MMA(0, 1, At, B1); PG8_BAR; PG8_SCHED;
	v_mfma_f32_16x16x32_bf16 v[6:9], v[132:135], v[180:183], v[8:11]
	v_mfma_f32_16x16x32_bf16 v[8:11], v[148:151], v[184:187], v[6:9]
	v_mfma_f32_16x16x32_bf16 v[56:59], v[156:159], v[180:183], v[56:59]
	v_mfma_f32_16x16x32_bf16 v[56:59], v[160:163], v[184:187], v[56:59]
	v_mfma_f32_16x16x32_bf16 v[52:55], v[132:135], v[188:191], v[52:55]
	v_mfma_f32_16x16x32_bf16 v[52:55], v[148:151], v[192:195], v[52:55]
	v_mfma_f32_16x16x32_bf16 v[48:51], v[156:159], v[188:191], v[48:51]
	v_mfma_f32_16x16x32_bf16 v[48:51], v[160:163], v[192:195], v[48:51]
	v_mfma_f32_16x16x32_bf16 v[44:47], v[132:135], v[196:199], v[44:47]
	v_mfma_f32_16x16x32_bf16 v[44:47], v[148:151], v[214:217], v[44:47]
	v_mfma_f32_16x16x32_bf16 v[40:43], v[156:159], v[196:199], v[40:43]
	v_mfma_f32_16x16x32_bf16 v[40:43], v[160:163], v[214:217], v[40:43]
	v_mfma_f32_16x16x32_bf16 v[36:39], v[132:135], v[218:221], v[36:39]
	v_mfma_f32_16x16x32_bf16 v[36:39], v[148:151], v[222:225], v[36:39]
	v_mfma_f32_16x16x32_bf16 v[32:35], v[156:159], v[218:221], v[32:35]
	v_mfma_f32_16x16x32_bf16 v[32:35], v[160:163], v[222:225], v[32:35]


; #define PG8_MMA(ai, bj, At, Bt) do { __builtin_amdgcn_s_setprio(1); _Pragma("unroll") for (int m = 0; m < 4; ++m) _Pragma("unroll") for (int n = 0; n < 2; ++n) _Pragma("unroll") for (int k = 0; k < 2; ++k) \
;         acc[ai][bj][m][n] = __builtin_amdgcn_mfma_f32_16x16x32_bf16(Bt[n][k], At[m][k], acc[ai][bj][m][n], 0, 0, 0); __builtin_amdgcn_s_setprio(0); } while (0)
; #define PG8_WAIT_V(n) asm volatile("s_waitcnt vmcnt(" #n ")" ::: "memory")
; #define PG8_WAIT_L(n) asm volatile("s_waitcnt lgkmcnt(" #n ")" ::: "memory")
; #define PG8_BAR __builtin_amdgcn_s_barrier()
; #define PG8_SCHED __builtin_amdgcn_sched_barrier(0)
; template <class Epi, bool ALIGN_EPI>
; __device__ __forceinline__ void gemm_phase(LAS unsigned char* lds, const Gemm g, const StaticOrder& S, const Epi& E, const int tid) {
;     ...
;             PG8_WAIT_V(8); PG8_WAIT_L(0); PG8_BAR; PG8_MMA(0, 0, At, B0); PG8_MMA(0, 1, At, B1); PG8_BAR; PG8_SCHED;
	v_mfma_f32_16x16x32_bf16 v[2:5], v[164:167], v[180:183], v[2:5]
	v_mfma_f32_16x16x32_bf16 v[4:7], v[168:171], v[184:187], v[2:5]
	v_mfma_f32_16x16x32_bf16 v[28:31], v[172:175], v[180:183], v[28:31]
	v_mfma_f32_16x16x32_bf16 v[28:31], v[176:179], v[184:187], v[28:31]
	v_mfma_f32_16x16x32_bf16 v[96:99], v[164:167], v[188:191], v[96:99]
	v_mfma_f32_16x16x32_bf16 v[96:99], v[168:171], v[192:195], v[96:99]
	v_mfma_f32_16x16x32_bf16 v[92:95], v[172:175], v[188:191], v[92:95]
	v_mfma_f32_16x16x32_bf16 v[92:95], v[176:179], v[192:195], v[92:95]
	v_mfma_f32_16x16x32_bf16 v[88:91], v[164:167], v[196:199], v[88:91]
	v_mfma_f32_16x16x32_bf16 v[88:91], v[168:171], v[214:217], v[88:91]
	v_mfma_f32_16x16x32_bf16 v[84:87], v[172:175], v[196:199], v[84:87]
	v_mfma_f32_16x16x32_bf16 v[84:87], v[176:179], v[214:217], v[84:87]
	v_mfma_f32_16x16x32_bf16 v[80:83], v[164:167], v[218:221], v[80:83]
	v_mfma_f32_16x16x32_bf16 v[80:83], v[168:171], v[222:225], v[80:83]
	v_mfma_f32_16x16x32_bf16 v[76:79], v[172:175], v[218:221], v[76:79]
	v_mfma_f32_16x16x32_bf16 v[76:79], v[176:179], v[222:225], v[76:79]

; #define PG8_STAGE(bufoff, gbase, voff) do { _Pragma("unroll") for (int _i = 0; _i < 2; ++_i) \
;         __builtin_amdgcn_global_load_lds((const unsigned*)((const char*)(gbase) + (voff)[_i]), (LAS unsigned*)(lds + (bufoff) + ldsw + _i * 8192), 16, 0, 0); } while (0)
; #define PG8_LDA(dst, b, h) do { _Pragma("unroll") for (int m = 0; m < 4; ++m) _Pragma("unroll") for (int k = 0; k < 2; ++k) dst[m][k] = *(const LAS bf16x8*)(lds + PG8_SA(b, h) + aoff + m * 2048 + k * 1024); } while (0)
; template <class Epi, bool ALIGN_EPI>
; __device__ __forceinline__ void gemm_phase(LAS unsigned char* lds, const Gemm g, const StaticOrder& S, const Epi& E, const int tid) {
;     ...
;             PG8_LDA(At, 1, 1); PG8_STAGE(PG8_SB(1, 0), b3, voffB); PG8_STAGE(PG8_SB(1, 1), b3 + hstepB, voffB); PG8_STAGE(PG8_SA(1, 0), a3, voffA);
	s_barrier
	s_add_u32 s34, s22, 0x8000
	s_addc_u32 s35, s23, 0
	s_add_i32 s87, s87, s61
	s_mov_b32 m0, s87
	ds_read_b128 v[180:183], v155 offset:49152
	ds_read_b128 v[184:187], v155 offset:50176
	ds_read_b128 v[188:191], v155 offset:51200
	ds_read_b128 v[192:195], v155 offset:52224


; #define PG8_STAGE(bufoff, gbase, voff) do { _Pragma("unroll") for (int _i = 0; _i < 2; ++_i) \
;         __builtin_amdgcn_global_load_lds((const unsigned*)((const char*)(gbase) + (voff)[_i]), (LAS unsigned*)(lds + (bufoff) + ldsw + _i * 8192), 16, 0, 0); } while (0)
; #define PG8_LDA(dst, b, h) do { _Pragma("unroll") for (int m = 0; m < 4; ++m) _Pragma("unroll") for (int k = 0; k < 2; ++k) dst[m][k] = *(const LAS bf16x8*)(lds + PG8_SA(b, h) + aoff + m * 2048 + k * 1024); } while (0)
; #define PG8_MMA(ai, bj, At, Bt) do { __builtin_amdgcn_s_setprio(1); _Pragma("unroll") for (int m = 0; m < 4; ++m) _Pragma("unroll") for (int n = 0; n < 2; ++n) _Pragma("unroll") for (int k = 0; k < 2; ++k) \
;         acc[ai][bj][m][n] = __builtin_amdgcn_mfma_f32_16x16x32_bf16(Bt[n][k], At[m][k], acc[ai][bj][m][n], 0, 0, 0); __builtin_amdgcn_s_setprio(0); } while (0)
; #define PG8_WAIT_V(n) asm volatile("s_waitcnt vmcnt(" #n ")" ::: "memory")
; #define PG8_WAIT_L(n) asm volatile("s_waitcnt lgkmcnt(" #n ")" ::: "memory")
; #define PG8_BAR __builtin_amdgcn_s_barrier()
; #define PG8_SCHED __builtin_amdgcn_sched_barrier(0)
; template <class Epi, bool ALIGN_EPI>
; __device__ __forceinline__ void gemm_phase(LAS unsigned char* lds, const Gemm g, const StaticOrder& S, const Epi& E, const int tid) {
;     ...
;             PG8_LDA(At, 1, 1); PG8_STAGE(PG8_SB(1, 0), b3, voffB); PG8_STAGE(PG8_SB(1, 1), b3 + hstepB, voffB); PG8_STAGE(PG8_SA(1, 0), a3, voffA);
;             PG8_WAIT_V(8); PG8_WAIT_L(0); PG8_BAR; PG8_MMA(1, 0, At, B0); PG8_MMA(1, 1, At, B1); PG8_BAR; PG8_SCHED;
	global_load_lds_dwordx4 v140, s[34:35]
	s_add_i32 m0, s87, 0x2000
	s_add_u32 s22, s22, 0xc000
	s_addc_u32 s23, s23, 0
	global_load_lds_dwordx4 v136, s[34:35]
	s_add_i32 s34, s88, s61
	s_mov_b32 m0, s34
	ds_read_b128 v[222:225], v155 offset:56320
	global_load_lds_dwordx4 v140, s[22:23]
	s_add_i32 m0, s34, 0x2000
	ds_read_b128 v[218:221], v155 offset:55296
	global_load_lds_dwordx4 v136, s[22:23]
	v_lshl_add_u64 v[2:3], v[152:153], 0, s[6:7]
	s_mov_b32 m0, s78
	ds_read_b128 v[214:217], v155 offset:54272
	global_load_lds_dwordx4 v[2:3], off
	v_lshl_add_u64 v[2:3], v[200:201], 0, s[6:7]
	s_mov_b32 m0, s79
	ds_read_b128 v[196:199], v155 offset:53248
	global_load_lds_dwordx4 v[2:3], off
	s_waitcnt vmcnt(8)
	s_waitcnt lgkmcnt(0)
	s_barrier


; #define PG8_MMA(ai, bj, At, Bt) do { __builtin_amdgcn_s_setprio(1); _Pragma("unroll") for (int m = 0; m < 4; ++m) _Pragma("unroll") for (int n = 0; n < 2; ++n) _Pragma("unroll") for (int k = 0; k < 2; ++k) \
;         acc[ai][bj][m][n] = __builtin_amdgcn_mfma_f32_16x16x32_bf16(Bt[n][k], At[m][k], acc[ai][bj][m][n], 0, 0, 0); __builtin_amdgcn_s_setprio(0); } while (0)
; #define PG8_WAIT_V(n) asm volatile("s_waitcnt vmcnt(" #n ")" ::: "memory")
; #define PG8_WAIT_L(n) asm volatile("s_waitcnt lgkmcnt(" #n ")" ::: "memory")
; #define PG8_BAR __builtin_amdgcn_s_barrier()
; #define PG8_SCHED __builtin_amdgcn_sched_barrier(0)
; template <class Epi, bool ALIGN_EPI>
; __device__ __forceinline__ void gemm_phase(LAS unsigned char* lds, const Gemm g, const StaticOrder& S, const Epi& E, const int tid) {
;     ...
;             PG8_WAIT_V(8); PG8_WAIT_L(0); PG8_BAR; PG8_MMA(1, 0, At, B0); PG8_MMA(1, 1, At, B1); PG8_BAR; PG8_SCHED;
	v_mfma_f32_16x16x32_bf16 v[24:27], v[132:135], v[180:183], v[24:27]
	v_mfma_f32_16x16x32_bf16 v[24:27], v[148:151], v[184:187], v[24:27]
	v_mfma_f32_16x16x32_bf16 v[20:23], v[156:159], v[180:183], v[20:23]
	v_mfma_f32_16x16x32_bf16 v[20:23], v[160:163], v[184:187], v[20:23]
	v_mfma_f32_16x16x32_bf16 v[64:67], v[132:135], v[188:191], v[64:67]
	v_mfma_f32_16x16x32_bf16 v[64:67], v[148:151], v[192:195], v[64:67]
	v_mfma_f32_16x16x32_bf16 v[72:75], v[156:159], v[188:191], v[72:75]
	v_mfma_f32_16x16x32_bf16 v[72:75], v[160:163], v[192:195], v[72:75]
	v_mfma_f32_16x16x32_bf16 v[16:19], v[132:135], v[196:199], v[16:19]
	v_mfma_f32_16x16x32_bf16 v[16:19], v[148:151], v[214:217], v[16:19]
	v_mfma_f32_16x16x32_bf16 v[12:15], v[156:159], v[196:199], v[12:15]
	v_mfma_f32_16x16x32_bf16 v[12:15], v[160:163], v[214:217], v[12:15]
	v_mfma_f32_16x16x32_bf16 v[60:63], v[132:135], v[218:221], v[60:63]
	v_mfma_f32_16x16x32_bf16 v[60:63], v[148:151], v[222:225], v[60:63]
	v_mfma_f32_16x16x32_bf16 v[68:71], v[156:159], v[218:221], v[68:71]
	v_mfma_f32_16x16x32_bf16 v[68:71], v[160:163], v[222:225], v[68:71]


; #define PG8_MMA(ai, bj, At, Bt) do { __builtin_amdgcn_s_setprio(1); _Pragma("unroll") for (int m = 0; m < 4; ++m) _Pragma("unroll") for (int n = 0; n < 2; ++n) _Pragma("unroll") for (int k = 0; k < 2; ++k) \
;         acc[ai][bj][m][n] = __builtin_amdgcn_mfma_f32_16x16x32_bf16(Bt[n][k], At[m][k], acc[ai][bj][m][n], 0, 0, 0); __builtin_amdgcn_s_setprio(0); } while (0)
; #define PG8_WAIT_V(n) asm volatile("s_waitcnt vmcnt(" #n ")" ::: "memory")
; #define PG8_WAIT_L(n) asm volatile("s_waitcnt lgkmcnt(" #n ")" ::: "memory")
; #define PG8_BAR __builtin_amdgcn_s_barrier()
; #define PG8_SCHED __builtin_amdgcn_sched_barrier(0)
; template <class Epi, bool ALIGN_EPI>
; __device__ __forceinline__ void gemm_phase(LAS unsigned char* lds, const Gemm g, const StaticOrder& S, const Epi& E, const int tid) {
;     ...
;             PG8_WAIT_V(8); PG8_WAIT_L(0); PG8_BAR; PG8_MMA(1, 0, At, B0); PG8_MMA(1, 1, At, B1); PG8_BAR; PG8_SCHED;
	v_mfma_f32_16x16x32_bf16 v[128:131], v[164:167], v[180:183], v[128:131]
	v_mfma_f32_16x16x32_bf16 v[128:131], v[168:171], v[184:187], v[128:131]
	v_mfma_f32_16x16x32_bf16 v[124:127], v[172:175], v[180:183], v[124:127]
	v_mfma_f32_16x16x32_bf16 v[124:127], v[176:179], v[184:187], v[124:127]
	v_mfma_f32_16x16x32_bf16 v[120:123], v[164:167], v[188:191], v[120:123]
	v_mfma_f32_16x16x32_bf16 v[120:123], v[168:171], v[192:195], v[120:123]
	v_mfma_f32_16x16x32_bf16 v[116:119], v[172:175], v[188:191], v[116:119]
	v_mfma_f32_16x16x32_bf16 v[116:119], v[176:179], v[192:195], v[116:119]
	v_mfma_f32_16x16x32_bf16 v[112:115], v[164:167], v[196:199], v[112:115]
	v_mfma_f32_16x16x32_bf16 v[112:115], v[168:171], v[214:217], v[112:115]
	v_mfma_f32_16x16x32_bf16 v[108:111], v[172:175], v[196:199], v[108:111]
	v_mfma_f32_16x16x32_bf16 v[108:111], v[176:179], v[214:217], v[108:111]
	v_mfma_f32_16x16x32_bf16 v[104:107], v[164:167], v[218:221], v[104:107]
	v_mfma_f32_16x16x32_bf16 v[104:107], v[168:171], v[222:225], v[104:107]
	v_mfma_f32_16x16x32_bf16 v[100:103], v[172:175], v[218:221], v[100:103]
	v_mfma_f32_16x16x32_bf16 v[100:103], v[176:179], v[222:225], v[100:103]

; #define PG8_MMA(ai, bj, At, Bt) do { __builtin_amdgcn_s_setprio(1); _Pragma("unroll") for (int m = 0; m < 4; ++m) _Pragma("unroll") for (int n = 0; n < 2; ++n) _Pragma("unroll") for (int k = 0; k < 2; ++k) \
;         acc[ai][bj][m][n] = __builtin_amdgcn_mfma_f32_16x16x32_bf16(Bt[n][k], At[m][k], acc[ai][bj][m][n], 0, 0, 0); __builtin_amdgcn_s_setprio(0); } while (0)
; #define PG8_WAIT_V(n) asm volatile("s_waitcnt vmcnt(" #n ")" ::: "memory")
; #define PG8_WAIT_L(n) asm volatile("s_waitcnt lgkmcnt(" #n ")" ::: "memory")
; #define PG8_BAR __builtin_amdgcn_s_barrier()
; #define PG8_SCHED __builtin_amdgcn_sched_barrier(0)
; __device__ __forceinline__ u32x4 zero_frag() { unsigned z_ = 0u; asm volatile("" : "+v"(z_)); return (u32x4){z_, z_, z_, z_}; }
; template <class Epi, bool ALIGN_EPI>
; __device__ __forceinline__ void gemm_phase(LAS unsigned char* lds, const Gemm g, const StaticOrder& S, const Epi& E, const int tid) {
;     ...
;             PG8_WAIT_V(8); PG8_WAIT_L(0); PG8_BAR; PG8_MMA(1, 0, At, B0); PG8_MMA(1, 1, At, B1); PG8_BAR; PG8_SCHED;
;         }
;         if constexpr (ALIGN_EPI) { if (wr == 0) PG8_BAR; }
;     __device__ __forceinline__ void operator()(f32x4 (&acc)[2][2][4][2], const Unit& u, int wr, int wc, LAS unsigned char* lds, int& rs_pm) const {
;     ...
;         const int row0 = u.pm * BM + wr * 64 + fr, col0 = u.pn * BM + wc * 32 + 8 * fq; u32x4 zb = zero_frag();
; #pragma unroll
;         for (int ai = 0; ai < 2; ++ai)
; #pragma unroll
;             for (int m = 0; m < 4; ++m) { float ss = 0.f;
;                 bf16* const xrow = xb + (((size_t)(u.pm * 32 + u.pn * 4 + (wc >> 1)) * BM + (wr * 64 + fr + ai * HALF + m * 16)) * 64 + (wc & 1) * 32 + 8 * fq);
; #pragma unroll
;                 for (int bj = 0; bj < 2; ++bj) {
;                     const u32x4 xw = *(const u32x4*)(xrow + (size_t)bj * (2 * BM * 64));
	s_barrier
	s_add_i32 s86, s86, 2
	s_add_u32 s10, s10, 0x100
	s_addc_u32 s11, s11, 0
	s_add_u32 s84, s84, 0x10000
	s_addc_u32 s85, s85, 0
	s_cmp_gt_u32 s86, 29
	s_cbranch_scc0 .LBB0_847
	v_and_b32_e32 v222, 15, v238
	v_lshrrev_b32_e32 v156, 4, v238
	s_lshl_b32 s100, s40, 5
	s_lshl_b32 s101, s41, 2
	v_lshlrev_b32_e32 v222, 7, v222
	s_add_i32 s100, s100, s101
	s_or_b32 s100, s100, s80
	v_lshl_or_b32 v222, v156, 4, v222
	s_ashr_i32 s101, s100, 31
	s_lshl_b64 s[100:101], s[100:101], 15
	s_add_u32 s98, s74, s100
	s_addc_u32 s99, s75, s101
	s_add_u32 s98, s98, s30
	s_addc_u32 s99, s99, s31
	s_lshl_b32 s100, s77, 7
	s_add_u32 s98, s98, s100
	s_addc_u32 s99, s99, 0
	s_lshl_b32 s100, s40, 15
	s_lshl_b32 s101, s77, 7
	s_add_i32 s100, s100, s101
	s_lshl_b32 s101, s41, 4
	s_add_i32 s100, s100, s101
	s_lshl_b32 s101, s76, 2
	s_add_i32 s100, s100, s101
	s_add_u32 s22, s42, s100
	s_addc_u32 s23, s43, 0
	global_load_dwordx4 v[176:179], v222, s[98:99]
	s_add_u32 s100, s98, 0x10000
	s_addc_u32 s101, s99, 0
	global_load_dwordx4 v[180:183], v222, s[100:101]
	global_load_dwordx4 v[184:187], v222, s[98:99] offset:2048
	s_add_u32 s100, s98, 0x10000
	s_addc_u32 s101, s99, 0
	global_load_dwordx4 v[188:191], v222, s[100:101] offset:2048
	s_add_u32 s100, s98, 0x1000
	s_addc_u32 s101, s99, 0
	global_load_dwordx4 v[192:195], v222, s[100:101]
	s_add_u32 s100, s98, 0x11000
	s_addc_u32 s101, s99, 0
	global_load_dwordx4 v[196:199], v222, s[100:101]
	s_add_u32 s100, s98, 0x1000
	s_addc_u32 s101, s99, 0
	global_load_dwordx4 v[214:217], v222, s[100:101] offset:2048
	s_add_u32 s100, s98, 0x11000
	s_addc_u32 s101, s99, 0
	global_load_dwordx4 v[218:221], v222, s[100:101] offset:2048
	s_and_b64 vcc, exec, s[44:45]
	s_cbranch_vccz .LBB0_850
	s_barrier
